# GEMM loops: 40 provably redundant lgkmcnt(0) waits after the phase barrier removed
# speedup vs baseline: 1.0036x; 1.0036x over previous
; #define PG8_STAGE(bufoff, gbase, voff) do { _Pragma("unroll") for (int _i = 0; _i < 2; ++_i) \
;         __builtin_amdgcn_global_load_lds((const unsigned*)((const char*)(gbase) + (voff)[_i]), (PG8_LAS unsigned*)(lds + (bufoff) + ldsw + _i * 8192), 16, 0, 0); } while (0)
; #define PG8_LDA(dst, b, h) do { _Pragma("unroll") for (int m = 0; m < 4; ++m) _Pragma("unroll") for (int k = 0; k < 2; ++k) dst[m][k] = *(const PG8_LAS bf16x8*)(lds + PG8_SA(b, h) + aoff + m * 2048 + k * 1024); } while (0)
; #define PG8_LDB(dst, b, h) do { _Pragma("unroll") for (int n = 0; n < 2; ++n) _Pragma("unroll") for (int k = 0; k < 2; ++k) dst[n][k] = *(const PG8_LAS bf16x8*)(lds + PG8_SB(b, h) + boff + n * 2048 + k * 1024); } while (0)
; #define PG8_MMA(ai, bj, At, Bt) do { __builtin_amdgcn_s_setprio(1); _Pragma("unroll") for (int m = 0; m < 4; ++m) _Pragma("unroll") for (int n = 0; n < 2; ++n) _Pragma("unroll") for (int k = 0; k < 2; ++k) \
;         acc[ai][bj][m][n] = __builtin_amdgcn_mfma_f32_16x16x32_bf16(Bt[n][k], At[m][k], acc[ai][bj][m][n], 0, 0, 0); __builtin_amdgcn_s_setprio(0); } while (0)
; #define PG8_WAIT_V(n) asm volatile("s_waitcnt vmcnt(" #n ")" ::: "memory")
; #define PG8_WAIT_L(n) asm volatile("s_waitcnt lgkmcnt(" #n ")" ::: "memory")
; template <class Epi, class Sched, bool ALIGN_EPI = false, bool SP2 = false>
; __device__ __forceinline__ void gemm_phase(PG8_LAS unsigned char* lds, const Gemm g, const Sched& S, const Epi& E, int wave_s) {
;     ...
;             const bool last = (t == nt - 2);
;             const char* a1 = cA + (size_t)(t + 1) * kstep;
;             const char* a2 = last ? nA : cA + (size_t)(t + 2) * kstep; const char* b2 = last ? nB : cB + (size_t)(t + 2) * kstep;
;             const char* a3 = a2 + kstep; const char* b3 = b2 + kstep;
;             if (last && has_next) S.a_ready(nxt);
;             if constexpr (SP2) {
;             PG8_LDB(B0, 0, 0); PG8_LDB(B1, 0, 1); PG8_SCHED; PG8_LDA(At, 0, 0); PG8_STAGE(PG8_SA(1, 1), a1 + hstep, voffA);
;             PG8_WAIT_V(8); PG8_WAIT_L(0); PG8_BAR; PG8_MMA(0, 0, At, B0); PG8_MMA(0, 1, At, B1); PG8_BAR; PG8_SCHED;
;             PG8_LDA(At, 0, 1); PG8_STAGE(PG8_SB(0, 0), b2, voffB); PG8_STAGE(PG8_SB(0, 1), b2 + hstep, voffB); PG8_STAGE(PG8_SA(0, 0), a2, voffA);
;             PG8_WAIT_V(8); PG8_WAIT_L(0); PG8_BAR; PG8_MMA(1, 0, At, B0); PG8_MMA(1, 1, At, B1); PG8_BAR; PG8_SCHED;
.LBB0_191:
	s_add_u32 s22, s20, 0xfffc0080
	s_addc_u32 s23, s21, -1
	s_add_i32 s72, 0, 0x10000
	s_cmp_eq_u32 s70, 12
	s_cselect_b32 s25, s13, s23
	s_cselect_b32 s24, s57, s22
	s_cselect_b32 s23, s11, s63
	s_cselect_b32 s22, s58, s62
	s_add_i32 s74, 0, 0x14000
	v_add_u32_e32 v156, s72, v145
	v_add_u32_e32 v160, s74, v145
	ds_read_b128 v[140:143], v156
	ds_read_b128 v[148:151], v156 offset:1024
	ds_read_b128 v[152:155], v156 offset:2048
	ds_read_b128 v[156:159], v156 offset:3072
	ds_read_b128 v[178:181], v160
	ds_read_b128 v[182:185], v160 offset:1024
	ds_read_b128 v[186:189], v160 offset:2048
	ds_read_b128 v[190:193], v160 offset:3072
	v_lshl_add_u64 v[160:161], s[20:21], 0, v[136:137]
	s_add_i32 m0, s19, 0xc000
	ds_read_b128 v[194:197], v147
	ds_read_b128 v[198:201], v147 offset:1024
	ds_read_b128 v[202:205], v147 offset:2048
	ds_read_b128 v[214:217], v147 offset:3072
	ds_read_b128 v[218:221], v147 offset:4096
	ds_read_b128 v[222:225], v147 offset:5120
	ds_read_b128 v[226:229], v147 offset:6144
	ds_read_b128 v[230:233], v147 offset:7168
	global_load_lds_dwordx4 v[160:161], off
	v_lshl_add_u64 v[160:161], s[20:21], 0, v[138:139]
	s_add_i32 m0, s19, 0xe000
	s_nop 0
	global_load_lds_dwordx4 v[160:161], off
	s_waitcnt vmcnt(8)
	s_waitcnt lgkmcnt(0)
	s_barrier
	s_setprio 1
	v_mfma_f32_16x16x32_bf16 v[126:129], v[140:143], v[194:197], v[126:129]
	v_mfma_f32_16x16x32_bf16 v[122:125], v[152:155], v[194:197], v[122:125]
	v_mfma_f32_16x16x32_bf16 v[118:121], v[140:143], v[202:205], v[118:121]
	v_mfma_f32_16x16x32_bf16 v[110:113], v[152:155], v[202:205], v[110:113]
	v_mfma_f32_16x16x32_bf16 v[102:105], v[140:143], v[218:221], v[102:105]
	v_mfma_f32_16x16x32_bf16 v[94:97], v[152:155], v[218:221], v[94:97]
	v_mfma_f32_16x16x32_bf16 v[86:89], v[140:143], v[226:229], v[86:89]
	v_mfma_f32_16x16x32_bf16 v[78:81], v[152:155], v[226:229], v[78:81]
	v_mfma_f32_16x16x32_bf16 v[126:129], v[148:151], v[198:201], v[126:129]
	v_mfma_f32_16x16x32_bf16 v[122:125], v[156:159], v[198:201], v[122:125]
	v_mfma_f32_16x16x32_bf16 v[118:121], v[148:151], v[214:217], v[118:121]
	v_mfma_f32_16x16x32_bf16 v[110:113], v[156:159], v[214:217], v[110:113]
	v_mfma_f32_16x16x32_bf16 v[102:105], v[148:151], v[222:225], v[102:105]
	v_mfma_f32_16x16x32_bf16 v[94:97], v[156:159], v[222:225], v[94:97]
	v_mfma_f32_16x16x32_bf16 v[86:89], v[148:151], v[230:233], v[86:89]
	v_mfma_f32_16x16x32_bf16 v[78:81], v[156:159], v[230:233], v[78:81]
	s_setprio 0
	s_setprio 1
	v_mfma_f32_16x16x32_bf16 v[114:117], v[178:181], v[194:197], v[114:117]
	v_mfma_f32_16x16x32_bf16 v[106:109], v[186:189], v[194:197], v[106:109]
	v_mfma_f32_16x16x32_bf16 v[98:101], v[178:181], v[202:205], v[98:101]
	v_mfma_f32_16x16x32_bf16 v[90:93], v[186:189], v[202:205], v[90:93]
	v_mfma_f32_16x16x32_bf16 v[82:85], v[178:181], v[218:221], v[82:85]
	v_mfma_f32_16x16x32_bf16 v[74:77], v[186:189], v[218:221], v[74:77]
	v_mfma_f32_16x16x32_bf16 v[70:73], v[178:181], v[226:229], v[70:73]
	v_mfma_f32_16x16x32_bf16 v[66:69], v[186:189], v[226:229], v[66:69]
	v_mfma_f32_16x16x32_bf16 v[114:117], v[182:185], v[198:201], v[114:117]
	v_mfma_f32_16x16x32_bf16 v[106:109], v[190:193], v[198:201], v[106:109]
	v_mfma_f32_16x16x32_bf16 v[98:101], v[182:185], v[214:217], v[98:101]
	v_mfma_f32_16x16x32_bf16 v[90:93], v[190:193], v[214:217], v[90:93]
	v_mfma_f32_16x16x32_bf16 v[82:85], v[182:185], v[222:225], v[82:85]
	v_mfma_f32_16x16x32_bf16 v[74:77], v[190:193], v[222:225], v[74:77]
	v_mfma_f32_16x16x32_bf16 v[70:73], v[182:185], v[230:233], v[70:73]
	v_mfma_f32_16x16x32_bf16 v[66:69], v[190:193], v[230:233], v[66:69]
	s_setprio 0
	s_barrier
	s_add_i32 s72, s72, s37
	v_lshl_add_u64 v[160:161], s[22:23], 0, v[0:1]
	s_mov_b32 m0, s72
	ds_read_b128 v[194:197], v147 offset:16384
	ds_read_b128 v[198:201], v147 offset:17408
	ds_read_b128 v[202:205], v147 offset:18432
	ds_read_b128 v[214:217], v147 offset:19456
	ds_read_b128 v[218:221], v147 offset:20480
	ds_read_b128 v[222:225], v147 offset:21504
	ds_read_b128 v[226:229], v147 offset:22528
	ds_read_b128 v[230:233], v147 offset:23552
	global_load_lds_dwordx4 v[160:161], off
	s_add_i32 m0, s72, 0x2000
	s_add_u32 s72, s22, 0x40000
	v_lshl_add_u64 v[162:163], s[22:23], 0, v[134:135]
	s_addc_u32 s73, s23, 0
	s_add_i32 s74, s74, s37
	global_load_lds_dwordx4 v[162:163], off
	v_lshl_add_u64 v[164:165], s[72:73], 0, v[0:1]
	s_mov_b32 m0, s74
	v_lshl_add_u64 v[166:167], s[24:25], 0, v[132:133]
	global_load_lds_dwordx4 v[164:165], off
	v_lshl_add_u64 v[164:165], s[72:73], 0, v[134:135]
	s_add_i32 m0, s74, 0x2000
	s_nop 0
	global_load_lds_dwordx4 v[164:165], off
	v_lshl_add_u64 v[164:165], s[24:25], 0, v[130:131]
	s_mov_b32 m0, s19
	s_nop 0
	global_load_lds_dwordx4 v[164:165], off
	s_mov_b32 m0, s46
	s_nop 0
	global_load_lds_dwordx4 v[166:167], off
	s_waitcnt vmcnt(8)
	s_waitcnt lgkmcnt(0)
	s_barrier
; #define PG8_STAGE(bufoff, gbase, voff) do { _Pragma("unroll") for (int _i = 0; _i < 2; ++_i) \
;         __builtin_amdgcn_global_load_lds((const unsigned*)((const char*)(gbase) + (voff)[_i]), (PG8_LAS unsigned*)(lds + (bufoff) + ldsw + _i * 8192), 16, 0, 0); } while (0)
; #define PG8_LDA(dst, b, h) do { _Pragma("unroll") for (int m = 0; m < 4; ++m) _Pragma("unroll") for (int k = 0; k < 2; ++k) dst[m][k] = *(const PG8_LAS bf16x8*)(lds + PG8_SA(b, h) + aoff + m * 2048 + k * 1024); } while (0)
; #define PG8_LDB(dst, b, h) do { _Pragma("unroll") for (int n = 0; n < 2; ++n) _Pragma("unroll") for (int k = 0; k < 2; ++k) dst[n][k] = *(const PG8_LAS bf16x8*)(lds + PG8_SB(b, h) + boff + n * 2048 + k * 1024); } while (0)
; #define PG8_MMA(ai, bj, At, Bt) do { __builtin_amdgcn_s_setprio(1); _Pragma("unroll") for (int m = 0; m < 4; ++m) _Pragma("unroll") for (int n = 0; n < 2; ++n) _Pragma("unroll") for (int k = 0; k < 2; ++k) \
;         acc[ai][bj][m][n] = __builtin_amdgcn_mfma_f32_16x16x32_bf16(Bt[n][k], At[m][k], acc[ai][bj][m][n], 0, 0, 0); __builtin_amdgcn_s_setprio(0); } while (0)
; #define PG8_WAIT_V(n) asm volatile("s_waitcnt vmcnt(" #n ")" ::: "memory")
; #define PG8_WAIT_L(n) asm volatile("s_waitcnt lgkmcnt(" #n ")" ::: "memory")
; #define PG8_BAR __builtin_amdgcn_s_barrier()
; #define PG8_SCHED __builtin_amdgcn_sched_barrier(0)
; template <class Epi, class Sched, bool ALIGN_EPI = false, bool SP2 = false>
; __device__ __forceinline__ void gemm_phase(PG8_LAS unsigned char* lds, const Gemm g, const Sched& S, const Epi& E, int wave_s) {
;     ...
;             PG8_WAIT_V(8); PG8_WAIT_L(0); PG8_BAR; PG8_MMA(1, 0, At, B0); PG8_MMA(1, 1, At, B1); PG8_BAR; PG8_SCHED;
;             PG8_LDB(B0, 1, 0); PG8_LDB(B1, 1, 1); PG8_SCHED; PG8_LDA(At, 1, 0); PG8_STAGE(PG8_SA(0, 1), a2 + hstep, voffA);
;             PG8_WAIT_V(8); PG8_WAIT_L(0); PG8_BAR; PG8_MMA(0, 0, At, B0); PG8_MMA(0, 1, At, B1); PG8_BAR; PG8_SCHED;
	s_setprio 1
	v_mfma_f32_16x16x32_bf16 v[62:65], v[140:143], v[194:197], v[62:65]
	v_mfma_f32_16x16x32_bf16 v[58:61], v[152:155], v[194:197], v[58:61]
	v_mfma_f32_16x16x32_bf16 v[54:57], v[140:143], v[202:205], v[54:57]
	v_mfma_f32_16x16x32_bf16 v[46:49], v[152:155], v[202:205], v[46:49]
	v_mfma_f32_16x16x32_bf16 v[38:41], v[140:143], v[218:221], v[38:41]
	v_mfma_f32_16x16x32_bf16 v[30:33], v[152:155], v[218:221], v[30:33]
	v_mfma_f32_16x16x32_bf16 v[22:25], v[140:143], v[226:229], v[22:25]
	v_mfma_f32_16x16x32_bf16 v[14:17], v[152:155], v[226:229], v[14:17]
	v_mfma_f32_16x16x32_bf16 v[62:65], v[148:151], v[198:201], v[62:65]
	v_mfma_f32_16x16x32_bf16 v[58:61], v[156:159], v[198:201], v[58:61]
	v_mfma_f32_16x16x32_bf16 v[54:57], v[148:151], v[214:217], v[54:57]
	v_mfma_f32_16x16x32_bf16 v[46:49], v[156:159], v[214:217], v[46:49]
	v_mfma_f32_16x16x32_bf16 v[38:41], v[148:151], v[222:225], v[38:41]
	v_mfma_f32_16x16x32_bf16 v[30:33], v[156:159], v[222:225], v[30:33]
	v_mfma_f32_16x16x32_bf16 v[22:25], v[148:151], v[230:233], v[22:25]
	v_mfma_f32_16x16x32_bf16 v[14:17], v[156:159], v[230:233], v[14:17]
	s_setprio 0
	s_setprio 1
	v_mfma_f32_16x16x32_bf16 v[50:53], v[178:181], v[194:197], v[50:53]
	v_mfma_f32_16x16x32_bf16 v[42:45], v[186:189], v[194:197], v[42:45]
	v_mfma_f32_16x16x32_bf16 v[34:37], v[178:181], v[202:205], v[34:37]
	v_mfma_f32_16x16x32_bf16 v[26:29], v[186:189], v[202:205], v[26:29]
	v_mfma_f32_16x16x32_bf16 v[18:21], v[178:181], v[218:221], v[18:21]
	v_mfma_f32_16x16x32_bf16 v[10:13], v[186:189], v[218:221], v[10:13]
	v_mfma_f32_16x16x32_bf16 v[6:9], v[178:181], v[226:229], v[6:9]
	v_mfma_f32_16x16x32_bf16 v[2:5], v[186:189], v[226:229], v[2:5]
	v_mfma_f32_16x16x32_bf16 v[50:53], v[182:185], v[198:201], v[50:53]
	v_mfma_f32_16x16x32_bf16 v[42:45], v[190:193], v[198:201], v[42:45]
	v_mfma_f32_16x16x32_bf16 v[34:37], v[182:185], v[214:217], v[34:37]
	v_mfma_f32_16x16x32_bf16 v[26:29], v[190:193], v[214:217], v[26:29]
	v_mfma_f32_16x16x32_bf16 v[18:21], v[182:185], v[222:225], v[18:21]
	v_mfma_f32_16x16x32_bf16 v[10:13], v[190:193], v[222:225], v[10:13]
	v_mfma_f32_16x16x32_bf16 v[6:9], v[182:185], v[230:233], v[6:9]
	v_mfma_f32_16x16x32_bf16 v[2:5], v[190:193], v[230:233], v[2:5]
	s_setprio 0
	s_barrier
	s_add_i32 s72, 0, 0x18000
	s_add_i32 s73, 0, 0x1c000
	v_add_u32_e32 v156, s72, v145
	v_add_u32_e32 v168, s73, v145
	ds_read_b128 v[140:143], v156
	ds_read_b128 v[148:151], v156 offset:1024
	ds_read_b128 v[152:155], v156 offset:2048
	ds_read_b128 v[156:159], v156 offset:3072
	ds_read_b128 v[178:181], v168
	ds_read_b128 v[182:185], v168 offset:1024
	ds_read_b128 v[186:189], v168 offset:2048
	ds_read_b128 v[190:193], v168 offset:3072
	s_add_u32 s24, s24, 0x40000
	s_addc_u32 s25, s25, 0
	s_mov_b32 m0, s47
	v_lshl_add_u64 v[168:169], s[24:25], 0, v[130:131]
	ds_read_b128 v[194:197], v147 offset:32768
	ds_read_b128 v[198:201], v147 offset:33792
	ds_read_b128 v[202:205], v147 offset:34816
	ds_read_b128 v[214:217], v147 offset:35840
	ds_read_b128 v[218:221], v147 offset:36864
	ds_read_b128 v[222:225], v147 offset:37888
	ds_read_b128 v[226:229], v147 offset:38912
	ds_read_b128 v[230:233], v147 offset:39936
	global_load_lds_dwordx4 v[168:169], off
	v_lshl_add_u64 v[168:169], s[24:25], 0, v[132:133]
	s_mov_b32 m0, s48
	s_nop 0
	global_load_lds_dwordx4 v[168:169], off
	s_waitcnt vmcnt(8)
	s_waitcnt lgkmcnt(0)
	s_barrier
	s_setprio 1
	v_mfma_f32_16x16x32_bf16 v[126:129], v[140:143], v[194:197], v[126:129]
	v_mfma_f32_16x16x32_bf16 v[122:125], v[152:155], v[194:197], v[122:125]
	v_mfma_f32_16x16x32_bf16 v[118:121], v[140:143], v[202:205], v[118:121]
	v_mfma_f32_16x16x32_bf16 v[110:113], v[152:155], v[202:205], v[110:113]
	v_mfma_f32_16x16x32_bf16 v[102:105], v[140:143], v[218:221], v[102:105]
	v_mfma_f32_16x16x32_bf16 v[94:97], v[152:155], v[218:221], v[94:97]
	v_mfma_f32_16x16x32_bf16 v[86:89], v[140:143], v[226:229], v[86:89]
	v_mfma_f32_16x16x32_bf16 v[78:81], v[152:155], v[226:229], v[78:81]
	v_mfma_f32_16x16x32_bf16 v[126:129], v[148:151], v[198:201], v[126:129]
	v_mfma_f32_16x16x32_bf16 v[122:125], v[156:159], v[198:201], v[122:125]
	v_mfma_f32_16x16x32_bf16 v[118:121], v[148:151], v[214:217], v[118:121]
	v_mfma_f32_16x16x32_bf16 v[110:113], v[156:159], v[214:217], v[110:113]
	v_mfma_f32_16x16x32_bf16 v[102:105], v[148:151], v[222:225], v[102:105]
	v_mfma_f32_16x16x32_bf16 v[94:97], v[156:159], v[222:225], v[94:97]
	v_mfma_f32_16x16x32_bf16 v[86:89], v[148:151], v[230:233], v[86:89]
	v_mfma_f32_16x16x32_bf16 v[78:81], v[156:159], v[230:233], v[78:81]
	s_setprio 0
	s_setprio 1
	v_mfma_f32_16x16x32_bf16 v[114:117], v[178:181], v[194:197], v[114:117]
	v_mfma_f32_16x16x32_bf16 v[106:109], v[186:189], v[194:197], v[106:109]
	v_mfma_f32_16x16x32_bf16 v[98:101], v[178:181], v[202:205], v[98:101]
	v_mfma_f32_16x16x32_bf16 v[90:93], v[186:189], v[202:205], v[90:93]
	v_mfma_f32_16x16x32_bf16 v[82:85], v[178:181], v[218:221], v[82:85]
	v_mfma_f32_16x16x32_bf16 v[74:77], v[186:189], v[218:221], v[74:77]
	v_mfma_f32_16x16x32_bf16 v[70:73], v[178:181], v[226:229], v[70:73]
	v_mfma_f32_16x16x32_bf16 v[66:69], v[186:189], v[226:229], v[66:69]
	v_mfma_f32_16x16x32_bf16 v[114:117], v[182:185], v[198:201], v[114:117]
	v_mfma_f32_16x16x32_bf16 v[106:109], v[190:193], v[198:201], v[106:109]
	v_mfma_f32_16x16x32_bf16 v[98:101], v[182:185], v[214:217], v[98:101]
	v_mfma_f32_16x16x32_bf16 v[90:93], v[190:193], v[214:217], v[90:93]
	v_mfma_f32_16x16x32_bf16 v[82:85], v[182:185], v[222:225], v[82:85]
	v_mfma_f32_16x16x32_bf16 v[74:77], v[190:193], v[222:225], v[74:77]
	v_mfma_f32_16x16x32_bf16 v[70:73], v[182:185], v[230:233], v[70:73]
	v_mfma_f32_16x16x32_bf16 v[66:69], v[190:193], v[230:233], v[66:69]
	s_setprio 0
	s_barrier
; #define PG8_STAGE(bufoff, gbase, voff) do { _Pragma("unroll") for (int _i = 0; _i < 2; ++_i) \
;         __builtin_amdgcn_global_load_lds((const unsigned*)((const char*)(gbase) + (voff)[_i]), (PG8_LAS unsigned*)(lds + (bufoff) + ldsw + _i * 8192), 16, 0, 0); } while (0)
; #define PG8_LDA(dst, b, h) do { _Pragma("unroll") for (int m = 0; m < 4; ++m) _Pragma("unroll") for (int k = 0; k < 2; ++k) dst[m][k] = *(const PG8_LAS bf16x8*)(lds + PG8_SA(b, h) + aoff + m * 2048 + k * 1024); } while (0)
; #define PG8_MMA(ai, bj, At, Bt) do { __builtin_amdgcn_s_setprio(1); _Pragma("unroll") for (int m = 0; m < 4; ++m) _Pragma("unroll") for (int n = 0; n < 2; ++n) _Pragma("unroll") for (int k = 0; k < 2; ++k) \
;         acc[ai][bj][m][n] = __builtin_amdgcn_mfma_f32_16x16x32_bf16(Bt[n][k], At[m][k], acc[ai][bj][m][n], 0, 0, 0); __builtin_amdgcn_s_setprio(0); } while (0)
; #define PG8_WAIT_V(n) asm volatile("s_waitcnt vmcnt(" #n ")" ::: "memory")
; #define PG8_WAIT_L(n) asm volatile("s_waitcnt lgkmcnt(" #n ")" ::: "memory")
; #define PG8_BAR __builtin_amdgcn_s_barrier()
; #define PG8_SCHED __builtin_amdgcn_sched_barrier(0)
; template <class Epi, class Sched, bool ALIGN_EPI = false, bool SP2 = false>
; __device__ __forceinline__ void gemm_phase(PG8_LAS unsigned char* lds, const Gemm g, const Sched& S, const Epi& E, int wave_s) {
;     ...
;             PG8_LDA(At, 1, 1); PG8_STAGE(PG8_SB(1, 0), b3, voffB); PG8_STAGE(PG8_SB(1, 1), b3 + hstep, voffB); PG8_STAGE(PG8_SA(1, 0), a3, voffA);
;             PG8_WAIT_V(8); PG8_WAIT_L(0); PG8_BAR; PG8_MMA(1, 0, At, B0); PG8_MMA(1, 1, At, B1); PG8_BAR; PG8_SCHED;
;     ...
;         if constexpr (ALIGN_EPI) { if (wr == 0) PG8_BAR; }
	s_add_i32 s24, s72, s37
	v_lshl_add_u64 v[160:161], v[160:161], 0, s[60:61]
	s_mov_b32 m0, s24
	ds_read_b128 v[194:197], v147 offset:49152
	ds_read_b128 v[198:201], v147 offset:50176
	ds_read_b128 v[202:205], v147 offset:51200
	ds_read_b128 v[214:217], v147 offset:52224
	ds_read_b128 v[218:221], v147 offset:53248
	ds_read_b128 v[222:225], v147 offset:54272
	ds_read_b128 v[226:229], v147 offset:55296
	ds_read_b128 v[230:233], v147 offset:56320
	global_load_lds_dwordx4 v[160:161], off
	s_add_i32 m0, s24, 0x2000
	s_add_u32 s22, s22, 0x40080
	v_lshl_add_u64 v[160:161], v[162:163], 0, s[60:61]
	s_addc_u32 s23, s23, 0
	s_add_i32 s24, s73, s37
	global_load_lds_dwordx4 v[160:161], off
	v_lshl_add_u64 v[160:161], s[22:23], 0, v[0:1]
	s_mov_b32 m0, s24
	s_nop 0
	global_load_lds_dwordx4 v[160:161], off
	v_lshl_add_u64 v[160:161], s[22:23], 0, v[134:135]
	s_add_i32 m0, s24, 0x2000
	s_nop 0
	global_load_lds_dwordx4 v[160:161], off
	v_lshl_add_u64 v[160:161], v[164:165], 0, s[60:61]
	s_mov_b32 m0, s49
	s_nop 0
	global_load_lds_dwordx4 v[160:161], off
	v_lshl_add_u64 v[160:161], v[166:167], 0, s[60:61]
	s_mov_b32 m0, s50
	s_nop 0
	global_load_lds_dwordx4 v[160:161], off
	s_waitcnt vmcnt(8)
	s_waitcnt lgkmcnt(0)
	s_barrier
	s_setprio 1
	v_mfma_f32_16x16x32_bf16 v[62:65], v[140:143], v[194:197], v[62:65]
	v_mfma_f32_16x16x32_bf16 v[58:61], v[152:155], v[194:197], v[58:61]
	v_mfma_f32_16x16x32_bf16 v[54:57], v[140:143], v[202:205], v[54:57]
	v_mfma_f32_16x16x32_bf16 v[46:49], v[152:155], v[202:205], v[46:49]
	v_mfma_f32_16x16x32_bf16 v[38:41], v[140:143], v[218:221], v[38:41]
	v_mfma_f32_16x16x32_bf16 v[30:33], v[152:155], v[218:221], v[30:33]
	v_mfma_f32_16x16x32_bf16 v[22:25], v[140:143], v[226:229], v[22:25]
	v_mfma_f32_16x16x32_bf16 v[14:17], v[152:155], v[226:229], v[14:17]
	v_mfma_f32_16x16x32_bf16 v[62:65], v[148:151], v[198:201], v[62:65]
	v_mfma_f32_16x16x32_bf16 v[58:61], v[156:159], v[198:201], v[58:61]
	v_mfma_f32_16x16x32_bf16 v[54:57], v[148:151], v[214:217], v[54:57]
	v_mfma_f32_16x16x32_bf16 v[46:49], v[156:159], v[214:217], v[46:49]
	v_mfma_f32_16x16x32_bf16 v[38:41], v[148:151], v[222:225], v[38:41]
	v_mfma_f32_16x16x32_bf16 v[30:33], v[156:159], v[222:225], v[30:33]
	v_mfma_f32_16x16x32_bf16 v[22:25], v[148:151], v[230:233], v[22:25]
	v_mfma_f32_16x16x32_bf16 v[14:17], v[156:159], v[230:233], v[14:17]
	s_setprio 0
	s_setprio 1
	v_mfma_f32_16x16x32_bf16 v[50:53], v[178:181], v[194:197], v[50:53]
	v_mfma_f32_16x16x32_bf16 v[42:45], v[186:189], v[194:197], v[42:45]
	v_mfma_f32_16x16x32_bf16 v[34:37], v[178:181], v[202:205], v[34:37]
	v_mfma_f32_16x16x32_bf16 v[26:29], v[186:189], v[202:205], v[26:29]
	v_mfma_f32_16x16x32_bf16 v[18:21], v[178:181], v[218:221], v[18:21]
	v_mfma_f32_16x16x32_bf16 v[10:13], v[186:189], v[218:221], v[10:13]
	v_mfma_f32_16x16x32_bf16 v[6:9], v[178:181], v[226:229], v[6:9]
	v_mfma_f32_16x16x32_bf16 v[2:5], v[186:189], v[226:229], v[2:5]
	v_mfma_f32_16x16x32_bf16 v[50:53], v[182:185], v[198:201], v[50:53]
	v_mfma_f32_16x16x32_bf16 v[42:45], v[190:193], v[198:201], v[42:45]
	v_mfma_f32_16x16x32_bf16 v[34:37], v[182:185], v[214:217], v[34:37]
	v_mfma_f32_16x16x32_bf16 v[26:29], v[190:193], v[214:217], v[26:29]
	v_mfma_f32_16x16x32_bf16 v[18:21], v[182:185], v[222:225], v[18:21]
	v_mfma_f32_16x16x32_bf16 v[10:13], v[190:193], v[222:225], v[10:13]
	v_mfma_f32_16x16x32_bf16 v[6:9], v[182:185], v[230:233], v[6:9]
	v_mfma_f32_16x16x32_bf16 v[2:5], v[190:193], v[230:233], v[2:5]
	s_setprio 0
	s_barrier
	s_add_i32 s70, s70, 2
	s_add_u32 s20, s20, 0x100
	s_addc_u32 s21, s21, 0
	s_add_u32 s62, s62, 0x100
	s_addc_u32 s63, s63, 0
	s_cmp_gt_u32 s70, 13
	s_cbranch_scc0 .LBB0_191
	s_and_b64 vcc, exec, s[8:9]
	s_cbranch_vccz .LBB0_194
	s_barrier

; #define PG8_STAGE(bufoff, gbase, voff) do { _Pragma("unroll") for (int _i = 0; _i < 2; ++_i) \
;         __builtin_amdgcn_global_load_lds((const unsigned*)((const char*)(gbase) + (voff)[_i]), (PG8_LAS unsigned*)(lds + (bufoff) + ldsw + _i * 8192), 16, 0, 0); } while (0)
; #define PG8_LDA(dst, b, h) do { _Pragma("unroll") for (int m = 0; m < 4; ++m) _Pragma("unroll") for (int k = 0; k < 2; ++k) dst[m][k] = *(const PG8_LAS bf16x8*)(lds + PG8_SA(b, h) + aoff + m * 2048 + k * 1024); } while (0)
; #define PG8_LDB(dst, b, h) do { _Pragma("unroll") for (int n = 0; n < 2; ++n) _Pragma("unroll") for (int k = 0; k < 2; ++k) dst[n][k] = *(const PG8_LAS bf16x8*)(lds + PG8_SB(b, h) + boff + n * 2048 + k * 1024); } while (0)
; #define PG8_WAIT_V(n) asm volatile("s_waitcnt vmcnt(" #n ")" ::: "memory")
; #define PG8_WAIT_L(n) asm volatile("s_waitcnt lgkmcnt(" #n ")" ::: "memory")
; #define PG8_BAR __builtin_amdgcn_s_barrier()
; #define PG8_SCHED __builtin_amdgcn_sched_barrier(0)
; template <class Epi, class Sched, bool ALIGN_EPI = false, bool SP2 = false>
; __device__ __forceinline__ void gemm_phase(PG8_LAS unsigned char* lds, const Gemm g, const Sched& S, const Epi& E, int wave_s) {
;     ...
;         const char* nA = has_next ? (const char*)g.A + (size_t)nxt.pm * tstep + (size_t)nxt.kq * kqstep : cA; const char* nB = has_next ? (const char*)g.Bt + (size_t)nxt.pn * tstep + (size_t)nxt.kq * kqstep : cB;
;         for (int t = 0; t < nt; t += 2) {
;             const bool last = (t == nt - 2);
;             const char* a1 = cA + (size_t)(t + 1) * kstep;
;             const char* a2 = last ? nA : cA + (size_t)(t + 2) * kstep; const char* b2 = last ? nB : cB + (size_t)(t + 2) * kstep;
;             const char* a3 = a2 + kstep; const char* b3 = b2 + kstep;
;             if (last && has_next) S.a_ready(nxt);
;             if constexpr (SP2) {
;             PG8_LDB(B0, 0, 0); PG8_LDB(B1, 0, 1); PG8_SCHED; PG8_LDA(At, 0, 0); PG8_STAGE(PG8_SA(1, 1), a1 + hstep, voffA);
;             PG8_WAIT_V(8); PG8_WAIT_L(0); PG8_BAR; PG8_MMA(0, 0, At, B0); PG8_MMA(0, 1, At, B1); PG8_BAR; PG8_SCHED;
;             PG8_LDA(At, 0, 1); PG8_STAGE(PG8_SB(0, 0), b2, voffB); PG8_STAGE(PG8_SB(0, 1), b2 + hstep, voffB); PG8_STAGE(PG8_SA(0, 0), a2, voffA);
;             PG8_WAIT_V(8); PG8_WAIT_L(0); PG8_BAR; PG8_MMA(1, 0, At, B0); PG8_MMA(1, 1, At, B1); PG8_BAR; PG8_SCHED;
.LBB0_381:
	s_add_u32 s27, s20, s26
	s_addc_u32 s46, s21, 0
	s_add_u32 s34, s27, 0x100
	s_addc_u32 s35, s46, 0
	s_and_b64 s[28:29], s[24:25], exec
	s_cselect_b32 s29, s11, s35
	s_cselect_b32 s28, s77, s34
	s_add_u32 s26, s14, s26
	s_addc_u32 s34, s15, 0
	s_add_u32 s26, s26, 0x100
	s_addc_u32 s34, s34, 0
	s_add_i32 s87, 0, 0x10000
	s_and_b64 s[24:25], s[24:25], exec
	s_cselect_b32 s35, s9, s34
	s_cselect_b32 s34, s78, s26
	s_add_i32 s25, 0, 0x14000
	s_add_u32 s48, s27, 0x10080
	s_addc_u32 s49, s46, 0
	s_add_i32 s86, s87, s58
	s_add_i32 m0, s13, 0xc000
	s_add_i32 s89, s13, 0xe000
	s_add_i32 s83, s86, 0x2000
	s_add_u32 s46, s34, 0x10000
	v_add_u32_e32 v152, s87, v141
	v_add_u32_e32 v160, s25, v141
	s_addc_u32 s47, s35, 0
	s_add_i32 s85, s25, s58
	ds_read_b128 v[136:139], v152
	ds_read_b128 v[144:147], v152 offset:1024
	ds_read_b128 v[148:151], v152 offset:2048
	ds_read_b128 v[152:155], v152 offset:3072
	ds_read_b128 v[156:159], v160
	ds_read_b128 v[178:181], v160 offset:1024
	ds_read_b128 v[182:185], v160 offset:2048
	ds_read_b128 v[186:189], v160 offset:3072
	s_add_i32 s84, s85, 0x2000
	s_add_i32 s82, 0, 0x18000
	s_add_i32 s81, 0, 0x1c000
	s_add_u32 s26, s28, 0x10000
	s_addc_u32 s27, s29, 0
	s_add_i32 s80, s82, s58
	s_add_i32 s79, s80, 0x2000
	s_add_u32 s24, s34, 0x10080
	s_addc_u32 s25, s35, 0
	s_add_i32 s88, s81, s58
	s_add_i32 s87, s88, 0x2000
	v_lshl_add_u64 v[160:161], s[48:49], 0, v[130:131]
	ds_read_b128 v[190:193], v143
	ds_read_b128 v[194:197], v143 offset:1024
	ds_read_b128 v[198:201], v143 offset:2048
	ds_read_b128 v[202:205], v143 offset:3072
	ds_read_b128 v[214:217], v143 offset:4096
	ds_read_b128 v[218:221], v143 offset:5120
	ds_read_b128 v[222:225], v143 offset:6144
	ds_read_b128 v[226:229], v143 offset:7168
	global_load_lds_dwordx4 v[160:161], off
	v_lshl_add_u64 v[160:161], s[48:49], 0, v[132:133]
	s_mov_b32 m0, s89
	s_nop 0
	global_load_lds_dwordx4 v[160:161], off
	s_waitcnt vmcnt(8)
	s_waitcnt lgkmcnt(0)
	s_barrier
	s_setprio 1
	v_mfma_f32_16x16x32_bf16 v[126:129], v[136:139], v[190:193], v[126:129]
	v_mfma_f32_16x16x32_bf16 v[122:125], v[148:151], v[190:193], v[122:125]
	v_mfma_f32_16x16x32_bf16 v[118:121], v[136:139], v[198:201], v[118:121]
	v_mfma_f32_16x16x32_bf16 v[110:113], v[148:151], v[198:201], v[110:113]
	v_mfma_f32_16x16x32_bf16 v[102:105], v[136:139], v[214:217], v[102:105]
	v_mfma_f32_16x16x32_bf16 v[94:97], v[148:151], v[214:217], v[94:97]
	v_mfma_f32_16x16x32_bf16 v[86:89], v[136:139], v[222:225], v[86:89]
	v_mfma_f32_16x16x32_bf16 v[78:81], v[148:151], v[222:225], v[78:81]
	v_mfma_f32_16x16x32_bf16 v[126:129], v[144:147], v[194:197], v[126:129]
	v_mfma_f32_16x16x32_bf16 v[122:125], v[152:155], v[194:197], v[122:125]
	v_mfma_f32_16x16x32_bf16 v[118:121], v[144:147], v[202:205], v[118:121]
	v_mfma_f32_16x16x32_bf16 v[110:113], v[152:155], v[202:205], v[110:113]
	v_mfma_f32_16x16x32_bf16 v[102:105], v[144:147], v[218:221], v[102:105]
	v_mfma_f32_16x16x32_bf16 v[94:97], v[152:155], v[218:221], v[94:97]
	v_mfma_f32_16x16x32_bf16 v[86:89], v[144:147], v[226:229], v[86:89]
	v_mfma_f32_16x16x32_bf16 v[78:81], v[152:155], v[226:229], v[78:81]
	s_setprio 0
	s_setprio 1
	v_mfma_f32_16x16x32_bf16 v[114:117], v[156:159], v[190:193], v[114:117]
	v_mfma_f32_16x16x32_bf16 v[106:109], v[182:185], v[190:193], v[106:109]
	v_mfma_f32_16x16x32_bf16 v[98:101], v[156:159], v[198:201], v[98:101]
	v_mfma_f32_16x16x32_bf16 v[90:93], v[182:185], v[198:201], v[90:93]
	v_mfma_f32_16x16x32_bf16 v[82:85], v[156:159], v[214:217], v[82:85]
	v_mfma_f32_16x16x32_bf16 v[74:77], v[182:185], v[214:217], v[74:77]
	v_mfma_f32_16x16x32_bf16 v[70:73], v[156:159], v[222:225], v[70:73]
	v_mfma_f32_16x16x32_bf16 v[66:69], v[182:185], v[222:225], v[66:69]
	v_mfma_f32_16x16x32_bf16 v[114:117], v[178:181], v[194:197], v[114:117]
	v_mfma_f32_16x16x32_bf16 v[106:109], v[186:189], v[194:197], v[106:109]
	v_mfma_f32_16x16x32_bf16 v[98:101], v[178:181], v[202:205], v[98:101]
	v_mfma_f32_16x16x32_bf16 v[90:93], v[186:189], v[202:205], v[90:93]
	v_mfma_f32_16x16x32_bf16 v[82:85], v[178:181], v[218:221], v[82:85]
	v_mfma_f32_16x16x32_bf16 v[74:77], v[186:189], v[218:221], v[74:77]
	v_mfma_f32_16x16x32_bf16 v[70:73], v[178:181], v[226:229], v[70:73]
	v_mfma_f32_16x16x32_bf16 v[66:69], v[186:189], v[226:229], v[66:69]
	s_setprio 0
	s_barrier
	s_mov_b32 m0, s86
	v_lshl_add_u64 v[160:161], s[34:35], 0, v[0:1]
	ds_read_b128 v[190:193], v143 offset:16384
	ds_read_b128 v[194:197], v143 offset:17408
	ds_read_b128 v[198:201], v143 offset:18432
	ds_read_b128 v[202:205], v143 offset:19456
	ds_read_b128 v[214:217], v143 offset:20480
	ds_read_b128 v[218:221], v143 offset:21504
	ds_read_b128 v[222:225], v143 offset:22528
	ds_read_b128 v[226:229], v143 offset:23552
	global_load_lds_dwordx4 v[160:161], off
	v_lshl_add_u64 v[162:163], s[34:35], 0, v[134:135]
	s_mov_b32 m0, s83
	v_lshl_add_u64 v[164:165], s[46:47], 0, v[0:1]
	global_load_lds_dwordx4 v[162:163], off
	s_mov_b32 m0, s85
	v_lshl_add_u64 v[166:167], s[28:29], 0, v[132:133]
	global_load_lds_dwordx4 v[164:165], off
	v_lshl_add_u64 v[164:165], s[46:47], 0, v[134:135]
	s_mov_b32 m0, s84
	s_nop 0
	global_load_lds_dwordx4 v[164:165], off
	v_lshl_add_u64 v[164:165], s[28:29], 0, v[130:131]
	s_mov_b32 m0, s13
	s_nop 0
	global_load_lds_dwordx4 v[164:165], off
	s_mov_b32 m0, s62
	s_nop 0
	global_load_lds_dwordx4 v[166:167], off
	s_waitcnt vmcnt(8)
	s_waitcnt lgkmcnt(0)
	s_barrier
; #define PG8_STAGE(bufoff, gbase, voff) do { _Pragma("unroll") for (int _i = 0; _i < 2; ++_i) \
;         __builtin_amdgcn_global_load_lds((const unsigned*)((const char*)(gbase) + (voff)[_i]), (PG8_LAS unsigned*)(lds + (bufoff) + ldsw + _i * 8192), 16, 0, 0); } while (0)
; #define PG8_LDA(dst, b, h) do { _Pragma("unroll") for (int m = 0; m < 4; ++m) _Pragma("unroll") for (int k = 0; k < 2; ++k) dst[m][k] = *(const PG8_LAS bf16x8*)(lds + PG8_SA(b, h) + aoff + m * 2048 + k * 1024); } while (0)
; #define PG8_LDB(dst, b, h) do { _Pragma("unroll") for (int n = 0; n < 2; ++n) _Pragma("unroll") for (int k = 0; k < 2; ++k) dst[n][k] = *(const PG8_LAS bf16x8*)(lds + PG8_SB(b, h) + boff + n * 2048 + k * 1024); } while (0)
; #define PG8_MMA(ai, bj, At, Bt) do { __builtin_amdgcn_s_setprio(1); _Pragma("unroll") for (int m = 0; m < 4; ++m) _Pragma("unroll") for (int n = 0; n < 2; ++n) _Pragma("unroll") for (int k = 0; k < 2; ++k) \
;         acc[ai][bj][m][n] = __builtin_amdgcn_mfma_f32_16x16x32_bf16(Bt[n][k], At[m][k], acc[ai][bj][m][n], 0, 0, 0); __builtin_amdgcn_s_setprio(0); } while (0)
; #define PG8_WAIT_V(n) asm volatile("s_waitcnt vmcnt(" #n ")" ::: "memory")
; #define PG8_WAIT_L(n) asm volatile("s_waitcnt lgkmcnt(" #n ")" ::: "memory")
; #define PG8_BAR __builtin_amdgcn_s_barrier()
; #define PG8_SCHED __builtin_amdgcn_sched_barrier(0)
; template <class Epi, class Sched, bool ALIGN_EPI = false, bool SP2 = false>
; __device__ __forceinline__ void gemm_phase(PG8_LAS unsigned char* lds, const Gemm g, const Sched& S, const Epi& E, int wave_s) {
;     ...
;             PG8_WAIT_V(8); PG8_WAIT_L(0); PG8_BAR; PG8_MMA(1, 0, At, B0); PG8_MMA(1, 1, At, B1); PG8_BAR; PG8_SCHED;
;             PG8_LDB(B0, 1, 0); PG8_LDB(B1, 1, 1); PG8_SCHED; PG8_LDA(At, 1, 0); PG8_STAGE(PG8_SA(0, 1), a2 + hstep, voffA);
;             PG8_WAIT_V(8); PG8_WAIT_L(0); PG8_BAR; PG8_MMA(0, 0, At, B0); PG8_MMA(0, 1, At, B1); PG8_BAR; PG8_SCHED;
	s_setprio 1
	v_mfma_f32_16x16x32_bf16 v[62:65], v[136:139], v[190:193], v[62:65]
	v_mfma_f32_16x16x32_bf16 v[58:61], v[148:151], v[190:193], v[58:61]
	v_mfma_f32_16x16x32_bf16 v[54:57], v[136:139], v[198:201], v[54:57]
	v_mfma_f32_16x16x32_bf16 v[46:49], v[148:151], v[198:201], v[46:49]
	v_mfma_f32_16x16x32_bf16 v[38:41], v[136:139], v[214:217], v[38:41]
	v_mfma_f32_16x16x32_bf16 v[30:33], v[148:151], v[214:217], v[30:33]
	v_mfma_f32_16x16x32_bf16 v[22:25], v[136:139], v[222:225], v[22:25]
	v_mfma_f32_16x16x32_bf16 v[14:17], v[148:151], v[222:225], v[14:17]
	v_mfma_f32_16x16x32_bf16 v[62:65], v[144:147], v[194:197], v[62:65]
	v_mfma_f32_16x16x32_bf16 v[58:61], v[152:155], v[194:197], v[58:61]
	v_mfma_f32_16x16x32_bf16 v[54:57], v[144:147], v[202:205], v[54:57]
	v_mfma_f32_16x16x32_bf16 v[46:49], v[152:155], v[202:205], v[46:49]
	v_mfma_f32_16x16x32_bf16 v[38:41], v[144:147], v[218:221], v[38:41]
	v_mfma_f32_16x16x32_bf16 v[30:33], v[152:155], v[218:221], v[30:33]
	v_mfma_f32_16x16x32_bf16 v[22:25], v[144:147], v[226:229], v[22:25]
	v_mfma_f32_16x16x32_bf16 v[14:17], v[152:155], v[226:229], v[14:17]
	s_setprio 0
	s_setprio 1
	v_mfma_f32_16x16x32_bf16 v[50:53], v[156:159], v[190:193], v[50:53]
	v_mfma_f32_16x16x32_bf16 v[42:45], v[182:185], v[190:193], v[42:45]
	v_mfma_f32_16x16x32_bf16 v[34:37], v[156:159], v[198:201], v[34:37]
	v_mfma_f32_16x16x32_bf16 v[26:29], v[182:185], v[198:201], v[26:29]
	v_mfma_f32_16x16x32_bf16 v[18:21], v[156:159], v[214:217], v[18:21]
	v_mfma_f32_16x16x32_bf16 v[10:13], v[182:185], v[214:217], v[10:13]
	v_mfma_f32_16x16x32_bf16 v[6:9], v[156:159], v[222:225], v[6:9]
	v_mfma_f32_16x16x32_bf16 v[2:5], v[182:185], v[222:225], v[2:5]
	v_mfma_f32_16x16x32_bf16 v[50:53], v[178:181], v[194:197], v[50:53]
	v_mfma_f32_16x16x32_bf16 v[42:45], v[186:189], v[194:197], v[42:45]
	v_mfma_f32_16x16x32_bf16 v[34:37], v[178:181], v[202:205], v[34:37]
	v_mfma_f32_16x16x32_bf16 v[26:29], v[186:189], v[202:205], v[26:29]
	v_mfma_f32_16x16x32_bf16 v[18:21], v[178:181], v[218:221], v[18:21]
	v_mfma_f32_16x16x32_bf16 v[10:13], v[186:189], v[218:221], v[10:13]
	v_mfma_f32_16x16x32_bf16 v[6:9], v[178:181], v[226:229], v[6:9]
	v_mfma_f32_16x16x32_bf16 v[2:5], v[186:189], v[226:229], v[2:5]
	s_setprio 0
	s_barrier
	v_add_u32_e32 v152, s82, v141
	v_add_u32_e32 v168, s81, v141
	ds_read_b128 v[136:139], v152
	ds_read_b128 v[144:147], v152 offset:1024
	ds_read_b128 v[148:151], v152 offset:2048
	ds_read_b128 v[152:155], v152 offset:3072
	ds_read_b128 v[156:159], v168
	ds_read_b128 v[178:181], v168 offset:1024
	ds_read_b128 v[182:185], v168 offset:2048
	ds_read_b128 v[186:189], v168 offset:3072
	s_mov_b32 m0, s63
	v_lshl_add_u64 v[168:169], s[26:27], 0, v[130:131]
	ds_read_b128 v[190:193], v143 offset:32768
	ds_read_b128 v[194:197], v143 offset:33792
	ds_read_b128 v[198:201], v143 offset:34816
	ds_read_b128 v[202:205], v143 offset:35840
	ds_read_b128 v[214:217], v143 offset:36864
	ds_read_b128 v[218:221], v143 offset:37888
	ds_read_b128 v[222:225], v143 offset:38912
	ds_read_b128 v[226:229], v143 offset:39936
	global_load_lds_dwordx4 v[168:169], off
	v_lshl_add_u64 v[168:169], s[26:27], 0, v[132:133]
	s_mov_b32 m0, s70
	s_nop 0
	global_load_lds_dwordx4 v[168:169], off
	s_waitcnt vmcnt(8)
	s_waitcnt lgkmcnt(0)
	s_barrier
	s_setprio 1
	v_mfma_f32_16x16x32_bf16 v[126:129], v[136:139], v[190:193], v[126:129]
	v_mfma_f32_16x16x32_bf16 v[122:125], v[148:151], v[190:193], v[122:125]
	v_mfma_f32_16x16x32_bf16 v[118:121], v[136:139], v[198:201], v[118:121]
	v_mfma_f32_16x16x32_bf16 v[110:113], v[148:151], v[198:201], v[110:113]
	v_mfma_f32_16x16x32_bf16 v[102:105], v[136:139], v[214:217], v[102:105]
	v_mfma_f32_16x16x32_bf16 v[94:97], v[148:151], v[214:217], v[94:97]
	v_mfma_f32_16x16x32_bf16 v[86:89], v[136:139], v[222:225], v[86:89]
	v_mfma_f32_16x16x32_bf16 v[78:81], v[148:151], v[222:225], v[78:81]
	v_mfma_f32_16x16x32_bf16 v[126:129], v[144:147], v[194:197], v[126:129]
	v_mfma_f32_16x16x32_bf16 v[122:125], v[152:155], v[194:197], v[122:125]
	v_mfma_f32_16x16x32_bf16 v[118:121], v[144:147], v[202:205], v[118:121]
	v_mfma_f32_16x16x32_bf16 v[110:113], v[152:155], v[202:205], v[110:113]
	v_mfma_f32_16x16x32_bf16 v[102:105], v[144:147], v[218:221], v[102:105]
	v_mfma_f32_16x16x32_bf16 v[94:97], v[152:155], v[218:221], v[94:97]
	v_mfma_f32_16x16x32_bf16 v[86:89], v[144:147], v[226:229], v[86:89]
	v_mfma_f32_16x16x32_bf16 v[78:81], v[152:155], v[226:229], v[78:81]
	s_setprio 0
	s_setprio 1
	v_mfma_f32_16x16x32_bf16 v[114:117], v[156:159], v[190:193], v[114:117]
	v_mfma_f32_16x16x32_bf16 v[106:109], v[182:185], v[190:193], v[106:109]
	v_mfma_f32_16x16x32_bf16 v[98:101], v[156:159], v[198:201], v[98:101]
	v_mfma_f32_16x16x32_bf16 v[90:93], v[182:185], v[198:201], v[90:93]
	v_mfma_f32_16x16x32_bf16 v[82:85], v[156:159], v[214:217], v[82:85]
	v_mfma_f32_16x16x32_bf16 v[74:77], v[182:185], v[214:217], v[74:77]
	v_mfma_f32_16x16x32_bf16 v[70:73], v[156:159], v[222:225], v[70:73]
	v_mfma_f32_16x16x32_bf16 v[66:69], v[182:185], v[222:225], v[66:69]
	v_mfma_f32_16x16x32_bf16 v[114:117], v[178:181], v[194:197], v[114:117]
	v_mfma_f32_16x16x32_bf16 v[106:109], v[186:189], v[194:197], v[106:109]
	v_mfma_f32_16x16x32_bf16 v[98:101], v[178:181], v[202:205], v[98:101]
	v_mfma_f32_16x16x32_bf16 v[90:93], v[186:189], v[202:205], v[90:93]
	v_mfma_f32_16x16x32_bf16 v[82:85], v[178:181], v[218:221], v[82:85]
	v_mfma_f32_16x16x32_bf16 v[74:77], v[186:189], v[218:221], v[74:77]
	v_mfma_f32_16x16x32_bf16 v[70:73], v[178:181], v[226:229], v[70:73]
	v_mfma_f32_16x16x32_bf16 v[66:69], v[186:189], v[226:229], v[66:69]
	s_setprio 0
	s_barrier
; #define PG8_STAGE(bufoff, gbase, voff) do { _Pragma("unroll") for (int _i = 0; _i < 2; ++_i) \
;         __builtin_amdgcn_global_load_lds((const unsigned*)((const char*)(gbase) + (voff)[_i]), (PG8_LAS unsigned*)(lds + (bufoff) + ldsw + _i * 8192), 16, 0, 0); } while (0)
; #define PG8_LDA(dst, b, h) do { _Pragma("unroll") for (int m = 0; m < 4; ++m) _Pragma("unroll") for (int k = 0; k < 2; ++k) dst[m][k] = *(const PG8_LAS bf16x8*)(lds + PG8_SA(b, h) + aoff + m * 2048 + k * 1024); } while (0)
; #define PG8_MMA(ai, bj, At, Bt) do { __builtin_amdgcn_s_setprio(1); _Pragma("unroll") for (int m = 0; m < 4; ++m) _Pragma("unroll") for (int n = 0; n < 2; ++n) _Pragma("unroll") for (int k = 0; k < 2; ++k) \
;         acc[ai][bj][m][n] = __builtin_amdgcn_mfma_f32_16x16x32_bf16(Bt[n][k], At[m][k], acc[ai][bj][m][n], 0, 0, 0); __builtin_amdgcn_s_setprio(0); } while (0)
; #define PG8_WAIT_V(n) asm volatile("s_waitcnt vmcnt(" #n ")" ::: "memory")
; #define PG8_WAIT_L(n) asm volatile("s_waitcnt lgkmcnt(" #n ")" ::: "memory")
; #define PG8_BAR __builtin_amdgcn_s_barrier()
; #define PG8_SCHED __builtin_amdgcn_sched_barrier(0)
; template <class Epi, class Sched, bool ALIGN_EPI = false, bool SP2 = false>
; __device__ __forceinline__ void gemm_phase(PG8_LAS unsigned char* lds, const Gemm g, const Sched& S, const Epi& E, int wave_s) {
;     ...
;             PG8_LDA(At, 1, 1); PG8_STAGE(PG8_SB(1, 0), b3, voffB); PG8_STAGE(PG8_SB(1, 1), b3 + hstep, voffB); PG8_STAGE(PG8_SA(1, 0), a3, voffA);
;             PG8_WAIT_V(8); PG8_WAIT_L(0); PG8_BAR; PG8_MMA(1, 0, At, B0); PG8_MMA(1, 1, At, B1); PG8_BAR; PG8_SCHED;
;     ...
;         if constexpr (ALIGN_EPI) { if (wr == 0) PG8_BAR; }
	s_mov_b32 m0, s80
	v_lshl_add_u64 v[160:161], v[160:161], 0, s[60:61]
	ds_read_b128 v[190:193], v143 offset:49152
	ds_read_b128 v[194:197], v143 offset:50176
	ds_read_b128 v[198:201], v143 offset:51200
	ds_read_b128 v[202:205], v143 offset:52224
	ds_read_b128 v[214:217], v143 offset:53248
	ds_read_b128 v[218:221], v143 offset:54272
	ds_read_b128 v[222:225], v143 offset:55296
	ds_read_b128 v[226:229], v143 offset:56320
	global_load_lds_dwordx4 v[160:161], off
	v_lshl_add_u64 v[160:161], v[162:163], 0, s[60:61]
	s_mov_b32 m0, s79
	s_nop 0
	global_load_lds_dwordx4 v[160:161], off
	v_lshl_add_u64 v[160:161], s[24:25], 0, v[0:1]
	s_mov_b32 m0, s88
	s_nop 0
	global_load_lds_dwordx4 v[160:161], off
	v_lshl_add_u64 v[160:161], s[24:25], 0, v[134:135]
	s_mov_b32 m0, s87
	s_nop 0
	global_load_lds_dwordx4 v[160:161], off
	v_lshl_add_u64 v[160:161], v[164:165], 0, s[60:61]
	s_mov_b32 m0, s72
	s_nop 0
	global_load_lds_dwordx4 v[160:161], off
	v_lshl_add_u64 v[160:161], v[166:167], 0, s[60:61]
	s_mov_b32 m0, s73
	s_nop 0
	global_load_lds_dwordx4 v[160:161], off
	s_waitcnt vmcnt(8)
	s_waitcnt lgkmcnt(0)
	s_barrier
	s_setprio 1
	v_mfma_f32_16x16x32_bf16 v[62:65], v[136:139], v[190:193], v[62:65]
	v_mfma_f32_16x16x32_bf16 v[58:61], v[148:151], v[190:193], v[58:61]
	v_mfma_f32_16x16x32_bf16 v[54:57], v[136:139], v[198:201], v[54:57]
	v_mfma_f32_16x16x32_bf16 v[46:49], v[148:151], v[198:201], v[46:49]
	v_mfma_f32_16x16x32_bf16 v[38:41], v[136:139], v[214:217], v[38:41]
	v_mfma_f32_16x16x32_bf16 v[30:33], v[148:151], v[214:217], v[30:33]
	v_mfma_f32_16x16x32_bf16 v[22:25], v[136:139], v[222:225], v[22:25]
	v_mfma_f32_16x16x32_bf16 v[14:17], v[148:151], v[222:225], v[14:17]
	v_mfma_f32_16x16x32_bf16 v[62:65], v[144:147], v[194:197], v[62:65]
	v_mfma_f32_16x16x32_bf16 v[58:61], v[152:155], v[194:197], v[58:61]
	v_mfma_f32_16x16x32_bf16 v[54:57], v[144:147], v[202:205], v[54:57]
	v_mfma_f32_16x16x32_bf16 v[46:49], v[152:155], v[202:205], v[46:49]
	v_mfma_f32_16x16x32_bf16 v[38:41], v[144:147], v[218:221], v[38:41]
	v_mfma_f32_16x16x32_bf16 v[30:33], v[152:155], v[218:221], v[30:33]
	v_mfma_f32_16x16x32_bf16 v[22:25], v[144:147], v[226:229], v[22:25]
	v_mfma_f32_16x16x32_bf16 v[14:17], v[152:155], v[226:229], v[14:17]
	s_setprio 0
	s_setprio 1
	v_mfma_f32_16x16x32_bf16 v[50:53], v[156:159], v[190:193], v[50:53]
	v_mfma_f32_16x16x32_bf16 v[42:45], v[182:185], v[190:193], v[42:45]
	v_mfma_f32_16x16x32_bf16 v[34:37], v[156:159], v[198:201], v[34:37]
	v_mfma_f32_16x16x32_bf16 v[26:29], v[182:185], v[198:201], v[26:29]
	v_mfma_f32_16x16x32_bf16 v[18:21], v[156:159], v[214:217], v[18:21]
	v_mfma_f32_16x16x32_bf16 v[10:13], v[182:185], v[214:217], v[10:13]
	v_mfma_f32_16x16x32_bf16 v[6:9], v[156:159], v[222:225], v[6:9]
	v_mfma_f32_16x16x32_bf16 v[2:5], v[182:185], v[222:225], v[2:5]
	v_mfma_f32_16x16x32_bf16 v[50:53], v[178:181], v[194:197], v[50:53]
	v_mfma_f32_16x16x32_bf16 v[42:45], v[186:189], v[194:197], v[42:45]
	v_mfma_f32_16x16x32_bf16 v[34:37], v[178:181], v[202:205], v[34:37]
	v_mfma_f32_16x16x32_bf16 v[26:29], v[186:189], v[202:205], v[26:29]
	v_mfma_f32_16x16x32_bf16 v[18:21], v[178:181], v[218:221], v[18:21]
	v_mfma_f32_16x16x32_bf16 v[10:13], v[186:189], v[218:221], v[10:13]
	v_mfma_f32_16x16x32_bf16 v[6:9], v[178:181], v[226:229], v[6:9]
	v_mfma_f32_16x16x32_bf16 v[2:5], v[186:189], v[226:229], v[2:5]
	s_setprio 0
	s_barrier
	s_movk_i32 s26, 0x100
	s_andn2_b64 vcc, exec, s[22:23]
	s_mov_b64 s[24:25], -1
	s_mov_b64 s[22:23], 0
	s_cbranch_vccz .LBB0_381
	s_and_b64 vcc, exec, s[6:7]
	s_cbranch_vccz .LBB0_384
	s_barrier

; #define PG8_STAGE(bufoff, gbase, voff) do { _Pragma("unroll") for (int _i = 0; _i < 2; ++_i) \
;         __builtin_amdgcn_global_load_lds((const unsigned*)((const char*)(gbase) + (voff)[_i]), (PG8_LAS unsigned*)(lds + (bufoff) + ldsw + _i * 8192), 16, 0, 0); } while (0)
; #define PG8_LDA(dst, b, h) do { _Pragma("unroll") for (int m = 0; m < 4; ++m) _Pragma("unroll") for (int k = 0; k < 2; ++k) dst[m][k] = *(const PG8_LAS bf16x8*)(lds + PG8_SA(b, h) + aoff + m * 2048 + k * 1024); } while (0)
; #define PG8_LDB(dst, b, h) do { _Pragma("unroll") for (int n = 0; n < 2; ++n) _Pragma("unroll") for (int k = 0; k < 2; ++k) dst[n][k] = *(const PG8_LAS bf16x8*)(lds + PG8_SB(b, h) + boff + n * 2048 + k * 1024); } while (0)
; #define PG8_WAIT_V(n) asm volatile("s_waitcnt vmcnt(" #n ")" ::: "memory")
; #define PG8_WAIT_L(n) asm volatile("s_waitcnt lgkmcnt(" #n ")" ::: "memory")
; #define PG8_BAR __builtin_amdgcn_s_barrier()
; #define PG8_SCHED __builtin_amdgcn_sched_barrier(0)
; template <class Epi, class Sched, bool ALIGN_EPI = false, bool SP2 = false>
; __device__ __forceinline__ void gemm_phase(PG8_LAS unsigned char* lds, const Gemm g, const Sched& S, const Epi& E, int wave_s) {
;     ...
;         const char* nA = has_next ? (const char*)g.A + (size_t)nxt.pm * tstep + (size_t)nxt.kq * kqstep : cA; const char* nB = has_next ? (const char*)g.Bt + (size_t)nxt.pn * tstep + (size_t)nxt.kq * kqstep : cB;
;         for (int t = 0; t < nt; t += 2) {
;             const bool last = (t == nt - 2);
;             const char* a1 = cA + (size_t)(t + 1) * kstep;
;             const char* a2 = last ? nA : cA + (size_t)(t + 2) * kstep; const char* b2 = last ? nB : cB + (size_t)(t + 2) * kstep;
;             const char* a3 = a2 + kstep; const char* b3 = b2 + kstep;
;             if (last && has_next) S.a_ready(nxt);
;             if constexpr (SP2) {
;             PG8_LDB(B0, 0, 0); PG8_LDB(B1, 0, 1); PG8_SCHED; PG8_LDA(At, 0, 0); PG8_STAGE(PG8_SA(1, 1), a1 + hstep, voffA);
;             PG8_WAIT_V(8); PG8_WAIT_L(0); PG8_BAR; PG8_MMA(0, 0, At, B0); PG8_MMA(0, 1, At, B1); PG8_BAR; PG8_SCHED;
;             PG8_LDA(At, 0, 1); PG8_STAGE(PG8_SB(0, 0), b2, voffB); PG8_STAGE(PG8_SB(0, 1), b2 + hstep, voffB); PG8_STAGE(PG8_SA(0, 0), a2, voffA);
;             PG8_WAIT_V(8); PG8_WAIT_L(0); PG8_BAR; PG8_MMA(1, 0, At, B0); PG8_MMA(1, 1, At, B1); PG8_BAR; PG8_SCHED;
.LBB0_396:
	s_ashr_i32 s13, s12, 31
	s_lshl_b64 s[14:15], s[12:13], 16
	s_add_u32 s14, s27, s14
	s_addc_u32 s15, s28, s15
	s_and_b64 s[16:17], s[2:3], exec
	s_cselect_b32 s25, s15, s23
	s_cselect_b32 s24, s14, s22
	s_ashr_i32 s11, s10, 31
	s_lshl_b64 s[16:17], s[10:11], 16
	s_add_u32 s16, s29, s16
	s_addc_u32 s17, s34, s17
	s_and_b64 s[56:57], s[2:3], exec
	s_cselect_b32 s21, s17, s21
	s_cselect_b32 s20, s16, s20
	s_add_i32 s11, 0, 0x10000
	s_add_i32 s13, 0, 0x14000
	v_add_u32_e32 v14, s11, v139
	v_add_u32_e32 v30, s13, v139
	ds_read_b128 v[2:5], v14
	ds_read_b128 v[6:9], v14 offset:1024
	ds_read_b128 v[10:13], v14 offset:2048
	ds_read_b128 v[14:17], v14 offset:3072
	ds_read_b128 v[18:21], v30
	ds_read_b128 v[22:25], v30 offset:1024
	ds_read_b128 v[26:29], v30 offset:2048
	ds_read_b128 v[30:33], v30 offset:3072
	s_add_u32 s22, s22, 0x8080
	s_addc_u32 s23, s23, 0
	v_lshl_add_u64 v[66:67], s[22:23], 0, v[134:135]
	s_add_i32 m0, s19, 0xc000
	ds_read_b128 v[34:37], v141
	ds_read_b128 v[38:41], v141 offset:1024
	ds_read_b128 v[42:45], v141 offset:2048
	ds_read_b128 v[46:49], v141 offset:3072
	ds_read_b128 v[50:53], v141 offset:4096
	ds_read_b128 v[54:57], v141 offset:5120
	ds_read_b128 v[58:61], v141 offset:6144
	ds_read_b128 v[62:65], v141 offset:7168
	global_load_lds_dwordx4 v[66:67], off
	v_lshl_add_u64 v[66:67], s[22:23], 0, v[132:133]
	s_add_i32 m0, s19, 0xe000
	s_nop 0
	global_load_lds_dwordx4 v[66:67], off
	s_waitcnt vmcnt(8)
	s_waitcnt lgkmcnt(0)
	s_barrier
	s_setprio 1
	v_mfma_f32_16x16x32_bf16 v[90:93], v[2:5], v[58:61], 0
	v_mfma_f32_16x16x32_bf16 v[66:69], v[2:5], v[34:37], 0
	v_mfma_f32_16x16x32_bf16 v[70:73], v[10:13], v[34:37], 0
	v_mfma_f32_16x16x32_bf16 v[74:77], v[2:5], v[42:45], 0
	v_mfma_f32_16x16x32_bf16 v[78:81], v[10:13], v[42:45], 0
	v_mfma_f32_16x16x32_bf16 v[82:85], v[2:5], v[50:53], 0
	v_mfma_f32_16x16x32_bf16 v[86:89], v[10:13], v[50:53], 0
	v_mfma_f32_16x16x32_bf16 v[94:97], v[6:9], v[62:65], v[90:93]
	v_mfma_f32_16x16x32_bf16 v[90:93], v[10:13], v[58:61], 0
	v_mfma_f32_16x16x32_bf16 v[66:69], v[6:9], v[38:41], v[66:69]
	v_mfma_f32_16x16x32_bf16 v[70:73], v[14:17], v[38:41], v[70:73]
	v_mfma_f32_16x16x32_bf16 v[74:77], v[6:9], v[46:49], v[74:77]
	v_mfma_f32_16x16x32_bf16 v[78:81], v[14:17], v[46:49], v[78:81]
	v_mfma_f32_16x16x32_bf16 v[82:85], v[6:9], v[54:57], v[82:85]
	v_mfma_f32_16x16x32_bf16 v[86:89], v[14:17], v[54:57], v[86:89]
	v_mfma_f32_16x16x32_bf16 v[102:105], v[14:17], v[62:65], v[90:93]
	s_setprio 0
	s_setprio 1
	v_mfma_f32_16x16x32_bf16 v[90:93], v[18:21], v[34:37], 0
	v_mfma_f32_16x16x32_bf16 v[34:37], v[26:29], v[34:37], 0
	v_mfma_f32_16x16x32_bf16 v[110:113], v[22:25], v[38:41], v[90:93]
	v_mfma_f32_16x16x32_bf16 v[34:37], v[30:33], v[38:41], v[34:37]
	v_mfma_f32_16x16x32_bf16 v[38:41], v[18:21], v[42:45], 0
	v_mfma_f32_16x16x32_bf16 v[42:45], v[26:29], v[42:45], 0
	v_mfma_f32_16x16x32_bf16 v[38:41], v[22:25], v[46:49], v[38:41]
	v_mfma_f32_16x16x32_bf16 v[42:45], v[30:33], v[46:49], v[42:45]
	v_mfma_f32_16x16x32_bf16 v[46:49], v[18:21], v[50:53], 0
	v_mfma_f32_16x16x32_bf16 v[50:53], v[26:29], v[50:53], 0
	v_mfma_f32_16x16x32_bf16 v[46:49], v[22:25], v[54:57], v[46:49]
	v_mfma_f32_16x16x32_bf16 v[54:57], v[30:33], v[54:57], v[50:53]
	v_mfma_f32_16x16x32_bf16 v[50:53], v[18:21], v[58:61], 0
	v_mfma_f32_16x16x32_bf16 v[142:145], v[22:25], v[62:65], v[50:53]
	v_mfma_f32_16x16x32_bf16 v[50:53], v[26:29], v[58:61], 0
	v_mfma_f32_16x16x32_bf16 v[146:149], v[30:33], v[62:65], v[50:53]
	s_setprio 0
	s_barrier
	s_add_i32 s11, s11, s35
	v_lshl_add_u64 v[136:137], s[20:21], 0, v[0:1]
	s_mov_b32 m0, s11
	s_nop 1
	ds_read_b128 v[50:53], v141 offset:16384
	ds_read_b128 v[58:61], v141 offset:17408
	ds_read_b128 v[62:65], v141 offset:18432
	ds_read_b128 v[90:93], v141 offset:19456
	ds_read_b128 v[98:101], v141 offset:20480
	ds_read_b128 v[106:109], v141 offset:21504
	ds_read_b128 v[114:117], v141 offset:22528
	ds_read_b128 v[118:121], v141 offset:23552
	global_load_lds_dwordx4 v[136:137], off
	s_add_i32 m0, s11, 0x2000
	s_add_u32 s22, s20, 0x8000
	v_lshl_add_u64 v[208:209], s[20:21], 0, v[130:131]
	s_addc_u32 s23, s21, 0
	s_add_i32 s11, s13, s35
	global_load_lds_dwordx4 v[208:209], off
	v_lshl_add_u64 v[122:123], s[22:23], 0, v[0:1]
	s_mov_b32 m0, s11
	v_lshl_add_u64 v[212:213], s[24:25], 0, v[134:135]
	global_load_lds_dwordx4 v[122:123], off
	v_lshl_add_u64 v[122:123], s[22:23], 0, v[130:131]
	s_add_i32 m0, s11, 0x2000
	v_lshl_add_u64 v[174:175], s[24:25], 0, v[132:133]
	global_load_lds_dwordx4 v[122:123], off
	s_mov_b32 m0, s19
	s_nop 0
	global_load_lds_dwordx4 v[212:213], off
	s_mov_b32 m0, s36
	s_nop 0
	global_load_lds_dwordx4 v[174:175], off
	s_waitcnt vmcnt(8)
	s_waitcnt lgkmcnt(0)
	s_barrier
; #define PG8_STAGE(bufoff, gbase, voff) do { _Pragma("unroll") for (int _i = 0; _i < 2; ++_i) \
;         __builtin_amdgcn_global_load_lds((const unsigned*)((const char*)(gbase) + (voff)[_i]), (PG8_LAS unsigned*)(lds + (bufoff) + ldsw + _i * 8192), 16, 0, 0); } while (0)
; #define PG8_LDA(dst, b, h) do { _Pragma("unroll") for (int m = 0; m < 4; ++m) _Pragma("unroll") for (int k = 0; k < 2; ++k) dst[m][k] = *(const PG8_LAS bf16x8*)(lds + PG8_SA(b, h) + aoff + m * 2048 + k * 1024); } while (0)
; #define PG8_LDB(dst, b, h) do { _Pragma("unroll") for (int n = 0; n < 2; ++n) _Pragma("unroll") for (int k = 0; k < 2; ++k) dst[n][k] = *(const PG8_LAS bf16x8*)(lds + PG8_SB(b, h) + boff + n * 2048 + k * 1024); } while (0)
; #define PG8_MMA(ai, bj, At, Bt) do { __builtin_amdgcn_s_setprio(1); _Pragma("unroll") for (int m = 0; m < 4; ++m) _Pragma("unroll") for (int n = 0; n < 2; ++n) _Pragma("unroll") for (int k = 0; k < 2; ++k) \
;         acc[ai][bj][m][n] = __builtin_amdgcn_mfma_f32_16x16x32_bf16(Bt[n][k], At[m][k], acc[ai][bj][m][n], 0, 0, 0); __builtin_amdgcn_s_setprio(0); } while (0)
; #define PG8_WAIT_V(n) asm volatile("s_waitcnt vmcnt(" #n ")" ::: "memory")
; #define PG8_WAIT_L(n) asm volatile("s_waitcnt lgkmcnt(" #n ")" ::: "memory")
; #define PG8_BAR __builtin_amdgcn_s_barrier()
; #define PG8_SCHED __builtin_amdgcn_sched_barrier(0)
; template <class Epi, class Sched, bool ALIGN_EPI = false, bool SP2 = false>
; __device__ __forceinline__ void gemm_phase(PG8_LAS unsigned char* lds, const Gemm g, const Sched& S, const Epi& E, int wave_s) {
;     ...
;             PG8_WAIT_V(8); PG8_WAIT_L(0); PG8_BAR; PG8_MMA(1, 0, At, B0); PG8_MMA(1, 1, At, B1); PG8_BAR; PG8_SCHED;
;             PG8_LDB(B0, 1, 0); PG8_LDB(B1, 1, 1); PG8_SCHED; PG8_LDA(At, 1, 0); PG8_STAGE(PG8_SA(0, 1), a2 + hstep, voffA);
;             PG8_WAIT_V(8); PG8_WAIT_L(0); PG8_BAR; PG8_MMA(0, 0, At, B0); PG8_MMA(0, 1, At, B1); PG8_BAR; PG8_SCHED;
	s_setprio 1
	v_mfma_f32_16x16x32_bf16 v[122:125], v[2:5], v[50:53], 0
	v_mfma_f32_16x16x32_bf16 v[150:153], v[6:9], v[58:61], v[122:125]
	v_mfma_f32_16x16x32_bf16 v[122:125], v[10:13], v[50:53], 0
	v_mfma_f32_16x16x32_bf16 v[154:157], v[14:17], v[58:61], v[122:125]
	v_mfma_f32_16x16x32_bf16 v[122:125], v[2:5], v[62:65], 0
	v_mfma_f32_16x16x32_bf16 v[158:161], v[6:9], v[90:93], v[122:125]
	v_mfma_f32_16x16x32_bf16 v[122:125], v[10:13], v[62:65], 0
	v_mfma_f32_16x16x32_bf16 v[178:181], v[14:17], v[90:93], v[122:125]
	v_mfma_f32_16x16x32_bf16 v[122:125], v[2:5], v[98:101], 0
	v_mfma_f32_16x16x32_bf16 v[2:5], v[2:5], v[114:117], 0
	v_mfma_f32_16x16x32_bf16 v[182:185], v[6:9], v[106:109], v[122:125]
	v_mfma_f32_16x16x32_bf16 v[2:5], v[6:9], v[118:121], v[2:5]
	v_mfma_f32_16x16x32_bf16 v[6:9], v[10:13], v[114:117], 0
	v_mfma_f32_16x16x32_bf16 v[122:125], v[10:13], v[98:101], 0
	v_mfma_f32_16x16x32_bf16 v[6:9], v[14:17], v[118:121], v[6:9]
	v_mfma_f32_16x16x32_bf16 v[186:189], v[14:17], v[106:109], v[122:125]
	s_setprio 0
	s_setprio 1
	v_mfma_f32_16x16x32_bf16 v[14:17], v[26:29], v[50:53], 0
	v_mfma_f32_16x16x32_bf16 v[190:193], v[30:33], v[58:61], v[14:17]
	v_mfma_f32_16x16x32_bf16 v[14:17], v[18:21], v[62:65], 0
	v_mfma_f32_16x16x32_bf16 v[194:197], v[22:25], v[90:93], v[14:17]
	v_mfma_f32_16x16x32_bf16 v[14:17], v[26:29], v[62:65], 0
	v_mfma_f32_16x16x32_bf16 v[198:201], v[30:33], v[90:93], v[14:17]
	v_mfma_f32_16x16x32_bf16 v[14:17], v[18:21], v[98:101], 0
	v_mfma_f32_16x16x32_bf16 v[202:205], v[22:25], v[106:109], v[14:17]
	v_mfma_f32_16x16x32_bf16 v[14:17], v[26:29], v[98:101], 0
	v_mfma_f32_16x16x32_bf16 v[10:13], v[18:21], v[50:53], 0
	v_mfma_f32_16x16x32_bf16 v[214:217], v[30:33], v[106:109], v[14:17]
	v_mfma_f32_16x16x32_bf16 v[14:17], v[18:21], v[114:117], 0
	v_mfma_f32_16x16x32_bf16 v[10:13], v[22:25], v[58:61], v[10:13]
	v_mfma_f32_16x16x32_bf16 v[218:221], v[22:25], v[118:121], v[14:17]
	v_mfma_f32_16x16x32_bf16 v[14:17], v[26:29], v[114:117], 0
	v_mfma_f32_16x16x32_bf16 v[222:225], v[30:33], v[118:121], v[14:17]
	s_setprio 0
	s_barrier
	s_add_i32 s11, 0, 0x18000
	v_add_u32_e32 v22, s11, v139
	s_add_i32 s13, 0, 0x1c000
	s_nop 1
	ds_read_b128 v[14:17], v22
	ds_read_b128 v[18:21], v22 offset:1024
	ds_read_b128 v[26:29], v22 offset:2048
	ds_read_b128 v[226:229], v22 offset:3072
	v_add_u32_e32 v22, s13, v139
	ds_read_b128 v[230:233], v22
	ds_read_b128 v[234:237], v22 offset:1024
	ds_read_b128 v[238:241], v22 offset:2048
	ds_read_b128 v[242:245], v22 offset:3072
	s_add_u32 s22, s24, 0x8000
	s_addc_u32 s23, s25, 0
	s_mov_b32 m0, s37
	v_lshl_add_u64 v[50:51], s[22:23], 0, v[134:135]
	ds_read_b128 v[22:25], v141 offset:32768
	ds_read_b128 v[30:33], v141 offset:33792
	ds_read_b128 v[62:65], v141 offset:34816
	ds_read_b128 v[246:249], v141 offset:35840
	ds_read_b128 v[250:253], v141 offset:36864
	ds_read_b128 v[162:165], v141 offset:37888
	ds_read_b128 v[166:169], v141 offset:38912
	ds_read_b128 v[170:173], v141 offset:39936
	global_load_lds_dwordx4 v[50:51], off
	v_lshl_add_u64 v[50:51], s[22:23], 0, v[132:133]
	s_mov_b32 m0, s46
	s_nop 0
	global_load_lds_dwordx4 v[50:51], off
	s_waitcnt vmcnt(8)
	s_waitcnt lgkmcnt(0)
	s_barrier
	s_setprio 1
	v_mfma_f32_16x16x32_bf16 v[50:53], v[14:17], v[22:25], v[66:69]
	v_mfma_f32_16x16x32_bf16 v[122:125], v[18:21], v[30:33], v[50:53]
	v_mfma_f32_16x16x32_bf16 v[50:53], v[26:29], v[22:25], v[70:73]
	v_mfma_f32_16x16x32_bf16 v[114:117], v[226:229], v[30:33], v[50:53]
	v_mfma_f32_16x16x32_bf16 v[50:53], v[14:17], v[62:65], v[74:77]
	v_mfma_f32_16x16x32_bf16 v[106:109], v[18:21], v[246:249], v[50:53]
	v_mfma_f32_16x16x32_bf16 v[50:53], v[26:29], v[62:65], v[78:81]
	v_mfma_f32_16x16x32_bf16 v[98:101], v[226:229], v[246:249], v[50:53]
	v_mfma_f32_16x16x32_bf16 v[50:53], v[14:17], v[250:253], v[82:85]
	v_mfma_f32_16x16x32_bf16 v[90:93], v[18:21], v[162:165], v[50:53]
	v_mfma_f32_16x16x32_bf16 v[50:53], v[26:29], v[250:253], v[86:89]
	v_mfma_f32_16x16x32_bf16 v[82:85], v[226:229], v[162:165], v[50:53]
	v_mfma_f32_16x16x32_bf16 v[50:53], v[14:17], v[166:169], v[94:97]
	v_mfma_f32_16x16x32_bf16 v[58:61], v[18:21], v[170:173], v[50:53]
	v_mfma_f32_16x16x32_bf16 v[50:53], v[26:29], v[166:169], v[102:105]
	v_mfma_f32_16x16x32_bf16 v[50:53], v[226:229], v[170:173], v[50:53]
	s_setprio 0
	s_setprio 1
	v_mfma_f32_16x16x32_bf16 v[66:69], v[230:233], v[22:25], v[110:113]
	v_mfma_f32_16x16x32_bf16 v[22:25], v[238:241], v[22:25], v[34:37]
	v_mfma_f32_16x16x32_bf16 v[118:121], v[242:245], v[30:33], v[22:25]
	v_mfma_f32_16x16x32_bf16 v[22:25], v[230:233], v[62:65], v[38:41]
	v_mfma_f32_16x16x32_bf16 v[110:113], v[234:237], v[246:249], v[22:25]
	v_mfma_f32_16x16x32_bf16 v[22:25], v[238:241], v[62:65], v[42:45]
	v_mfma_f32_16x16x32_bf16 v[102:105], v[242:245], v[246:249], v[22:25]
	v_mfma_f32_16x16x32_bf16 v[22:25], v[230:233], v[250:253], v[46:49]
	v_mfma_f32_16x16x32_bf16 v[94:97], v[234:237], v[162:165], v[22:25]
	v_mfma_f32_16x16x32_bf16 v[22:25], v[238:241], v[250:253], v[54:57]
	v_mfma_f32_16x16x32_bf16 v[86:89], v[242:245], v[162:165], v[22:25]
	v_mfma_f32_16x16x32_bf16 v[22:25], v[230:233], v[166:169], v[142:145]
	v_mfma_f32_16x16x32_bf16 v[62:65], v[234:237], v[170:173], v[22:25]
	v_mfma_f32_16x16x32_bf16 v[22:25], v[238:241], v[166:169], v[146:149]
	v_mfma_f32_16x16x32_bf16 v[126:129], v[234:237], v[30:33], v[66:69]
	v_mfma_f32_16x16x32_bf16 v[54:57], v[242:245], v[170:173], v[22:25]
	s_setprio 0
	s_barrier
; #define PG8_STAGE(bufoff, gbase, voff) do { _Pragma("unroll") for (int _i = 0; _i < 2; ++_i) \
;         __builtin_amdgcn_global_load_lds((const unsigned*)((const char*)(gbase) + (voff)[_i]), (PG8_LAS unsigned*)(lds + (bufoff) + ldsw + _i * 8192), 16, 0, 0); } while (0)
; #define PG8_LDA(dst, b, h) do { _Pragma("unroll") for (int m = 0; m < 4; ++m) _Pragma("unroll") for (int k = 0; k < 2; ++k) dst[m][k] = *(const PG8_LAS bf16x8*)(lds + PG8_SA(b, h) + aoff + m * 2048 + k * 1024); } while (0)
; #define PG8_MMA(ai, bj, At, Bt) do { __builtin_amdgcn_s_setprio(1); _Pragma("unroll") for (int m = 0; m < 4; ++m) _Pragma("unroll") for (int n = 0; n < 2; ++n) _Pragma("unroll") for (int k = 0; k < 2; ++k) \
;         acc[ai][bj][m][n] = __builtin_amdgcn_mfma_f32_16x16x32_bf16(Bt[n][k], At[m][k], acc[ai][bj][m][n], 0, 0, 0); __builtin_amdgcn_s_setprio(0); } while (0)
; #define PG8_WAIT_V(n) asm volatile("s_waitcnt vmcnt(" #n ")" ::: "memory")
; #define PG8_WAIT_L(n) asm volatile("s_waitcnt lgkmcnt(" #n ")" ::: "memory")
; #define PG8_BAR __builtin_amdgcn_s_barrier()
; #define PG8_SCHED __builtin_amdgcn_sched_barrier(0)
; template <class Epi, class Sched, bool ALIGN_EPI = false, bool SP2 = false>
; __device__ __forceinline__ void gemm_phase(PG8_LAS unsigned char* lds, const Gemm g, const Sched& S, const Epi& E, int wave_s) {
;     ...
;             PG8_LDA(At, 1, 1); PG8_STAGE(PG8_SB(1, 0), b3, voffB); PG8_STAGE(PG8_SB(1, 1), b3 + hstep, voffB); PG8_STAGE(PG8_SA(1, 0), a3, voffA);
;             PG8_WAIT_V(8); PG8_WAIT_L(0); PG8_BAR; PG8_MMA(1, 0, At, B0); PG8_MMA(1, 1, At, B1); PG8_BAR; PG8_SCHED;
;     ...
;         if constexpr (ALIGN_EPI) { if (wr == 0) PG8_BAR; }
	s_add_i32 s11, s11, s35
	s_nop 2
	v_lshl_add_u64 v[22:23], v[136:137], 0, s[60:61]
	s_mov_b32 m0, s11
	ds_read_b128 v[34:37], v141 offset:49152
	ds_read_b128 v[42:45], v141 offset:50176
	ds_read_b128 v[142:145], v141 offset:51200
	ds_read_b128 v[146:149], v141 offset:52224
	ds_read_b128 v[162:165], v141 offset:53248
	ds_read_b128 v[166:169], v141 offset:54272
	ds_read_b128 v[170:173], v141 offset:55296
	ds_read_b128 v[246:249], v141 offset:56320
	global_load_lds_dwordx4 v[22:23], off
	s_add_i32 m0, s11, 0x2000
	s_add_u32 s20, s20, 0x8080
	v_lshl_add_u64 v[22:23], v[208:209], 0, s[60:61]
	s_addc_u32 s21, s21, 0
	s_add_i32 s11, s13, s35
	global_load_lds_dwordx4 v[22:23], off
	v_lshl_add_u64 v[22:23], s[20:21], 0, v[0:1]
	s_mov_b32 m0, s11
	s_nop 0
	global_load_lds_dwordx4 v[22:23], off
	v_lshl_add_u64 v[22:23], s[20:21], 0, v[130:131]
	s_add_i32 m0, s11, 0x2000
	s_nop 0
	global_load_lds_dwordx4 v[22:23], off
	v_lshl_add_u64 v[22:23], v[212:213], 0, s[60:61]
	s_mov_b32 m0, s47
	s_nop 0
	global_load_lds_dwordx4 v[22:23], off
	v_lshl_add_u64 v[22:23], v[174:175], 0, s[60:61]
	s_mov_b32 m0, s48
	s_nop 0
	global_load_lds_dwordx4 v[22:23], off
	s_waitcnt vmcnt(8)
	s_waitcnt lgkmcnt(0)
	s_barrier
	s_setprio 1
	v_mfma_f32_16x16x32_bf16 v[22:25], v[14:17], v[34:37], v[150:153]
	v_mfma_f32_16x16x32_bf16 v[78:81], v[18:21], v[42:45], v[22:25]
	v_mfma_f32_16x16x32_bf16 v[22:25], v[26:29], v[34:37], v[154:157]
	v_mfma_f32_16x16x32_bf16 v[70:73], v[226:229], v[42:45], v[22:25]
	v_mfma_f32_16x16x32_bf16 v[22:25], v[14:17], v[142:145], v[158:161]
	v_mfma_f32_16x16x32_bf16 v[46:49], v[18:21], v[146:149], v[22:25]
	v_mfma_f32_16x16x32_bf16 v[22:25], v[26:29], v[142:145], v[178:181]
	v_mfma_f32_16x16x32_bf16 v[38:41], v[226:229], v[146:149], v[22:25]
	v_mfma_f32_16x16x32_bf16 v[22:25], v[14:17], v[162:165], v[182:185]
	v_mfma_f32_16x16x32_bf16 v[2:5], v[14:17], v[170:173], v[2:5]
	v_mfma_f32_16x16x32_bf16 v[30:33], v[18:21], v[166:169], v[22:25]
	v_mfma_f32_16x16x32_bf16 v[22:25], v[26:29], v[162:165], v[186:189]
	v_mfma_f32_16x16x32_bf16 v[14:17], v[18:21], v[246:249], v[2:5]
	v_mfma_f32_16x16x32_bf16 v[2:5], v[26:29], v[170:173], v[6:9]
	v_mfma_f32_16x16x32_bf16 v[22:25], v[226:229], v[166:169], v[22:25]
	v_mfma_f32_16x16x32_bf16 v[6:9], v[226:229], v[246:249], v[2:5]
	s_setprio 0
	s_setprio 1
	v_mfma_f32_16x16x32_bf16 v[2:5], v[230:233], v[34:37], v[10:13]
	v_mfma_f32_16x16x32_bf16 v[74:77], v[234:237], v[42:45], v[2:5]
	v_mfma_f32_16x16x32_bf16 v[2:5], v[238:241], v[34:37], v[190:193]
	v_mfma_f32_16x16x32_bf16 v[66:69], v[242:245], v[42:45], v[2:5]
	v_mfma_f32_16x16x32_bf16 v[2:5], v[230:233], v[142:145], v[194:197]
	v_mfma_f32_16x16x32_bf16 v[42:45], v[234:237], v[146:149], v[2:5]
	v_mfma_f32_16x16x32_bf16 v[2:5], v[238:241], v[142:145], v[198:201]
	v_mfma_f32_16x16x32_bf16 v[34:37], v[242:245], v[146:149], v[2:5]
	v_mfma_f32_16x16x32_bf16 v[2:5], v[230:233], v[162:165], v[202:205]
	v_mfma_f32_16x16x32_bf16 v[26:29], v[234:237], v[166:169], v[2:5]
	v_mfma_f32_16x16x32_bf16 v[2:5], v[238:241], v[162:165], v[214:217]
	v_mfma_f32_16x16x32_bf16 v[18:21], v[242:245], v[166:169], v[2:5]
	v_mfma_f32_16x16x32_bf16 v[2:5], v[230:233], v[170:173], v[218:221]
	v_mfma_f32_16x16x32_bf16 v[10:13], v[234:237], v[246:249], v[2:5]
	v_mfma_f32_16x16x32_bf16 v[2:5], v[238:241], v[170:173], v[222:225]
	v_mfma_f32_16x16x32_bf16 v[2:5], v[242:245], v[246:249], v[2:5]
	s_setprio 0
	s_barrier
	s_andn2_b64 vcc, exec, s[6:7]
	s_cbranch_vccnz .LBB0_398
	s_barrier

; #define PG8_STAGE(bufoff, gbase, voff) do { _Pragma("unroll") for (int _i = 0; _i < 2; ++_i) \
;         __builtin_amdgcn_global_load_lds((const unsigned*)((const char*)(gbase) + (voff)[_i]), (PG8_LAS unsigned*)(lds + (bufoff) + ldsw + _i * 8192), 16, 0, 0); } while (0)
; #define PG8_LDA(dst, b, h) do { _Pragma("unroll") for (int m = 0; m < 4; ++m) _Pragma("unroll") for (int k = 0; k < 2; ++k) dst[m][k] = *(const PG8_LAS bf16x8*)(lds + PG8_SA(b, h) + aoff + m * 2048 + k * 1024); } while (0)
; #define PG8_LDB(dst, b, h) do { _Pragma("unroll") for (int n = 0; n < 2; ++n) _Pragma("unroll") for (int k = 0; k < 2; ++k) dst[n][k] = *(const PG8_LAS bf16x8*)(lds + PG8_SB(b, h) + boff + n * 2048 + k * 1024); } while (0)
; #define PG8_MMA(ai, bj, At, Bt) do { __builtin_amdgcn_s_setprio(1); _Pragma("unroll") for (int m = 0; m < 4; ++m) _Pragma("unroll") for (int n = 0; n < 2; ++n) _Pragma("unroll") for (int k = 0; k < 2; ++k) \
;         acc[ai][bj][m][n] = __builtin_amdgcn_mfma_f32_16x16x32_bf16(Bt[n][k], At[m][k], acc[ai][bj][m][n], 0, 0, 0); __builtin_amdgcn_s_setprio(0); } while (0)
; #define PG8_WAIT_V(n) asm volatile("s_waitcnt vmcnt(" #n ")" ::: "memory")
; #define PG8_WAIT_L(n) asm volatile("s_waitcnt lgkmcnt(" #n ")" ::: "memory")
; template <class Epi, class Sched, bool ALIGN_EPI = false, bool SP2 = false>
; __device__ __forceinline__ void gemm_phase(PG8_LAS unsigned char* lds, const Gemm g, const Sched& S, const Epi& E, int wave_s) {
;     ...
;             const bool last = (t == nt - 2);
;             const char* a1 = cA + (size_t)(t + 1) * kstep;
;             const char* a2 = last ? nA : cA + (size_t)(t + 2) * kstep; const char* b2 = last ? nB : cB + (size_t)(t + 2) * kstep;
;             const char* a3 = a2 + kstep; const char* b3 = b2 + kstep;
;             if (last && has_next) S.a_ready(nxt);
;             if constexpr (SP2) {
;             PG8_LDB(B0, 0, 0); PG8_LDB(B1, 0, 1); PG8_SCHED; PG8_LDA(At, 0, 0); PG8_STAGE(PG8_SA(1, 1), a1 + hstep, voffA);
;             PG8_WAIT_V(8); PG8_WAIT_L(0); PG8_BAR; PG8_MMA(0, 0, At, B0); PG8_MMA(0, 1, At, B1); PG8_BAR; PG8_SCHED;
;             PG8_LDA(At, 0, 1); PG8_STAGE(PG8_SB(0, 0), b2, voffB); PG8_STAGE(PG8_SB(0, 1), b2 + hstep, voffB); PG8_STAGE(PG8_SA(0, 0), a2, voffA);
;             PG8_WAIT_V(8); PG8_WAIT_L(0); PG8_BAR; PG8_MMA(1, 0, At, B0); PG8_MMA(1, 1, At, B1); PG8_BAR; PG8_SCHED;
.LBB0_690:
	s_add_u32 s20, s18, 0xfffc0080
	s_addc_u32 s21, s19, -1
	s_add_i32 s70, 0, 0x10000
	s_cmp_eq_u32 s63, 12
	s_cselect_b32 s23, s11, s21
	s_cselect_b32 s22, s56, s20
	v_add_u32_e32 v140, s70, v143
	s_cselect_b32 s21, s9, s62
	s_cselect_b32 s20, s57, s58
	s_add_i32 s74, 0, 0x14000
	ds_read_b128 v[146:149], v140
	ds_read_b128 v[150:153], v140 offset:1024
	ds_read_b128 v[154:157], v140 offset:2048
	ds_read_b128 v[158:161], v140 offset:3072
	v_add_u32_e32 v140, s74, v143
	ds_read_b128 v[162:165], v140
	ds_read_b128 v[166:169], v140 offset:1024
	ds_read_b128 v[170:173], v140 offset:2048
	ds_read_b128 v[178:181], v140 offset:3072
	v_lshl_add_u64 v[140:141], s[18:19], 0, v[136:137]
	s_add_i32 m0, s13, 0xc000
	ds_read_b128 v[182:185], v145
	ds_read_b128 v[186:189], v145 offset:1024
	ds_read_b128 v[190:193], v145 offset:2048
	ds_read_b128 v[194:197], v145 offset:3072
	ds_read_b128 v[198:201], v145 offset:4096
	ds_read_b128 v[202:205], v145 offset:5120
	ds_read_b128 v[214:217], v145 offset:6144
	ds_read_b128 v[218:221], v145 offset:7168
	global_load_lds_dwordx4 v[140:141], off
	v_lshl_add_u64 v[140:141], s[18:19], 0, v[138:139]
	s_add_i32 m0, s13, 0xe000
	s_nop 0
	global_load_lds_dwordx4 v[140:141], off
	s_waitcnt vmcnt(8)
	s_waitcnt lgkmcnt(0)
	s_barrier
	s_setprio 1
	v_mfma_f32_16x16x32_bf16 v[126:129], v[146:149], v[182:185], v[126:129]
	v_mfma_f32_16x16x32_bf16 v[122:125], v[154:157], v[182:185], v[122:125]
	v_mfma_f32_16x16x32_bf16 v[118:121], v[146:149], v[190:193], v[118:121]
	v_mfma_f32_16x16x32_bf16 v[110:113], v[154:157], v[190:193], v[110:113]
	v_mfma_f32_16x16x32_bf16 v[102:105], v[146:149], v[198:201], v[102:105]
	v_mfma_f32_16x16x32_bf16 v[94:97], v[154:157], v[198:201], v[94:97]
	v_mfma_f32_16x16x32_bf16 v[86:89], v[146:149], v[214:217], v[86:89]
	v_mfma_f32_16x16x32_bf16 v[78:81], v[154:157], v[214:217], v[78:81]
	v_mfma_f32_16x16x32_bf16 v[126:129], v[150:153], v[186:189], v[126:129]
	v_mfma_f32_16x16x32_bf16 v[122:125], v[158:161], v[186:189], v[122:125]
	v_mfma_f32_16x16x32_bf16 v[118:121], v[150:153], v[194:197], v[118:121]
	v_mfma_f32_16x16x32_bf16 v[110:113], v[158:161], v[194:197], v[110:113]
	v_mfma_f32_16x16x32_bf16 v[102:105], v[150:153], v[202:205], v[102:105]
	v_mfma_f32_16x16x32_bf16 v[94:97], v[158:161], v[202:205], v[94:97]
	v_mfma_f32_16x16x32_bf16 v[86:89], v[150:153], v[218:221], v[86:89]
	v_mfma_f32_16x16x32_bf16 v[78:81], v[158:161], v[218:221], v[78:81]
	s_setprio 0
	s_setprio 1
	v_mfma_f32_16x16x32_bf16 v[114:117], v[162:165], v[182:185], v[114:117]
	v_mfma_f32_16x16x32_bf16 v[106:109], v[170:173], v[182:185], v[106:109]
	v_mfma_f32_16x16x32_bf16 v[98:101], v[162:165], v[190:193], v[98:101]
	v_mfma_f32_16x16x32_bf16 v[90:93], v[170:173], v[190:193], v[90:93]
	v_mfma_f32_16x16x32_bf16 v[82:85], v[162:165], v[198:201], v[82:85]
	v_mfma_f32_16x16x32_bf16 v[74:77], v[170:173], v[198:201], v[74:77]
	v_mfma_f32_16x16x32_bf16 v[70:73], v[162:165], v[214:217], v[70:73]
	v_mfma_f32_16x16x32_bf16 v[66:69], v[170:173], v[214:217], v[66:69]
	v_mfma_f32_16x16x32_bf16 v[114:117], v[166:169], v[186:189], v[114:117]
	v_mfma_f32_16x16x32_bf16 v[106:109], v[178:181], v[186:189], v[106:109]
	v_mfma_f32_16x16x32_bf16 v[98:101], v[166:169], v[194:197], v[98:101]
	v_mfma_f32_16x16x32_bf16 v[90:93], v[178:181], v[194:197], v[90:93]
	v_mfma_f32_16x16x32_bf16 v[82:85], v[166:169], v[202:205], v[82:85]
	v_mfma_f32_16x16x32_bf16 v[74:77], v[178:181], v[202:205], v[74:77]
	v_mfma_f32_16x16x32_bf16 v[70:73], v[166:169], v[218:221], v[70:73]
	v_mfma_f32_16x16x32_bf16 v[66:69], v[178:181], v[218:221], v[66:69]
	s_setprio 0
	s_barrier
	s_add_i32 s70, s70, s35
	v_lshl_add_u64 v[140:141], s[20:21], 0, v[0:1]
	s_mov_b32 m0, s70
	ds_read_b128 v[182:185], v145 offset:16384
	ds_read_b128 v[186:189], v145 offset:17408
	ds_read_b128 v[190:193], v145 offset:18432
	ds_read_b128 v[194:197], v145 offset:19456
	ds_read_b128 v[198:201], v145 offset:20480
	ds_read_b128 v[202:205], v145 offset:21504
	ds_read_b128 v[214:217], v145 offset:22528
	ds_read_b128 v[218:221], v145 offset:23552
	global_load_lds_dwordx4 v[140:141], off
	s_add_i32 m0, s70, 0x2000
	s_add_u32 s72, s20, 0x40000
	v_lshl_add_u64 v[174:175], s[20:21], 0, v[134:135]
	s_addc_u32 s73, s21, 0
	s_add_i32 s70, s74, s35
	global_load_lds_dwordx4 v[174:175], off
	v_lshl_add_u64 v[208:209], s[72:73], 0, v[0:1]
	s_mov_b32 m0, s70
	v_lshl_add_u64 v[212:213], s[22:23], 0, v[132:133]
	global_load_lds_dwordx4 v[208:209], off
	v_lshl_add_u64 v[208:209], s[72:73], 0, v[134:135]
	s_add_i32 m0, s70, 0x2000
	s_nop 0
	global_load_lds_dwordx4 v[208:209], off
	v_lshl_add_u64 v[208:209], s[22:23], 0, v[130:131]
	s_mov_b32 m0, s13
	s_nop 0
	global_load_lds_dwordx4 v[208:209], off
	s_mov_b32 m0, s36
	s_nop 0
	global_load_lds_dwordx4 v[212:213], off
	s_waitcnt vmcnt(8)
	s_waitcnt lgkmcnt(0)
	s_barrier
; #define PG8_STAGE(bufoff, gbase, voff) do { _Pragma("unroll") for (int _i = 0; _i < 2; ++_i) \
;         __builtin_amdgcn_global_load_lds((const unsigned*)((const char*)(gbase) + (voff)[_i]), (PG8_LAS unsigned*)(lds + (bufoff) + ldsw + _i * 8192), 16, 0, 0); } while (0)
; #define PG8_LDA(dst, b, h) do { _Pragma("unroll") for (int m = 0; m < 4; ++m) _Pragma("unroll") for (int k = 0; k < 2; ++k) dst[m][k] = *(const PG8_LAS bf16x8*)(lds + PG8_SA(b, h) + aoff + m * 2048 + k * 1024); } while (0)
; #define PG8_LDB(dst, b, h) do { _Pragma("unroll") for (int n = 0; n < 2; ++n) _Pragma("unroll") for (int k = 0; k < 2; ++k) dst[n][k] = *(const PG8_LAS bf16x8*)(lds + PG8_SB(b, h) + boff + n * 2048 + k * 1024); } while (0)
; #define PG8_MMA(ai, bj, At, Bt) do { __builtin_amdgcn_s_setprio(1); _Pragma("unroll") for (int m = 0; m < 4; ++m) _Pragma("unroll") for (int n = 0; n < 2; ++n) _Pragma("unroll") for (int k = 0; k < 2; ++k) \
;         acc[ai][bj][m][n] = __builtin_amdgcn_mfma_f32_16x16x32_bf16(Bt[n][k], At[m][k], acc[ai][bj][m][n], 0, 0, 0); __builtin_amdgcn_s_setprio(0); } while (0)
; #define PG8_WAIT_V(n) asm volatile("s_waitcnt vmcnt(" #n ")" ::: "memory")
; #define PG8_WAIT_L(n) asm volatile("s_waitcnt lgkmcnt(" #n ")" ::: "memory")
; #define PG8_BAR __builtin_amdgcn_s_barrier()
; #define PG8_SCHED __builtin_amdgcn_sched_barrier(0)
; template <class Epi, class Sched, bool ALIGN_EPI = false, bool SP2 = false>
; __device__ __forceinline__ void gemm_phase(PG8_LAS unsigned char* lds, const Gemm g, const Sched& S, const Epi& E, int wave_s) {
;     ...
;             PG8_WAIT_V(8); PG8_WAIT_L(0); PG8_BAR; PG8_MMA(1, 0, At, B0); PG8_MMA(1, 1, At, B1); PG8_BAR; PG8_SCHED;
;             PG8_LDB(B0, 1, 0); PG8_LDB(B1, 1, 1); PG8_SCHED; PG8_LDA(At, 1, 0); PG8_STAGE(PG8_SA(0, 1), a2 + hstep, voffA);
;             PG8_WAIT_V(8); PG8_WAIT_L(0); PG8_BAR; PG8_MMA(0, 0, At, B0); PG8_MMA(0, 1, At, B1); PG8_BAR; PG8_SCHED;
	s_setprio 1
	v_mfma_f32_16x16x32_bf16 v[62:65], v[146:149], v[182:185], v[62:65]
	v_mfma_f32_16x16x32_bf16 v[58:61], v[154:157], v[182:185], v[58:61]
	v_mfma_f32_16x16x32_bf16 v[54:57], v[146:149], v[190:193], v[54:57]
	v_mfma_f32_16x16x32_bf16 v[46:49], v[154:157], v[190:193], v[46:49]
	v_mfma_f32_16x16x32_bf16 v[38:41], v[146:149], v[198:201], v[38:41]
	v_mfma_f32_16x16x32_bf16 v[30:33], v[154:157], v[198:201], v[30:33]
	v_mfma_f32_16x16x32_bf16 v[22:25], v[146:149], v[214:217], v[22:25]
	v_mfma_f32_16x16x32_bf16 v[14:17], v[154:157], v[214:217], v[14:17]
	v_mfma_f32_16x16x32_bf16 v[62:65], v[150:153], v[186:189], v[62:65]
	v_mfma_f32_16x16x32_bf16 v[58:61], v[158:161], v[186:189], v[58:61]
	v_mfma_f32_16x16x32_bf16 v[54:57], v[150:153], v[194:197], v[54:57]
	v_mfma_f32_16x16x32_bf16 v[46:49], v[158:161], v[194:197], v[46:49]
	v_mfma_f32_16x16x32_bf16 v[38:41], v[150:153], v[202:205], v[38:41]
	v_mfma_f32_16x16x32_bf16 v[30:33], v[158:161], v[202:205], v[30:33]
	v_mfma_f32_16x16x32_bf16 v[22:25], v[150:153], v[218:221], v[22:25]
	v_mfma_f32_16x16x32_bf16 v[14:17], v[158:161], v[218:221], v[14:17]
	s_setprio 0
	s_setprio 1
	v_mfma_f32_16x16x32_bf16 v[50:53], v[162:165], v[182:185], v[50:53]
	v_mfma_f32_16x16x32_bf16 v[42:45], v[170:173], v[182:185], v[42:45]
	v_mfma_f32_16x16x32_bf16 v[34:37], v[162:165], v[190:193], v[34:37]
	v_mfma_f32_16x16x32_bf16 v[26:29], v[170:173], v[190:193], v[26:29]
	v_mfma_f32_16x16x32_bf16 v[18:21], v[162:165], v[198:201], v[18:21]
	v_mfma_f32_16x16x32_bf16 v[10:13], v[170:173], v[198:201], v[10:13]
	v_mfma_f32_16x16x32_bf16 v[6:9], v[162:165], v[214:217], v[6:9]
	v_mfma_f32_16x16x32_bf16 v[2:5], v[170:173], v[214:217], v[2:5]
	v_mfma_f32_16x16x32_bf16 v[50:53], v[166:169], v[186:189], v[50:53]
	v_mfma_f32_16x16x32_bf16 v[42:45], v[178:181], v[186:189], v[42:45]
	v_mfma_f32_16x16x32_bf16 v[34:37], v[166:169], v[194:197], v[34:37]
	v_mfma_f32_16x16x32_bf16 v[26:29], v[178:181], v[194:197], v[26:29]
	v_mfma_f32_16x16x32_bf16 v[18:21], v[166:169], v[202:205], v[18:21]
	v_mfma_f32_16x16x32_bf16 v[10:13], v[178:181], v[202:205], v[10:13]
	v_mfma_f32_16x16x32_bf16 v[6:9], v[166:169], v[218:221], v[6:9]
	v_mfma_f32_16x16x32_bf16 v[2:5], v[178:181], v[218:221], v[2:5]
	s_setprio 0
	s_barrier
	s_add_i32 s70, 0, 0x18000
	s_add_i32 s72, 0, 0x1c000
	v_add_u32_e32 v158, s70, v143
	v_add_u32_e32 v178, s72, v143
	ds_read_b128 v[146:149], v158
	ds_read_b128 v[150:153], v158 offset:1024
	ds_read_b128 v[154:157], v158 offset:2048
	ds_read_b128 v[158:161], v158 offset:3072
	ds_read_b128 v[162:165], v178
	ds_read_b128 v[166:169], v178 offset:1024
	ds_read_b128 v[170:173], v178 offset:2048
	ds_read_b128 v[178:181], v178 offset:3072
	s_add_u32 s22, s22, 0x40000
	s_addc_u32 s23, s23, 0
	s_mov_b32 m0, s37
	v_lshl_add_u64 v[222:223], s[22:23], 0, v[130:131]
	ds_read_b128 v[182:185], v145 offset:32768
	ds_read_b128 v[186:189], v145 offset:33792
	ds_read_b128 v[190:193], v145 offset:34816
	ds_read_b128 v[194:197], v145 offset:35840
	ds_read_b128 v[198:201], v145 offset:36864
	ds_read_b128 v[202:205], v145 offset:37888
	ds_read_b128 v[214:217], v145 offset:38912
	ds_read_b128 v[218:221], v145 offset:39936
	global_load_lds_dwordx4 v[222:223], off
	v_lshl_add_u64 v[222:223], s[22:23], 0, v[132:133]
	s_mov_b32 m0, s46
	s_nop 0
	global_load_lds_dwordx4 v[222:223], off
	s_waitcnt vmcnt(8)
	s_waitcnt lgkmcnt(0)
	s_barrier
	s_setprio 1
	v_mfma_f32_16x16x32_bf16 v[126:129], v[146:149], v[182:185], v[126:129]
	v_mfma_f32_16x16x32_bf16 v[122:125], v[154:157], v[182:185], v[122:125]
	v_mfma_f32_16x16x32_bf16 v[118:121], v[146:149], v[190:193], v[118:121]
	v_mfma_f32_16x16x32_bf16 v[110:113], v[154:157], v[190:193], v[110:113]
	v_mfma_f32_16x16x32_bf16 v[102:105], v[146:149], v[198:201], v[102:105]
	v_mfma_f32_16x16x32_bf16 v[94:97], v[154:157], v[198:201], v[94:97]
	v_mfma_f32_16x16x32_bf16 v[86:89], v[146:149], v[214:217], v[86:89]
	v_mfma_f32_16x16x32_bf16 v[78:81], v[154:157], v[214:217], v[78:81]
	v_mfma_f32_16x16x32_bf16 v[126:129], v[150:153], v[186:189], v[126:129]
	v_mfma_f32_16x16x32_bf16 v[122:125], v[158:161], v[186:189], v[122:125]
	v_mfma_f32_16x16x32_bf16 v[118:121], v[150:153], v[194:197], v[118:121]
	v_mfma_f32_16x16x32_bf16 v[110:113], v[158:161], v[194:197], v[110:113]
	v_mfma_f32_16x16x32_bf16 v[102:105], v[150:153], v[202:205], v[102:105]
	v_mfma_f32_16x16x32_bf16 v[94:97], v[158:161], v[202:205], v[94:97]
	v_mfma_f32_16x16x32_bf16 v[86:89], v[150:153], v[218:221], v[86:89]
	v_mfma_f32_16x16x32_bf16 v[78:81], v[158:161], v[218:221], v[78:81]
	s_setprio 0
	s_setprio 1
	v_mfma_f32_16x16x32_bf16 v[114:117], v[162:165], v[182:185], v[114:117]
	v_mfma_f32_16x16x32_bf16 v[106:109], v[170:173], v[182:185], v[106:109]
	v_mfma_f32_16x16x32_bf16 v[98:101], v[162:165], v[190:193], v[98:101]
	v_mfma_f32_16x16x32_bf16 v[90:93], v[170:173], v[190:193], v[90:93]
	v_mfma_f32_16x16x32_bf16 v[82:85], v[162:165], v[198:201], v[82:85]
	v_mfma_f32_16x16x32_bf16 v[74:77], v[170:173], v[198:201], v[74:77]
	v_mfma_f32_16x16x32_bf16 v[70:73], v[162:165], v[214:217], v[70:73]
	v_mfma_f32_16x16x32_bf16 v[66:69], v[170:173], v[214:217], v[66:69]
	v_mfma_f32_16x16x32_bf16 v[114:117], v[166:169], v[186:189], v[114:117]
	v_mfma_f32_16x16x32_bf16 v[106:109], v[178:181], v[186:189], v[106:109]
	v_mfma_f32_16x16x32_bf16 v[98:101], v[166:169], v[194:197], v[98:101]
	v_mfma_f32_16x16x32_bf16 v[90:93], v[178:181], v[194:197], v[90:93]
	v_mfma_f32_16x16x32_bf16 v[82:85], v[166:169], v[202:205], v[82:85]
	v_mfma_f32_16x16x32_bf16 v[74:77], v[178:181], v[202:205], v[74:77]
	v_mfma_f32_16x16x32_bf16 v[70:73], v[166:169], v[218:221], v[70:73]
	v_mfma_f32_16x16x32_bf16 v[66:69], v[178:181], v[218:221], v[66:69]
	s_setprio 0
	s_barrier
; #define PG8_STAGE(bufoff, gbase, voff) do { _Pragma("unroll") for (int _i = 0; _i < 2; ++_i) \
;         __builtin_amdgcn_global_load_lds((const unsigned*)((const char*)(gbase) + (voff)[_i]), (PG8_LAS unsigned*)(lds + (bufoff) + ldsw + _i * 8192), 16, 0, 0); } while (0)
; #define PG8_LDA(dst, b, h) do { _Pragma("unroll") for (int m = 0; m < 4; ++m) _Pragma("unroll") for (int k = 0; k < 2; ++k) dst[m][k] = *(const PG8_LAS bf16x8*)(lds + PG8_SA(b, h) + aoff + m * 2048 + k * 1024); } while (0)
; #define PG8_MMA(ai, bj, At, Bt) do { __builtin_amdgcn_s_setprio(1); _Pragma("unroll") for (int m = 0; m < 4; ++m) _Pragma("unroll") for (int n = 0; n < 2; ++n) _Pragma("unroll") for (int k = 0; k < 2; ++k) \
;         acc[ai][bj][m][n] = __builtin_amdgcn_mfma_f32_16x16x32_bf16(Bt[n][k], At[m][k], acc[ai][bj][m][n], 0, 0, 0); __builtin_amdgcn_s_setprio(0); } while (0)
; #define PG8_WAIT_V(n) asm volatile("s_waitcnt vmcnt(" #n ")" ::: "memory")
; #define PG8_WAIT_L(n) asm volatile("s_waitcnt lgkmcnt(" #n ")" ::: "memory")
; #define PG8_BAR __builtin_amdgcn_s_barrier()
; #define PG8_SCHED __builtin_amdgcn_sched_barrier(0)
; template <class Epi, class Sched, bool ALIGN_EPI = false, bool SP2 = false>
; __device__ __forceinline__ void gemm_phase(PG8_LAS unsigned char* lds, const Gemm g, const Sched& S, const Epi& E, int wave_s) {
;     ...
;             PG8_LDA(At, 1, 1); PG8_STAGE(PG8_SB(1, 0), b3, voffB); PG8_STAGE(PG8_SB(1, 1), b3 + hstep, voffB); PG8_STAGE(PG8_SA(1, 0), a3, voffA);
;             PG8_WAIT_V(8); PG8_WAIT_L(0); PG8_BAR; PG8_MMA(1, 0, At, B0); PG8_MMA(1, 1, At, B1); PG8_BAR; PG8_SCHED;
;     ...
;         if constexpr (ALIGN_EPI) { if (wr == 0) PG8_BAR; }
	s_add_i32 s22, s70, s35
	v_lshl_add_u64 v[140:141], v[140:141], 0, s[60:61]
	s_mov_b32 m0, s22
	ds_read_b128 v[182:185], v145 offset:49152
	ds_read_b128 v[186:189], v145 offset:50176
	ds_read_b128 v[190:193], v145 offset:51200
	ds_read_b128 v[194:197], v145 offset:52224
	ds_read_b128 v[198:201], v145 offset:53248
	ds_read_b128 v[202:205], v145 offset:54272
	ds_read_b128 v[214:217], v145 offset:55296
	ds_read_b128 v[218:221], v145 offset:56320
	global_load_lds_dwordx4 v[140:141], off
	s_add_i32 m0, s22, 0x2000
	s_add_u32 s20, s20, 0x40080
	v_lshl_add_u64 v[140:141], v[174:175], 0, s[60:61]
	s_addc_u32 s21, s21, 0
	s_add_i32 s22, s72, s35
	global_load_lds_dwordx4 v[140:141], off
	v_lshl_add_u64 v[140:141], s[20:21], 0, v[0:1]
	s_mov_b32 m0, s22
	s_nop 0
	global_load_lds_dwordx4 v[140:141], off
	v_lshl_add_u64 v[140:141], s[20:21], 0, v[134:135]
	s_add_i32 m0, s22, 0x2000
	s_nop 0
	global_load_lds_dwordx4 v[140:141], off
	v_lshl_add_u64 v[140:141], v[208:209], 0, s[60:61]
	s_mov_b32 m0, s47
	s_nop 0
	global_load_lds_dwordx4 v[140:141], off
	v_lshl_add_u64 v[140:141], v[212:213], 0, s[60:61]
	s_mov_b32 m0, s48
	s_nop 0
	global_load_lds_dwordx4 v[140:141], off
	s_waitcnt vmcnt(8)
	s_waitcnt lgkmcnt(0)
	s_barrier
	s_setprio 1
	v_mfma_f32_16x16x32_bf16 v[62:65], v[146:149], v[182:185], v[62:65]
	v_mfma_f32_16x16x32_bf16 v[58:61], v[154:157], v[182:185], v[58:61]
	v_mfma_f32_16x16x32_bf16 v[54:57], v[146:149], v[190:193], v[54:57]
	v_mfma_f32_16x16x32_bf16 v[46:49], v[154:157], v[190:193], v[46:49]
	v_mfma_f32_16x16x32_bf16 v[38:41], v[146:149], v[198:201], v[38:41]
	v_mfma_f32_16x16x32_bf16 v[30:33], v[154:157], v[198:201], v[30:33]
	v_mfma_f32_16x16x32_bf16 v[22:25], v[146:149], v[214:217], v[22:25]
	v_mfma_f32_16x16x32_bf16 v[14:17], v[154:157], v[214:217], v[14:17]
	v_mfma_f32_16x16x32_bf16 v[62:65], v[150:153], v[186:189], v[62:65]
	v_mfma_f32_16x16x32_bf16 v[58:61], v[158:161], v[186:189], v[58:61]
	v_mfma_f32_16x16x32_bf16 v[54:57], v[150:153], v[194:197], v[54:57]
	v_mfma_f32_16x16x32_bf16 v[46:49], v[158:161], v[194:197], v[46:49]
	v_mfma_f32_16x16x32_bf16 v[38:41], v[150:153], v[202:205], v[38:41]
	v_mfma_f32_16x16x32_bf16 v[30:33], v[158:161], v[202:205], v[30:33]
	v_mfma_f32_16x16x32_bf16 v[22:25], v[150:153], v[218:221], v[22:25]
	v_mfma_f32_16x16x32_bf16 v[14:17], v[158:161], v[218:221], v[14:17]
	s_setprio 0
	s_setprio 1
	v_mfma_f32_16x16x32_bf16 v[50:53], v[162:165], v[182:185], v[50:53]
	v_mfma_f32_16x16x32_bf16 v[42:45], v[170:173], v[182:185], v[42:45]
	v_mfma_f32_16x16x32_bf16 v[34:37], v[162:165], v[190:193], v[34:37]
	v_mfma_f32_16x16x32_bf16 v[26:29], v[170:173], v[190:193], v[26:29]
	v_mfma_f32_16x16x32_bf16 v[18:21], v[162:165], v[198:201], v[18:21]
	v_mfma_f32_16x16x32_bf16 v[10:13], v[170:173], v[198:201], v[10:13]
	v_mfma_f32_16x16x32_bf16 v[6:9], v[162:165], v[214:217], v[6:9]
	v_mfma_f32_16x16x32_bf16 v[2:5], v[170:173], v[214:217], v[2:5]
	v_mfma_f32_16x16x32_bf16 v[50:53], v[166:169], v[186:189], v[50:53]
	v_mfma_f32_16x16x32_bf16 v[42:45], v[178:181], v[186:189], v[42:45]
	v_mfma_f32_16x16x32_bf16 v[34:37], v[166:169], v[194:197], v[34:37]
	v_mfma_f32_16x16x32_bf16 v[26:29], v[178:181], v[194:197], v[26:29]
	v_mfma_f32_16x16x32_bf16 v[18:21], v[166:169], v[202:205], v[18:21]
	v_mfma_f32_16x16x32_bf16 v[10:13], v[178:181], v[202:205], v[10:13]
	v_mfma_f32_16x16x32_bf16 v[6:9], v[166:169], v[218:221], v[6:9]
	v_mfma_f32_16x16x32_bf16 v[2:5], v[178:181], v[218:221], v[2:5]
	s_setprio 0
	s_barrier
	s_add_i32 s63, s63, 2
	s_add_u32 s18, s18, 0x100
	s_addc_u32 s19, s19, 0
	s_add_u32 s58, s58, 0x100
	s_addc_u32 s62, s62, 0
	s_cmp_gt_u32 s63, 13
	s_cbranch_scc0 .LBB0_690
	s_and_b64 vcc, exec, s[6:7]
	s_cbranch_vccz .LBB0_693
	s_barrier

; #define PG8_STAGE(bufoff, gbase, voff) do { _Pragma("unroll") for (int _i = 0; _i < 2; ++_i) \
;         __builtin_amdgcn_global_load_lds((const unsigned*)((const char*)(gbase) + (voff)[_i]), (PG8_LAS unsigned*)(lds + (bufoff) + ldsw + _i * 8192), 16, 0, 0); } while (0)
; #define PG8_LDA(dst, b, h) do { _Pragma("unroll") for (int m = 0; m < 4; ++m) _Pragma("unroll") for (int k = 0; k < 2; ++k) dst[m][k] = *(const PG8_LAS bf16x8*)(lds + PG8_SA(b, h) + aoff + m * 2048 + k * 1024); } while (0)
; #define PG8_LDB(dst, b, h) do { _Pragma("unroll") for (int n = 0; n < 2; ++n) _Pragma("unroll") for (int k = 0; k < 2; ++k) dst[n][k] = *(const PG8_LAS bf16x8*)(lds + PG8_SB(b, h) + boff + n * 2048 + k * 1024); } while (0)
; #define PG8_MMA(ai, bj, At, Bt) do { __builtin_amdgcn_s_setprio(1); _Pragma("unroll") for (int m = 0; m < 4; ++m) _Pragma("unroll") for (int n = 0; n < 2; ++n) _Pragma("unroll") for (int k = 0; k < 2; ++k) \
;         acc[ai][bj][m][n] = __builtin_amdgcn_mfma_f32_16x16x32_bf16(Bt[n][k], At[m][k], acc[ai][bj][m][n], 0, 0, 0); __builtin_amdgcn_s_setprio(0); } while (0)
; #define PG8_WAIT_V(n) asm volatile("s_waitcnt vmcnt(" #n ")" ::: "memory")
; #define PG8_WAIT_L(n) asm volatile("s_waitcnt lgkmcnt(" #n ")" ::: "memory")
; #define PG8_BAR __builtin_amdgcn_s_barrier()
; #define PG8_SCHED __builtin_amdgcn_sched_barrier(0)
; template <class Epi, class Sched, bool ALIGN_EPI = false, bool SP2 = false>
; __device__ __forceinline__ void gemm_phase(PG8_LAS unsigned char* lds, const Gemm g, const Sched& S, const Epi& E, int wave_s) {
;     ...
;             PG8_LDB(B0, 0, 0); PG8_LDB(B1, 0, 1); PG8_SCHED; PG8_LDA(At, 0, 0); PG8_STAGE(PG8_SA(1, 1), a1 + hstep, voffA);
;             PG8_WAIT_V(8); PG8_WAIT_L(0); PG8_BAR; PG8_MMA(0, 0, At, B0); PG8_MMA(0, 1, At, B1); PG8_BAR; PG8_SCHED;
;             PG8_LDA(At, 0, 1); PG8_STAGE(PG8_SB(0, 0), b2, voffB); PG8_STAGE(PG8_SB(0, 1), b2 + hstep, voffB); PG8_STAGE(PG8_SA(0, 0), a2, voffA);
;             PG8_WAIT_V(8); PG8_WAIT_L(0); PG8_BAR; PG8_MMA(1, 0, At, B0); PG8_MMA(1, 1, At, B1); PG8_BAR; PG8_SCHED;
.LBB0_710:
	s_add_i32 s57, 0, 0x10000
	s_add_i32 s17, 0, 0x14000
	v_add_u32_e32 v220, s57, v136
	v_add_u32_e32 v221, s17, v136
	ds_read_b128 v[2:5], v220
	ds_read_b128 v[6:9], v220 offset:1024
	ds_read_b128 v[10:13], v220 offset:2048
	ds_read_b128 v[14:17], v220 offset:3072
	ds_read_b128 v[18:21], v221
	ds_read_b128 v[22:25], v221 offset:1024
	ds_read_b128 v[26:29], v221 offset:2048
	ds_read_b128 v[30:33], v221 offset:3072
	s_add_u32 s72, s24, 0x40080
	s_addc_u32 s73, s25, 0
	s_add_i32 s62, s9, 0xc000
	v_lshl_add_u64 v[66:67], s[72:73], 0, v[134:135]
	s_mov_b32 m0, s62
	s_add_i32 s7, s9, 0xe000
	ds_read_b128 v[34:37], v139
	ds_read_b128 v[38:41], v139 offset:1024
	ds_read_b128 v[42:45], v139 offset:2048
	ds_read_b128 v[46:49], v139 offset:3072
	ds_read_b128 v[50:53], v139 offset:4096
	ds_read_b128 v[54:57], v139 offset:5120
	ds_read_b128 v[58:61], v139 offset:6144
	ds_read_b128 v[62:65], v139 offset:7168
	global_load_lds_dwordx4 v[66:67], off
	v_lshl_add_u64 v[66:67], s[72:73], 0, v[132:133]
	s_mov_b32 m0, s7
	s_nop 0
	global_load_lds_dwordx4 v[66:67], off
	s_waitcnt vmcnt(8)
	s_waitcnt lgkmcnt(0)
	s_barrier
	s_setprio 1
	v_mfma_f32_16x16x32_bf16 v[66:69], v[2:5], v[34:37], 0
	v_mfma_f32_16x16x32_bf16 v[70:73], v[10:13], v[34:37], 0
	v_mfma_f32_16x16x32_bf16 v[74:77], v[2:5], v[42:45], 0
	v_mfma_f32_16x16x32_bf16 v[78:81], v[10:13], v[42:45], 0
	v_mfma_f32_16x16x32_bf16 v[82:85], v[2:5], v[50:53], 0
	v_mfma_f32_16x16x32_bf16 v[86:89], v[10:13], v[50:53], 0
	v_mfma_f32_16x16x32_bf16 v[90:93], v[2:5], v[58:61], 0
	v_mfma_f32_16x16x32_bf16 v[94:97], v[10:13], v[58:61], 0
	v_mfma_f32_16x16x32_bf16 v[66:69], v[6:9], v[38:41], v[66:69]
	v_mfma_f32_16x16x32_bf16 v[70:73], v[14:17], v[38:41], v[70:73]
	v_mfma_f32_16x16x32_bf16 v[74:77], v[6:9], v[46:49], v[74:77]
	v_mfma_f32_16x16x32_bf16 v[78:81], v[14:17], v[46:49], v[78:81]
	v_mfma_f32_16x16x32_bf16 v[82:85], v[6:9], v[54:57], v[82:85]
	v_mfma_f32_16x16x32_bf16 v[86:89], v[14:17], v[54:57], v[86:89]
	v_mfma_f32_16x16x32_bf16 v[90:93], v[6:9], v[62:65], v[90:93]
	v_mfma_f32_16x16x32_bf16 v[94:97], v[14:17], v[62:65], v[94:97]
	s_setprio 0
	s_setprio 1
	v_mfma_f32_16x16x32_bf16 v[98:101], v[18:21], v[34:37], 0
	v_mfma_f32_16x16x32_bf16 v[34:37], v[26:29], v[34:37], 0
	v_mfma_f32_16x16x32_bf16 v[98:101], v[22:25], v[38:41], v[98:101]
	v_mfma_f32_16x16x32_bf16 v[34:37], v[30:33], v[38:41], v[34:37]
	v_mfma_f32_16x16x32_bf16 v[38:41], v[18:21], v[42:45], 0
	v_mfma_f32_16x16x32_bf16 v[42:45], v[26:29], v[42:45], 0
	v_mfma_f32_16x16x32_bf16 v[38:41], v[22:25], v[46:49], v[38:41]
	v_mfma_f32_16x16x32_bf16 v[42:45], v[30:33], v[46:49], v[42:45]
	v_mfma_f32_16x16x32_bf16 v[46:49], v[18:21], v[50:53], 0
	v_mfma_f32_16x16x32_bf16 v[50:53], v[26:29], v[50:53], 0
	v_mfma_f32_16x16x32_bf16 v[46:49], v[22:25], v[54:57], v[46:49]
	v_mfma_f32_16x16x32_bf16 v[50:53], v[30:33], v[54:57], v[50:53]
	v_mfma_f32_16x16x32_bf16 v[54:57], v[18:21], v[58:61], 0
	v_mfma_f32_16x16x32_bf16 v[58:61], v[26:29], v[58:61], 0
	v_mfma_f32_16x16x32_bf16 v[54:57], v[22:25], v[62:65], v[54:57]
	v_mfma_f32_16x16x32_bf16 v[58:61], v[30:33], v[62:65], v[58:61]
	s_setprio 0
	s_barrier
	s_add_i32 s57, s57, s37
	v_lshl_add_u64 v[172:173], s[26:27], 0, v[0:1]
	s_mov_b64 s[74:75], 0x100
	s_add_i32 s15, s57, 0x2000
	v_lshl_add_u64 v[140:141], v[172:173], 0, s[74:75]
	s_mov_b32 m0, s57
	v_lshl_add_u64 v[174:175], s[26:27], 0, v[130:131]
	s_add_u32 s72, s26, 0x40100
	ds_read_b128 v[62:65], v139 offset:16384
	ds_read_b128 v[102:105], v139 offset:17408
	ds_read_b128 v[106:109], v139 offset:18432
	ds_read_b128 v[110:113], v139 offset:19456
	ds_read_b128 v[114:117], v139 offset:20480
	ds_read_b128 v[118:121], v139 offset:21504
	ds_read_b128 v[122:125], v139 offset:22528
	ds_read_b128 v[126:129], v139 offset:23552
	global_load_lds_dwordx4 v[140:141], off
	v_lshl_add_u64 v[140:141], v[174:175], 0, s[74:75]
	s_mov_b32 m0, s15
	s_addc_u32 s73, s27, 0
	s_add_i32 s17, s17, s37
	global_load_lds_dwordx4 v[140:141], off
	v_lshl_add_u64 v[140:141], s[72:73], 0, v[0:1]
	s_mov_b32 m0, s17
	s_add_i32 s19, s17, 0x2000
	global_load_lds_dwordx4 v[140:141], off
	v_lshl_add_u64 v[140:141], s[72:73], 0, v[130:131]
	s_mov_b32 m0, s19
	v_lshl_add_u64 v[208:209], s[24:25], 0, v[134:135]
	global_load_lds_dwordx4 v[140:141], off
	v_lshl_add_u64 v[140:141], v[208:209], 0, s[74:75]
	s_mov_b32 m0, s9
	v_lshl_add_u64 v[212:213], s[24:25], 0, v[132:133]
	global_load_lds_dwordx4 v[140:141], off
	v_lshl_add_u64 v[140:141], v[212:213], 0, s[74:75]
	s_mov_b32 m0, s11
	s_nop 0
	global_load_lds_dwordx4 v[140:141], off
	s_waitcnt vmcnt(8)
	s_waitcnt lgkmcnt(0)
	s_barrier
; #define PG8_STAGE(bufoff, gbase, voff) do { _Pragma("unroll") for (int _i = 0; _i < 2; ++_i) \
;         __builtin_amdgcn_global_load_lds((const unsigned*)((const char*)(gbase) + (voff)[_i]), (PG8_LAS unsigned*)(lds + (bufoff) + ldsw + _i * 8192), 16, 0, 0); } while (0)
; #define PG8_LDA(dst, b, h) do { _Pragma("unroll") for (int m = 0; m < 4; ++m) _Pragma("unroll") for (int k = 0; k < 2; ++k) dst[m][k] = *(const PG8_LAS bf16x8*)(lds + PG8_SA(b, h) + aoff + m * 2048 + k * 1024); } while (0)
; #define PG8_LDB(dst, b, h) do { _Pragma("unroll") for (int n = 0; n < 2; ++n) _Pragma("unroll") for (int k = 0; k < 2; ++k) dst[n][k] = *(const PG8_LAS bf16x8*)(lds + PG8_SB(b, h) + boff + n * 2048 + k * 1024); } while (0)
; #define PG8_MMA(ai, bj, At, Bt) do { __builtin_amdgcn_s_setprio(1); _Pragma("unroll") for (int m = 0; m < 4; ++m) _Pragma("unroll") for (int n = 0; n < 2; ++n) _Pragma("unroll") for (int k = 0; k < 2; ++k) \
;         acc[ai][bj][m][n] = __builtin_amdgcn_mfma_f32_16x16x32_bf16(Bt[n][k], At[m][k], acc[ai][bj][m][n], 0, 0, 0); __builtin_amdgcn_s_setprio(0); } while (0)
; #define PG8_WAIT_V(n) asm volatile("s_waitcnt vmcnt(" #n ")" ::: "memory")
; #define PG8_WAIT_L(n) asm volatile("s_waitcnt lgkmcnt(" #n ")" ::: "memory")
; #define PG8_BAR __builtin_amdgcn_s_barrier()
; #define PG8_SCHED __builtin_amdgcn_sched_barrier(0)
; template <class Epi, class Sched, bool ALIGN_EPI = false, bool SP2 = false>
; __device__ __forceinline__ void gemm_phase(PG8_LAS unsigned char* lds, const Gemm g, const Sched& S, const Epi& E, int wave_s) {
;     ...
;             PG8_WAIT_V(8); PG8_WAIT_L(0); PG8_BAR; PG8_MMA(1, 0, At, B0); PG8_MMA(1, 1, At, B1); PG8_BAR; PG8_SCHED;
;             PG8_LDB(B0, 1, 0); PG8_LDB(B1, 1, 1); PG8_SCHED; PG8_LDA(At, 1, 0); PG8_STAGE(PG8_SA(0, 1), a2 + hstep, voffA);
;             PG8_WAIT_V(8); PG8_WAIT_L(0); PG8_BAR; PG8_MMA(0, 0, At, B0); PG8_MMA(0, 1, At, B1); PG8_BAR; PG8_SCHED;
	s_setprio 1
	v_mfma_f32_16x16x32_bf16 v[140:143], v[2:5], v[62:65], 0
	v_mfma_f32_16x16x32_bf16 v[148:151], v[2:5], v[106:109], 0
	v_mfma_f32_16x16x32_bf16 v[156:159], v[2:5], v[114:117], 0
	v_mfma_f32_16x16x32_bf16 v[2:5], v[2:5], v[122:125], 0
	v_mfma_f32_16x16x32_bf16 v[140:143], v[6:9], v[102:105], v[140:143]
	v_mfma_f32_16x16x32_bf16 v[148:151], v[6:9], v[110:113], v[148:151]
	v_mfma_f32_16x16x32_bf16 v[156:159], v[6:9], v[118:121], v[156:159]
	v_mfma_f32_16x16x32_bf16 v[2:5], v[6:9], v[126:129], v[2:5]
	v_mfma_f32_16x16x32_bf16 v[6:9], v[10:13], v[122:125], 0
	v_mfma_f32_16x16x32_bf16 v[144:147], v[10:13], v[62:65], 0
	v_mfma_f32_16x16x32_bf16 v[152:155], v[10:13], v[106:109], 0
	v_mfma_f32_16x16x32_bf16 v[160:163], v[10:13], v[114:117], 0
	v_mfma_f32_16x16x32_bf16 v[6:9], v[14:17], v[126:129], v[6:9]
	v_mfma_f32_16x16x32_bf16 v[144:147], v[14:17], v[102:105], v[144:147]
	v_mfma_f32_16x16x32_bf16 v[152:155], v[14:17], v[110:113], v[152:155]
	v_mfma_f32_16x16x32_bf16 v[160:163], v[14:17], v[118:121], v[160:163]
	s_setprio 0
	s_setprio 1
	v_mfma_f32_16x16x32_bf16 v[10:13], v[18:21], v[62:65], 0
	v_mfma_f32_16x16x32_bf16 v[14:17], v[26:29], v[62:65], 0
	v_mfma_f32_16x16x32_bf16 v[10:13], v[22:25], v[102:105], v[10:13]
	v_mfma_f32_16x16x32_bf16 v[14:17], v[30:33], v[102:105], v[14:17]
	v_mfma_f32_16x16x32_bf16 v[62:65], v[18:21], v[106:109], 0
	v_mfma_f32_16x16x32_bf16 v[102:105], v[26:29], v[106:109], 0
	v_mfma_f32_16x16x32_bf16 v[106:109], v[18:21], v[114:117], 0
	v_mfma_f32_16x16x32_bf16 v[18:21], v[18:21], v[122:125], 0
	v_mfma_f32_16x16x32_bf16 v[62:65], v[22:25], v[110:113], v[62:65]
	v_mfma_f32_16x16x32_bf16 v[102:105], v[30:33], v[110:113], v[102:105]
	v_mfma_f32_16x16x32_bf16 v[106:109], v[22:25], v[118:121], v[106:109]
	v_mfma_f32_16x16x32_bf16 v[110:113], v[26:29], v[114:117], 0
	v_mfma_f32_16x16x32_bf16 v[18:21], v[22:25], v[126:129], v[18:21]
	v_mfma_f32_16x16x32_bf16 v[22:25], v[26:29], v[122:125], 0
	v_mfma_f32_16x16x32_bf16 v[110:113], v[30:33], v[118:121], v[110:113]
	v_mfma_f32_16x16x32_bf16 v[22:25], v[30:33], v[126:129], v[22:25]
	s_setprio 0
	s_barrier
	s_add_i32 s63, 0, 0x18000
	s_add_i32 s70, 0, 0x1c000
	v_add_u32_e32 v230, s63, v136
	v_add_u32_e32 v234, s70, v136
	ds_read_b128 v[26:29], v230
	ds_read_b128 v[30:33], v230 offset:1024
	ds_read_b128 v[114:117], v230 offset:2048
	ds_read_b128 v[118:121], v230 offset:3072
	ds_read_b128 v[122:125], v234
	ds_read_b128 v[126:129], v234 offset:1024
	ds_read_b128 v[164:167], v234 offset:2048
	ds_read_b128 v[168:171], v234 offset:3072
	s_add_u32 s72, s24, 0x40100
	s_addc_u32 s73, s25, 0
	s_mov_b32 m0, s46
	v_lshl_add_u64 v[218:219], s[72:73], 0, v[134:135]
	ds_read_b128 v[178:181], v139 offset:32768
	ds_read_b128 v[182:185], v139 offset:33792
	ds_read_b128 v[186:189], v139 offset:34816
	ds_read_b128 v[190:193], v139 offset:35840
	ds_read_b128 v[194:197], v139 offset:36864
	ds_read_b128 v[198:201], v139 offset:37888
	ds_read_b128 v[202:205], v139 offset:38912
	ds_read_b128 v[214:217], v139 offset:39936
	global_load_lds_dwordx4 v[218:219], off
	v_lshl_add_u64 v[218:219], s[72:73], 0, v[132:133]
	s_mov_b32 m0, s47
	s_nop 0
	global_load_lds_dwordx4 v[218:219], off
	s_waitcnt vmcnt(8)
	s_waitcnt lgkmcnt(0)
	s_barrier
	s_setprio 1
	v_mfma_f32_16x16x32_bf16 v[66:69], v[26:29], v[178:181], v[66:69]
	v_mfma_f32_16x16x32_bf16 v[70:73], v[114:117], v[178:181], v[70:73]
	v_mfma_f32_16x16x32_bf16 v[74:77], v[26:29], v[186:189], v[74:77]
	v_mfma_f32_16x16x32_bf16 v[78:81], v[114:117], v[186:189], v[78:81]
	v_mfma_f32_16x16x32_bf16 v[82:85], v[26:29], v[194:197], v[82:85]
	v_mfma_f32_16x16x32_bf16 v[86:89], v[114:117], v[194:197], v[86:89]
	v_mfma_f32_16x16x32_bf16 v[90:93], v[26:29], v[202:205], v[90:93]
	v_mfma_f32_16x16x32_bf16 v[94:97], v[114:117], v[202:205], v[94:97]
	v_mfma_f32_16x16x32_bf16 v[66:69], v[30:33], v[182:185], v[66:69]
	v_mfma_f32_16x16x32_bf16 v[70:73], v[118:121], v[182:185], v[70:73]
	v_mfma_f32_16x16x32_bf16 v[74:77], v[30:33], v[190:193], v[74:77]
	v_mfma_f32_16x16x32_bf16 v[78:81], v[118:121], v[190:193], v[78:81]
	v_mfma_f32_16x16x32_bf16 v[82:85], v[30:33], v[198:201], v[82:85]
	v_mfma_f32_16x16x32_bf16 v[86:89], v[118:121], v[198:201], v[86:89]
	v_mfma_f32_16x16x32_bf16 v[90:93], v[30:33], v[214:217], v[90:93]
	v_mfma_f32_16x16x32_bf16 v[94:97], v[118:121], v[214:217], v[94:97]
	s_setprio 0
	s_setprio 1
	v_mfma_f32_16x16x32_bf16 v[98:101], v[122:125], v[178:181], v[98:101]
	v_mfma_f32_16x16x32_bf16 v[34:37], v[164:167], v[178:181], v[34:37]
	v_mfma_f32_16x16x32_bf16 v[38:41], v[122:125], v[186:189], v[38:41]
	v_mfma_f32_16x16x32_bf16 v[42:45], v[164:167], v[186:189], v[42:45]
	v_mfma_f32_16x16x32_bf16 v[46:49], v[122:125], v[194:197], v[46:49]
	v_mfma_f32_16x16x32_bf16 v[50:53], v[164:167], v[194:197], v[50:53]
	v_mfma_f32_16x16x32_bf16 v[54:57], v[122:125], v[202:205], v[54:57]
	v_mfma_f32_16x16x32_bf16 v[58:61], v[164:167], v[202:205], v[58:61]
	v_mfma_f32_16x16x32_bf16 v[98:101], v[126:129], v[182:185], v[98:101]
	v_mfma_f32_16x16x32_bf16 v[34:37], v[168:171], v[182:185], v[34:37]
	v_mfma_f32_16x16x32_bf16 v[38:41], v[126:129], v[190:193], v[38:41]
	v_mfma_f32_16x16x32_bf16 v[42:45], v[168:171], v[190:193], v[42:45]
	v_mfma_f32_16x16x32_bf16 v[46:49], v[126:129], v[198:201], v[46:49]
	v_mfma_f32_16x16x32_bf16 v[50:53], v[168:171], v[198:201], v[50:53]
	v_mfma_f32_16x16x32_bf16 v[54:57], v[126:129], v[214:217], v[54:57]
	v_mfma_f32_16x16x32_bf16 v[58:61], v[168:171], v[214:217], v[58:61]
	s_setprio 0
	s_barrier
; #define PG8_STAGE(bufoff, gbase, voff) do { _Pragma("unroll") for (int _i = 0; _i < 2; ++_i) \
;         __builtin_amdgcn_global_load_lds((const unsigned*)((const char*)(gbase) + (voff)[_i]), (PG8_LAS unsigned*)(lds + (bufoff) + ldsw + _i * 8192), 16, 0, 0); } while (0)
; #define PG8_LDA(dst, b, h) do { _Pragma("unroll") for (int m = 0; m < 4; ++m) _Pragma("unroll") for (int k = 0; k < 2; ++k) dst[m][k] = *(const PG8_LAS bf16x8*)(lds + PG8_SA(b, h) + aoff + m * 2048 + k * 1024); } while (0)
; #define PG8_LDB(dst, b, h) do { _Pragma("unroll") for (int n = 0; n < 2; ++n) _Pragma("unroll") for (int k = 0; k < 2; ++k) dst[n][k] = *(const PG8_LAS bf16x8*)(lds + PG8_SB(b, h) + boff + n * 2048 + k * 1024); } while (0)
; #define PG8_MMA(ai, bj, At, Bt) do { __builtin_amdgcn_s_setprio(1); _Pragma("unroll") for (int m = 0; m < 4; ++m) _Pragma("unroll") for (int n = 0; n < 2; ++n) _Pragma("unroll") for (int k = 0; k < 2; ++k) \
;         acc[ai][bj][m][n] = __builtin_amdgcn_mfma_f32_16x16x32_bf16(Bt[n][k], At[m][k], acc[ai][bj][m][n], 0, 0, 0); __builtin_amdgcn_s_setprio(0); } while (0)
; #define PG8_WAIT_V(n) asm volatile("s_waitcnt vmcnt(" #n ")" ::: "memory")
; #define PG8_WAIT_L(n) asm volatile("s_waitcnt lgkmcnt(" #n ")" ::: "memory")
; #define PG8_BAR __builtin_amdgcn_s_barrier()
; #define PG8_SCHED __builtin_amdgcn_sched_barrier(0)
; template <class Epi, class Sched, bool ALIGN_EPI = false, bool SP2 = false>
; __device__ __forceinline__ void gemm_phase(PG8_LAS unsigned char* lds, const Gemm g, const Sched& S, const Epi& E, int wave_s) {
;     ...
;             PG8_LDB(B0, 0, 0); PG8_LDB(B1, 0, 1); PG8_SCHED; PG8_LDA(At, 0, 0); PG8_STAGE(PG8_SA(1, 1), a1 + hstep, voffA);
;     ...
;             PG8_LDA(At, 1, 1); PG8_STAGE(PG8_SB(1, 0), b3, voffB); PG8_STAGE(PG8_SB(1, 1), b3 + hstep, voffB); PG8_STAGE(PG8_SA(1, 0), a3, voffA);
;             PG8_WAIT_V(8); PG8_WAIT_L(0); PG8_BAR; PG8_MMA(1, 0, At, B0); PG8_MMA(1, 1, At, B1); PG8_BAR; PG8_SCHED;
	s_add_i32 s63, s63, s37
	s_mov_b64 s[74:75], 0x180
	s_add_i32 s58, s63, 0x2000
	v_lshl_add_u64 v[172:173], v[172:173], 0, s[74:75]
	s_mov_b32 m0, s63
	s_add_u32 s72, s26, 0x40180
	ds_read_b128 v[178:181], v139 offset:49152
	ds_read_b128 v[182:185], v139 offset:50176
	ds_read_b128 v[186:189], v139 offset:51200
	ds_read_b128 v[190:193], v139 offset:52224
	ds_read_b128 v[194:197], v139 offset:53248
	ds_read_b128 v[198:201], v139 offset:54272
	ds_read_b128 v[202:205], v139 offset:55296
	ds_read_b128 v[214:217], v139 offset:56320
	global_load_lds_dwordx4 v[172:173], off
	v_lshl_add_u64 v[172:173], v[174:175], 0, s[74:75]
	s_mov_b32 m0, s58
	s_addc_u32 s73, s27, 0
	s_add_i32 s26, s70, s37
	global_load_lds_dwordx4 v[172:173], off
	v_lshl_add_u64 v[172:173], s[72:73], 0, v[0:1]
	s_mov_b32 m0, s26
	s_add_i32 s27, s26, 0x2000
	global_load_lds_dwordx4 v[172:173], off
	v_lshl_add_u64 v[172:173], s[72:73], 0, v[130:131]
	s_mov_b32 m0, s27
	s_nop 0
	global_load_lds_dwordx4 v[172:173], off
	v_lshl_add_u64 v[172:173], v[208:209], 0, s[74:75]
	s_mov_b32 m0, s50
	s_nop 0
	global_load_lds_dwordx4 v[172:173], off
	v_lshl_add_u64 v[172:173], v[212:213], 0, s[74:75]
	s_mov_b32 m0, s51
	s_nop 0
	global_load_lds_dwordx4 v[172:173], off
	s_waitcnt vmcnt(8)
	s_waitcnt lgkmcnt(0)
	s_barrier
	s_setprio 1
	v_mfma_f32_16x16x32_bf16 v[2:5], v[26:29], v[202:205], v[2:5]
	v_mfma_f32_16x16x32_bf16 v[6:9], v[114:117], v[202:205], v[6:9]
	v_mfma_f32_16x16x32_bf16 v[140:143], v[26:29], v[178:181], v[140:143]
	v_mfma_f32_16x16x32_bf16 v[144:147], v[114:117], v[178:181], v[144:147]
	v_mfma_f32_16x16x32_bf16 v[148:151], v[26:29], v[186:189], v[148:151]
	v_mfma_f32_16x16x32_bf16 v[152:155], v[114:117], v[186:189], v[152:155]
	v_mfma_f32_16x16x32_bf16 v[156:159], v[26:29], v[194:197], v[156:159]
	v_mfma_f32_16x16x32_bf16 v[160:163], v[114:117], v[194:197], v[160:163]
	v_mfma_f32_16x16x32_bf16 v[2:5], v[30:33], v[214:217], v[2:5]
	v_mfma_f32_16x16x32_bf16 v[6:9], v[118:121], v[214:217], v[6:9]
	v_mfma_f32_16x16x32_bf16 v[140:143], v[30:33], v[182:185], v[140:143]
	v_mfma_f32_16x16x32_bf16 v[144:147], v[118:121], v[182:185], v[144:147]
	v_mfma_f32_16x16x32_bf16 v[148:151], v[30:33], v[190:193], v[148:151]
	v_mfma_f32_16x16x32_bf16 v[152:155], v[118:121], v[190:193], v[152:155]
	v_mfma_f32_16x16x32_bf16 v[156:159], v[30:33], v[198:201], v[156:159]
	v_mfma_f32_16x16x32_bf16 v[160:163], v[118:121], v[198:201], v[160:163]
	s_setprio 0
	s_setprio 1
	v_mfma_f32_16x16x32_bf16 v[10:13], v[122:125], v[178:181], v[10:13]
	v_mfma_f32_16x16x32_bf16 v[14:17], v[164:167], v[178:181], v[14:17]
	v_mfma_f32_16x16x32_bf16 v[26:29], v[122:125], v[186:189], v[62:65]
	v_mfma_f32_16x16x32_bf16 v[30:33], v[164:167], v[186:189], v[102:105]
	v_mfma_f32_16x16x32_bf16 v[62:65], v[122:125], v[194:197], v[106:109]
	v_mfma_f32_16x16x32_bf16 v[102:105], v[164:167], v[194:197], v[110:113]
	v_mfma_f32_16x16x32_bf16 v[18:21], v[122:125], v[202:205], v[18:21]
	v_mfma_f32_16x16x32_bf16 v[22:25], v[164:167], v[202:205], v[22:25]
	v_mfma_f32_16x16x32_bf16 v[10:13], v[126:129], v[182:185], v[10:13]
	v_mfma_f32_16x16x32_bf16 v[14:17], v[168:171], v[182:185], v[14:17]
	v_mfma_f32_16x16x32_bf16 v[26:29], v[126:129], v[190:193], v[26:29]
	v_mfma_f32_16x16x32_bf16 v[30:33], v[168:171], v[190:193], v[30:33]
	v_mfma_f32_16x16x32_bf16 v[62:65], v[126:129], v[198:201], v[62:65]
	v_mfma_f32_16x16x32_bf16 v[102:105], v[168:171], v[198:201], v[102:105]
	v_mfma_f32_16x16x32_bf16 v[18:21], v[126:129], v[214:217], v[18:21]
	v_mfma_f32_16x16x32_bf16 v[22:25], v[168:171], v[214:217], v[22:25]
	s_setprio 0
	s_barrier
	ds_read_b128 v[106:109], v220
	ds_read_b128 v[110:113], v220 offset:1024
	ds_read_b128 v[114:117], v220 offset:2048
	ds_read_b128 v[118:121], v220 offset:3072
	ds_read_b128 v[122:125], v221
	ds_read_b128 v[126:129], v221 offset:1024
	ds_read_b128 v[164:167], v221 offset:2048
	ds_read_b128 v[168:171], v221 offset:3072
	s_add_u32 s24, s24, 0x40180
	s_addc_u32 s25, s25, 0
	s_mov_b32 m0, s62
	v_lshl_add_u64 v[172:173], s[24:25], 0, v[134:135]
	ds_read_b128 v[178:181], v139
	ds_read_b128 v[182:185], v139 offset:1024
	ds_read_b128 v[186:189], v139 offset:2048
	ds_read_b128 v[190:193], v139 offset:3072
	ds_read_b128 v[194:197], v139 offset:4096
	ds_read_b128 v[198:201], v139 offset:5120
	ds_read_b128 v[202:205], v139 offset:6144
	ds_read_b128 v[214:217], v139 offset:7168
	global_load_lds_dwordx4 v[172:173], off
	v_lshl_add_u64 v[172:173], s[24:25], 0, v[132:133]
	s_mov_b32 m0, s7
	s_nop 0
	global_load_lds_dwordx4 v[172:173], off
	s_waitcnt vmcnt(8)
	s_waitcnt lgkmcnt(0)
	s_barrier
; #define PG8_STAGE(bufoff, gbase, voff) do { _Pragma("unroll") for (int _i = 0; _i < 2; ++_i) \
;         __builtin_amdgcn_global_load_lds((const unsigned*)((const char*)(gbase) + (voff)[_i]), (PG8_LAS unsigned*)(lds + (bufoff) + ldsw + _i * 8192), 16, 0, 0); } while (0)
; #define PG8_LDA(dst, b, h) do { _Pragma("unroll") for (int m = 0; m < 4; ++m) _Pragma("unroll") for (int k = 0; k < 2; ++k) dst[m][k] = *(const PG8_LAS bf16x8*)(lds + PG8_SA(b, h) + aoff + m * 2048 + k * 1024); } while (0)
; #define PG8_MMA(ai, bj, At, Bt) do { __builtin_amdgcn_s_setprio(1); _Pragma("unroll") for (int m = 0; m < 4; ++m) _Pragma("unroll") for (int n = 0; n < 2; ++n) _Pragma("unroll") for (int k = 0; k < 2; ++k) \
;         acc[ai][bj][m][n] = __builtin_amdgcn_mfma_f32_16x16x32_bf16(Bt[n][k], At[m][k], acc[ai][bj][m][n], 0, 0, 0); __builtin_amdgcn_s_setprio(0); } while (0)
; #define PG8_WAIT_V(n) asm volatile("s_waitcnt vmcnt(" #n ")" ::: "memory")
; #define PG8_WAIT_L(n) asm volatile("s_waitcnt lgkmcnt(" #n ")" ::: "memory")
; #define PG8_BAR __builtin_amdgcn_s_barrier()
; #define PG8_SCHED __builtin_amdgcn_sched_barrier(0)
; template <class Epi, class Sched, bool ALIGN_EPI = false, bool SP2 = false>
; __device__ __forceinline__ void gemm_phase(PG8_LAS unsigned char* lds, const Gemm g, const Sched& S, const Epi& E, int wave_s) {
;     ...
;             PG8_WAIT_V(8); PG8_WAIT_L(0); PG8_BAR; PG8_MMA(0, 0, At, B0); PG8_MMA(0, 1, At, B1); PG8_BAR; PG8_SCHED;
;             PG8_LDA(At, 0, 1); PG8_STAGE(PG8_SB(0, 0), b2, voffB); PG8_STAGE(PG8_SB(0, 1), b2 + hstep, voffB); PG8_STAGE(PG8_SA(0, 0), a2, voffA);
;             PG8_WAIT_V(8); PG8_WAIT_L(0); PG8_BAR; PG8_MMA(1, 0, At, B0); PG8_MMA(1, 1, At, B1); PG8_BAR; PG8_SCHED;
	s_setprio 1
	v_mfma_f32_16x16x32_bf16 v[66:69], v[106:109], v[178:181], v[66:69]
	v_mfma_f32_16x16x32_bf16 v[70:73], v[114:117], v[178:181], v[70:73]
	v_mfma_f32_16x16x32_bf16 v[74:77], v[106:109], v[186:189], v[74:77]
	v_mfma_f32_16x16x32_bf16 v[78:81], v[114:117], v[186:189], v[78:81]
	v_mfma_f32_16x16x32_bf16 v[82:85], v[106:109], v[194:197], v[82:85]
	v_mfma_f32_16x16x32_bf16 v[86:89], v[114:117], v[194:197], v[86:89]
	v_mfma_f32_16x16x32_bf16 v[90:93], v[106:109], v[202:205], v[90:93]
	v_mfma_f32_16x16x32_bf16 v[94:97], v[114:117], v[202:205], v[94:97]
	v_mfma_f32_16x16x32_bf16 v[66:69], v[110:113], v[182:185], v[66:69]
	v_mfma_f32_16x16x32_bf16 v[70:73], v[118:121], v[182:185], v[70:73]
	v_mfma_f32_16x16x32_bf16 v[74:77], v[110:113], v[190:193], v[74:77]
	v_mfma_f32_16x16x32_bf16 v[78:81], v[118:121], v[190:193], v[78:81]
	v_mfma_f32_16x16x32_bf16 v[82:85], v[110:113], v[198:201], v[82:85]
	v_mfma_f32_16x16x32_bf16 v[86:89], v[118:121], v[198:201], v[86:89]
	v_mfma_f32_16x16x32_bf16 v[90:93], v[110:113], v[214:217], v[90:93]
	v_mfma_f32_16x16x32_bf16 v[94:97], v[118:121], v[214:217], v[94:97]
	s_setprio 0
	s_setprio 1
	v_mfma_f32_16x16x32_bf16 v[34:37], v[164:167], v[178:181], v[34:37]
	v_mfma_f32_16x16x32_bf16 v[98:101], v[122:125], v[178:181], v[98:101]
	v_mfma_f32_16x16x32_bf16 v[178:181], v[168:171], v[182:185], v[34:37]
	v_mfma_f32_16x16x32_bf16 v[34:37], v[122:125], v[186:189], v[38:41]
	v_mfma_f32_16x16x32_bf16 v[98:101], v[126:129], v[182:185], v[98:101]
	v_mfma_f32_16x16x32_bf16 v[182:185], v[126:129], v[190:193], v[34:37]
	v_mfma_f32_16x16x32_bf16 v[34:37], v[164:167], v[186:189], v[42:45]
	v_mfma_f32_16x16x32_bf16 v[42:45], v[168:171], v[190:193], v[34:37]
	v_mfma_f32_16x16x32_bf16 v[34:37], v[122:125], v[194:197], v[46:49]
	v_mfma_f32_16x16x32_bf16 v[46:49], v[126:129], v[198:201], v[34:37]
	v_mfma_f32_16x16x32_bf16 v[34:37], v[164:167], v[194:197], v[50:53]
	v_mfma_f32_16x16x32_bf16 v[50:53], v[168:171], v[198:201], v[34:37]
	v_mfma_f32_16x16x32_bf16 v[34:37], v[122:125], v[202:205], v[54:57]
	v_mfma_f32_16x16x32_bf16 v[54:57], v[126:129], v[214:217], v[34:37]
	v_mfma_f32_16x16x32_bf16 v[34:37], v[164:167], v[202:205], v[58:61]
	v_mfma_f32_16x16x32_bf16 v[186:189], v[168:171], v[214:217], v[34:37]
	s_setprio 0
	s_barrier
	s_mov_b32 m0, s57
	v_lshl_add_u64 v[172:173], s[22:23], 0, v[0:1]
	s_add_u32 s24, s22, 0x40000
	s_nop 1
	ds_read_b128 v[34:37], v139 offset:16384
	ds_read_b128 v[38:41], v139 offset:17408
	ds_read_b128 v[58:61], v139 offset:18432
	ds_read_b128 v[190:193], v139 offset:19456
	ds_read_b128 v[194:197], v139 offset:20480
	ds_read_b128 v[198:201], v139 offset:21504
	ds_read_b128 v[202:205], v139 offset:22528
	ds_read_b128 v[214:217], v139 offset:23552
	global_load_lds_dwordx4 v[172:173], off
	v_lshl_add_u64 v[174:175], s[22:23], 0, v[130:131]
	s_mov_b32 m0, s15
	s_addc_u32 s25, s23, 0
	global_load_lds_dwordx4 v[174:175], off
	v_lshl_add_u64 v[208:209], s[24:25], 0, v[0:1]
	s_mov_b32 m0, s17
	v_lshl_add_u64 v[212:213], s[20:21], 0, v[132:133]
	global_load_lds_dwordx4 v[208:209], off
	v_lshl_add_u64 v[208:209], s[24:25], 0, v[130:131]
	s_mov_b32 m0, s19
	s_nop 0
	global_load_lds_dwordx4 v[208:209], off
	v_lshl_add_u64 v[208:209], s[20:21], 0, v[134:135]
	s_mov_b32 m0, s9
	s_nop 0
	global_load_lds_dwordx4 v[208:209], off
	s_mov_b32 m0, s11
	s_nop 0
	global_load_lds_dwordx4 v[212:213], off
	s_waitcnt vmcnt(8)
	s_waitcnt lgkmcnt(0)
	s_barrier
	s_setprio 1
	v_mfma_f32_16x16x32_bf16 v[140:143], v[106:109], v[34:37], v[140:143]
	v_mfma_f32_16x16x32_bf16 v[148:151], v[106:109], v[58:61], v[148:151]
	v_mfma_f32_16x16x32_bf16 v[156:159], v[106:109], v[194:197], v[156:159]
	v_mfma_f32_16x16x32_bf16 v[2:5], v[106:109], v[202:205], v[2:5]
	v_mfma_f32_16x16x32_bf16 v[140:143], v[110:113], v[38:41], v[140:143]
	v_mfma_f32_16x16x32_bf16 v[148:151], v[110:113], v[190:193], v[148:151]
	v_mfma_f32_16x16x32_bf16 v[156:159], v[110:113], v[198:201], v[156:159]
	v_mfma_f32_16x16x32_bf16 v[110:113], v[110:113], v[214:217], v[2:5]
	v_mfma_f32_16x16x32_bf16 v[2:5], v[114:117], v[202:205], v[6:9]
	v_mfma_f32_16x16x32_bf16 v[144:147], v[114:117], v[34:37], v[144:147]
	v_mfma_f32_16x16x32_bf16 v[152:155], v[114:117], v[58:61], v[152:155]
	v_mfma_f32_16x16x32_bf16 v[160:163], v[114:117], v[194:197], v[160:163]
	v_mfma_f32_16x16x32_bf16 v[114:117], v[118:121], v[214:217], v[2:5]
	v_mfma_f32_16x16x32_bf16 v[144:147], v[118:121], v[38:41], v[144:147]
	v_mfma_f32_16x16x32_bf16 v[152:155], v[118:121], v[190:193], v[152:155]
	v_mfma_f32_16x16x32_bf16 v[160:163], v[118:121], v[198:201], v[160:163]
	s_setprio 0
	s_setprio 1
	v_mfma_f32_16x16x32_bf16 v[2:5], v[122:125], v[34:37], v[10:13]
	v_mfma_f32_16x16x32_bf16 v[118:121], v[126:129], v[38:41], v[2:5]
	v_mfma_f32_16x16x32_bf16 v[2:5], v[164:167], v[34:37], v[14:17]
	v_mfma_f32_16x16x32_bf16 v[218:221], v[168:171], v[38:41], v[2:5]
	v_mfma_f32_16x16x32_bf16 v[2:5], v[122:125], v[58:61], v[26:29]
	v_mfma_f32_16x16x32_bf16 v[222:225], v[126:129], v[190:193], v[2:5]
	v_mfma_f32_16x16x32_bf16 v[2:5], v[164:167], v[58:61], v[30:33]
	v_mfma_f32_16x16x32_bf16 v[190:193], v[168:171], v[190:193], v[2:5]
	v_mfma_f32_16x16x32_bf16 v[2:5], v[122:125], v[194:197], v[62:65]
	v_mfma_f32_16x16x32_bf16 v[226:229], v[126:129], v[198:201], v[2:5]
	v_mfma_f32_16x16x32_bf16 v[2:5], v[164:167], v[194:197], v[102:105]
	v_mfma_f32_16x16x32_bf16 v[194:197], v[168:171], v[198:201], v[2:5]
	v_mfma_f32_16x16x32_bf16 v[2:5], v[122:125], v[202:205], v[18:21]
	v_mfma_f32_16x16x32_bf16 v[198:201], v[126:129], v[214:217], v[2:5]
	v_mfma_f32_16x16x32_bf16 v[2:5], v[164:167], v[202:205], v[22:25]
	v_mfma_f32_16x16x32_bf16 v[164:167], v[168:171], v[214:217], v[2:5]
	s_setprio 0
	s_barrier
; #define PG8_STAGE(bufoff, gbase, voff) do { _Pragma("unroll") for (int _i = 0; _i < 2; ++_i) \
;         __builtin_amdgcn_global_load_lds((const unsigned*)((const char*)(gbase) + (voff)[_i]), (PG8_LAS unsigned*)(lds + (bufoff) + ldsw + _i * 8192), 16, 0, 0); } while (0)
; #define PG8_LDA(dst, b, h) do { _Pragma("unroll") for (int m = 0; m < 4; ++m) _Pragma("unroll") for (int k = 0; k < 2; ++k) dst[m][k] = *(const PG8_LAS bf16x8*)(lds + PG8_SA(b, h) + aoff + m * 2048 + k * 1024); } while (0)
; #define PG8_LDB(dst, b, h) do { _Pragma("unroll") for (int n = 0; n < 2; ++n) _Pragma("unroll") for (int k = 0; k < 2; ++k) dst[n][k] = *(const PG8_LAS bf16x8*)(lds + PG8_SB(b, h) + boff + n * 2048 + k * 1024); } while (0)
; #define PG8_MMA(ai, bj, At, Bt) do { __builtin_amdgcn_s_setprio(1); _Pragma("unroll") for (int m = 0; m < 4; ++m) _Pragma("unroll") for (int n = 0; n < 2; ++n) _Pragma("unroll") for (int k = 0; k < 2; ++k) \
;         acc[ai][bj][m][n] = __builtin_amdgcn_mfma_f32_16x16x32_bf16(Bt[n][k], At[m][k], acc[ai][bj][m][n], 0, 0, 0); __builtin_amdgcn_s_setprio(0); } while (0)
; #define PG8_WAIT_V(n) asm volatile("s_waitcnt vmcnt(" #n ")" ::: "memory")
; #define PG8_WAIT_L(n) asm volatile("s_waitcnt lgkmcnt(" #n ")" ::: "memory")
; #define PG8_BAR __builtin_amdgcn_s_barrier()
; #define PG8_SCHED __builtin_amdgcn_sched_barrier(0)
; template <class Epi, class Sched, bool ALIGN_EPI = false, bool SP2 = false>
; __device__ __forceinline__ void gemm_phase(PG8_LAS unsigned char* lds, const Gemm g, const Sched& S, const Epi& E, int wave_s) {
;     ...
;             PG8_LDB(B0, 1, 0); PG8_LDB(B1, 1, 1); PG8_SCHED; PG8_LDA(At, 1, 0); PG8_STAGE(PG8_SA(0, 1), a2 + hstep, voffA);
;             PG8_WAIT_V(8); PG8_WAIT_L(0); PG8_BAR; PG8_MMA(0, 0, At, B0); PG8_MMA(0, 1, At, B1); PG8_BAR; PG8_SCHED;
;             PG8_LDA(At, 1, 1); PG8_STAGE(PG8_SB(1, 0), b3, voffB); PG8_STAGE(PG8_SB(1, 1), b3 + hstep, voffB); PG8_STAGE(PG8_SA(1, 0), a3, voffA);
;             PG8_WAIT_V(8); PG8_WAIT_L(0); PG8_BAR; PG8_MMA(1, 0, At, B0); PG8_MMA(1, 1, At, B1); PG8_BAR; PG8_SCHED;
	ds_read_b128 v[102:105], v230
	ds_read_b128 v[122:125], v230 offset:1024
	ds_read_b128 v[126:129], v230 offset:2048
	ds_read_b128 v[168:171], v230 offset:3072
	ds_read_b128 v[202:205], v234
	ds_read_b128 v[214:217], v234 offset:1024
	ds_read_b128 v[230:233], v234 offset:2048
	ds_read_b128 v[234:237], v234 offset:3072
	s_add_u32 s24, s20, 0x40000
	s_addc_u32 s25, s21, 0
	s_mov_b32 m0, s46
	v_lshl_add_u64 v[2:3], s[24:25], 0, v[134:135]
	ds_read_b128 v[26:29], v139 offset:32768
	ds_read_b128 v[30:33], v139 offset:33792
	ds_read_b128 v[62:65], v139 offset:34816
	ds_read_b128 v[106:109], v139 offset:35840
	ds_read_b128 v[238:241], v139 offset:36864
	ds_read_b128 v[242:245], v139 offset:37888
	ds_read_b128 v[246:249], v139 offset:38912
	ds_read_b128 v[250:253], v139 offset:39936
	global_load_lds_dwordx4 v[2:3], off
	v_lshl_add_u64 v[2:3], s[24:25], 0, v[132:133]
	s_mov_b32 m0, s47
	s_nop 0
	global_load_lds_dwordx4 v[2:3], off
	s_waitcnt vmcnt(8)
	s_waitcnt lgkmcnt(0)
	s_barrier
	s_setprio 1
	v_mfma_f32_16x16x32_bf16 v[2:5], v[102:105], v[26:29], v[66:69]
	v_mfma_f32_16x16x32_bf16 v[34:37], v[122:125], v[30:33], v[2:5]
	v_mfma_f32_16x16x32_bf16 v[2:5], v[126:129], v[26:29], v[70:73]
	v_mfma_f32_16x16x32_bf16 v[38:41], v[168:171], v[30:33], v[2:5]
	v_mfma_f32_16x16x32_bf16 v[2:5], v[102:105], v[62:65], v[74:77]
	v_mfma_f32_16x16x32_bf16 v[18:21], v[122:125], v[106:109], v[2:5]
	v_mfma_f32_16x16x32_bf16 v[2:5], v[126:129], v[62:65], v[78:81]
	v_mfma_f32_16x16x32_bf16 v[22:25], v[168:171], v[106:109], v[2:5]
	v_mfma_f32_16x16x32_bf16 v[2:5], v[102:105], v[238:241], v[82:85]
	v_mfma_f32_16x16x32_bf16 v[10:13], v[122:125], v[242:245], v[2:5]
	v_mfma_f32_16x16x32_bf16 v[2:5], v[126:129], v[238:241], v[86:89]
	v_mfma_f32_16x16x32_bf16 v[14:17], v[168:171], v[242:245], v[2:5]
	v_mfma_f32_16x16x32_bf16 v[2:5], v[102:105], v[246:249], v[90:93]
	v_mfma_f32_16x16x32_bf16 v[6:9], v[126:129], v[246:249], v[94:97]
	v_mfma_f32_16x16x32_bf16 v[2:5], v[122:125], v[250:253], v[2:5]
	v_mfma_f32_16x16x32_bf16 v[6:9], v[168:171], v[250:253], v[6:9]
	s_setprio 0
	s_setprio 1
	v_mfma_f32_16x16x32_bf16 v[58:61], v[202:205], v[26:29], v[98:101]
	v_mfma_f32_16x16x32_bf16 v[26:29], v[230:233], v[26:29], v[178:181]
	v_mfma_f32_16x16x32_bf16 v[78:81], v[234:237], v[30:33], v[26:29]
	v_mfma_f32_16x16x32_bf16 v[26:29], v[202:205], v[62:65], v[182:185]
	v_mfma_f32_16x16x32_bf16 v[70:73], v[214:217], v[30:33], v[58:61]
	v_mfma_f32_16x16x32_bf16 v[58:61], v[214:217], v[106:109], v[26:29]
	v_mfma_f32_16x16x32_bf16 v[26:29], v[230:233], v[62:65], v[42:45]
	v_mfma_f32_16x16x32_bf16 v[62:65], v[234:237], v[106:109], v[26:29]
	v_mfma_f32_16x16x32_bf16 v[26:29], v[202:205], v[238:241], v[46:49]
	v_mfma_f32_16x16x32_bf16 v[42:45], v[214:217], v[242:245], v[26:29]
	v_mfma_f32_16x16x32_bf16 v[26:29], v[230:233], v[238:241], v[50:53]
	v_mfma_f32_16x16x32_bf16 v[46:49], v[234:237], v[242:245], v[26:29]
	v_mfma_f32_16x16x32_bf16 v[26:29], v[202:205], v[246:249], v[54:57]
	v_mfma_f32_16x16x32_bf16 v[30:33], v[230:233], v[246:249], v[186:189]
	v_mfma_f32_16x16x32_bf16 v[26:29], v[214:217], v[250:253], v[26:29]
	v_mfma_f32_16x16x32_bf16 v[30:33], v[234:237], v[250:253], v[30:33]
	s_setprio 0
	s_barrier
	s_mov_b32 m0, s63
	v_lshl_add_u64 v[50:51], v[172:173], 0, s[60:61]
	s_add_u32 s24, s22, 0x40080
	ds_read_b128 v[82:85], v139 offset:49152
	ds_read_b128 v[90:93], v139 offset:50176
	ds_read_b128 v[178:181], v139 offset:51200
	ds_read_b128 v[182:185], v139 offset:52224
	ds_read_b128 v[186:189], v139 offset:53248
	ds_read_b128 v[238:241], v139 offset:54272
	ds_read_b128 v[242:245], v139 offset:55296
	ds_read_b128 v[246:249], v139 offset:56320
	global_load_lds_dwordx4 v[50:51], off
	v_lshl_add_u64 v[50:51], v[174:175], 0, s[60:61]
	s_mov_b32 m0, s58
	s_addc_u32 s25, s23, 0
	global_load_lds_dwordx4 v[50:51], off
	v_lshl_add_u64 v[50:51], s[24:25], 0, v[0:1]
	s_mov_b32 m0, s26
	s_nop 0
	global_load_lds_dwordx4 v[50:51], off
	v_lshl_add_u64 v[50:51], s[24:25], 0, v[130:131]
	s_mov_b32 m0, s27
	s_nop 0
	global_load_lds_dwordx4 v[50:51], off
	v_lshl_add_u64 v[50:51], v[208:209], 0, s[60:61]
	s_mov_b32 m0, s50
	s_nop 0
	global_load_lds_dwordx4 v[50:51], off
	v_lshl_add_u64 v[50:51], v[212:213], 0, s[60:61]
	s_mov_b32 m0, s51
	s_nop 0
	global_load_lds_dwordx4 v[50:51], off
	s_waitcnt vmcnt(8)
	s_waitcnt lgkmcnt(0)
	s_barrier
	s_setprio 1
	v_mfma_f32_16x16x32_bf16 v[50:53], v[102:105], v[82:85], v[140:143]
	v_mfma_f32_16x16x32_bf16 v[98:101], v[122:125], v[90:93], v[50:53]
	v_mfma_f32_16x16x32_bf16 v[50:53], v[126:129], v[82:85], v[144:147]
	v_mfma_f32_16x16x32_bf16 v[106:109], v[168:171], v[90:93], v[50:53]
	v_mfma_f32_16x16x32_bf16 v[50:53], v[102:105], v[178:181], v[148:151]
	v_mfma_f32_16x16x32_bf16 v[86:89], v[122:125], v[182:185], v[50:53]
	v_mfma_f32_16x16x32_bf16 v[50:53], v[126:129], v[178:181], v[152:155]
	v_mfma_f32_16x16x32_bf16 v[94:97], v[168:171], v[182:185], v[50:53]
	v_mfma_f32_16x16x32_bf16 v[50:53], v[102:105], v[186:189], v[156:159]
	v_mfma_f32_16x16x32_bf16 v[66:69], v[122:125], v[238:241], v[50:53]
	v_mfma_f32_16x16x32_bf16 v[50:53], v[126:129], v[186:189], v[160:163]
	v_mfma_f32_16x16x32_bf16 v[74:77], v[168:171], v[238:241], v[50:53]
	v_mfma_f32_16x16x32_bf16 v[50:53], v[102:105], v[242:245], v[110:113]
	v_mfma_f32_16x16x32_bf16 v[54:57], v[126:129], v[242:245], v[114:117]
	v_mfma_f32_16x16x32_bf16 v[50:53], v[122:125], v[246:249], v[50:53]
	v_mfma_f32_16x16x32_bf16 v[54:57], v[168:171], v[246:249], v[54:57]
	s_setprio 0
	s_setprio 1
	v_mfma_f32_16x16x32_bf16 v[102:105], v[202:205], v[82:85], v[118:121]
	v_mfma_f32_16x16x32_bf16 v[82:85], v[230:233], v[82:85], v[218:221]
	v_mfma_f32_16x16x32_bf16 v[126:129], v[234:237], v[90:93], v[82:85]
	v_mfma_f32_16x16x32_bf16 v[82:85], v[202:205], v[178:181], v[222:225]
	v_mfma_f32_16x16x32_bf16 v[114:117], v[214:217], v[182:185], v[82:85]
	v_mfma_f32_16x16x32_bf16 v[82:85], v[230:233], v[178:181], v[190:193]
	v_mfma_f32_16x16x32_bf16 v[118:121], v[234:237], v[182:185], v[82:85]
	v_mfma_f32_16x16x32_bf16 v[82:85], v[202:205], v[186:189], v[226:229]
	v_mfma_f32_16x16x32_bf16 v[122:125], v[214:217], v[90:93], v[102:105]
	v_mfma_f32_16x16x32_bf16 v[102:105], v[214:217], v[238:241], v[82:85]
	v_mfma_f32_16x16x32_bf16 v[82:85], v[230:233], v[186:189], v[194:197]
	v_mfma_f32_16x16x32_bf16 v[110:113], v[234:237], v[238:241], v[82:85]
	v_mfma_f32_16x16x32_bf16 v[82:85], v[202:205], v[242:245], v[198:201]
	v_mfma_f32_16x16x32_bf16 v[90:93], v[230:233], v[242:245], v[164:167]
	v_mfma_f32_16x16x32_bf16 v[82:85], v[214:217], v[246:249], v[82:85]
	v_mfma_f32_16x16x32_bf16 v[90:93], v[234:237], v[246:249], v[90:93]
	s_setprio 0
	s_barrier
	s_andn2_b64 vcc, exec, s[12:13]
	s_cbranch_vccnz .LBB0_712
	s_barrier

; #define PG8_STAGE(bufoff, gbase, voff) do { _Pragma("unroll") for (int _i = 0; _i < 2; ++_i) \
;         __builtin_amdgcn_global_load_lds((const unsigned*)((const char*)(gbase) + (voff)[_i]), (PG8_LAS unsigned*)(lds + (bufoff) + ldsw + _i * 8192), 16, 0, 0); } while (0)
; #define PG8_LDA(dst, b, h) do { _Pragma("unroll") for (int m = 0; m < 4; ++m) _Pragma("unroll") for (int k = 0; k < 2; ++k) dst[m][k] = *(const PG8_LAS bf16x8*)(lds + PG8_SA(b, h) + aoff + m * 2048 + k * 1024); } while (0)
; #define PG8_LDB(dst, b, h) do { _Pragma("unroll") for (int n = 0; n < 2; ++n) _Pragma("unroll") for (int k = 0; k < 2; ++k) dst[n][k] = *(const PG8_LAS bf16x8*)(lds + PG8_SB(b, h) + boff + n * 2048 + k * 1024); } while (0)
; #define PG8_MMA(ai, bj, At, Bt) do { __builtin_amdgcn_s_setprio(1); _Pragma("unroll") for (int m = 0; m < 4; ++m) _Pragma("unroll") for (int n = 0; n < 2; ++n) _Pragma("unroll") for (int k = 0; k < 2; ++k) \
;         acc[ai][bj][m][n] = __builtin_amdgcn_mfma_f32_16x16x32_bf16(Bt[n][k], At[m][k], acc[ai][bj][m][n], 0, 0, 0); __builtin_amdgcn_s_setprio(0); } while (0)
; #define PG8_WAIT_V(n) asm volatile("s_waitcnt vmcnt(" #n ")" ::: "memory")
; #define PG8_WAIT_L(n) asm volatile("s_waitcnt lgkmcnt(" #n ")" ::: "memory")
; template <class Epi, class Sched, bool ALIGN_EPI = false, bool SP2 = false>
; __device__ __forceinline__ void gemm_phase(PG8_LAS unsigned char* lds, const Gemm g, const Sched& S, const Epi& E, int wave_s) {
;     ...
;             const bool last = (t == nt - 2);
;             const char* a1 = cA + (size_t)(t + 1) * kstep;
;             const char* a2 = last ? nA : cA + (size_t)(t + 2) * kstep; const char* b2 = last ? nB : cB + (size_t)(t + 2) * kstep;
;             const char* a3 = a2 + kstep; const char* b3 = b2 + kstep;
;             if (last && has_next) S.a_ready(nxt);
;             if constexpr (SP2) {
;             PG8_LDB(B0, 0, 0); PG8_LDB(B1, 0, 1); PG8_SCHED; PG8_LDA(At, 0, 0); PG8_STAGE(PG8_SA(1, 1), a1 + hstep, voffA);
;             PG8_WAIT_V(8); PG8_WAIT_L(0); PG8_BAR; PG8_MMA(0, 0, At, B0); PG8_MMA(0, 1, At, B1); PG8_BAR; PG8_SCHED;
;             PG8_LDA(At, 0, 1); PG8_STAGE(PG8_SB(0, 0), b2, voffB); PG8_STAGE(PG8_SB(0, 1), b2 + hstep, voffB); PG8_STAGE(PG8_SA(0, 0), a2, voffA);
;             PG8_WAIT_V(8); PG8_WAIT_L(0); PG8_BAR; PG8_MMA(1, 0, At, B0); PG8_MMA(1, 1, At, B1); PG8_BAR; PG8_SCHED;
.LBB0_1008:
	s_add_u32 s26, s24, 0xfffc0080
	s_addc_u32 s27, s25, -1
	s_add_i32 s79, 0, 0x10000
	s_cmp_eq_u32 s78, 12
	s_cselect_b32 s29, s13, s27
	s_cselect_b32 s28, s74, s26
	v_add_u32_e32 v140, s79, v143
	s_cselect_b32 s27, s11, s77
	s_cselect_b32 s26, s75, s76
	s_add_i32 s82, 0, 0x14000
	ds_read_b128 v[146:149], v140
	ds_read_b128 v[150:153], v140 offset:1024
	ds_read_b128 v[154:157], v140 offset:2048
	ds_read_b128 v[158:161], v140 offset:3072
	v_add_u32_e32 v140, s82, v143
	ds_read_b128 v[162:165], v140
	ds_read_b128 v[166:169], v140 offset:1024
	ds_read_b128 v[170:173], v140 offset:2048
	ds_read_b128 v[178:181], v140 offset:3072
	v_lshl_add_u64 v[140:141], s[24:25], 0, v[136:137]
	s_add_i32 m0, s21, 0xc000
	ds_read_b128 v[182:185], v145
	ds_read_b128 v[186:189], v145 offset:1024
	ds_read_b128 v[190:193], v145 offset:2048
	ds_read_b128 v[194:197], v145 offset:3072
	ds_read_b128 v[198:201], v145 offset:4096
	ds_read_b128 v[202:205], v145 offset:5120
	ds_read_b128 v[214:217], v145 offset:6144
	ds_read_b128 v[218:221], v145 offset:7168
	global_load_lds_dwordx4 v[140:141], off
	v_lshl_add_u64 v[140:141], s[24:25], 0, v[138:139]
	s_add_i32 m0, s21, 0xe000
	s_nop 0
	global_load_lds_dwordx4 v[140:141], off
	s_waitcnt vmcnt(8)
	s_waitcnt lgkmcnt(0)
	s_barrier
	s_setprio 1
	v_mfma_f32_16x16x32_bf16 v[126:129], v[146:149], v[182:185], v[126:129]
	v_mfma_f32_16x16x32_bf16 v[122:125], v[154:157], v[182:185], v[122:125]
	v_mfma_f32_16x16x32_bf16 v[110:113], v[146:149], v[190:193], v[110:113]
	v_mfma_f32_16x16x32_bf16 v[106:109], v[154:157], v[190:193], v[106:109]
	v_mfma_f32_16x16x32_bf16 v[94:97], v[146:149], v[198:201], v[94:97]
	v_mfma_f32_16x16x32_bf16 v[90:93], v[154:157], v[198:201], v[90:93]
	v_mfma_f32_16x16x32_bf16 v[78:81], v[146:149], v[214:217], v[78:81]
	v_mfma_f32_16x16x32_bf16 v[74:77], v[154:157], v[214:217], v[74:77]
	v_mfma_f32_16x16x32_bf16 v[126:129], v[150:153], v[186:189], v[126:129]
	v_mfma_f32_16x16x32_bf16 v[122:125], v[158:161], v[186:189], v[122:125]
	v_mfma_f32_16x16x32_bf16 v[110:113], v[150:153], v[194:197], v[110:113]
	v_mfma_f32_16x16x32_bf16 v[106:109], v[158:161], v[194:197], v[106:109]
	v_mfma_f32_16x16x32_bf16 v[94:97], v[150:153], v[202:205], v[94:97]
	v_mfma_f32_16x16x32_bf16 v[90:93], v[158:161], v[202:205], v[90:93]
	v_mfma_f32_16x16x32_bf16 v[78:81], v[150:153], v[218:221], v[78:81]
	v_mfma_f32_16x16x32_bf16 v[74:77], v[158:161], v[218:221], v[74:77]
	s_setprio 0
	s_setprio 1
	v_mfma_f32_16x16x32_bf16 v[118:121], v[162:165], v[182:185], v[118:121]
	v_mfma_f32_16x16x32_bf16 v[114:117], v[170:173], v[182:185], v[114:117]
	v_mfma_f32_16x16x32_bf16 v[102:105], v[162:165], v[190:193], v[102:105]
	v_mfma_f32_16x16x32_bf16 v[98:101], v[170:173], v[190:193], v[98:101]
	v_mfma_f32_16x16x32_bf16 v[86:89], v[162:165], v[198:201], v[86:89]
	v_mfma_f32_16x16x32_bf16 v[82:85], v[170:173], v[198:201], v[82:85]
	v_mfma_f32_16x16x32_bf16 v[70:73], v[162:165], v[214:217], v[70:73]
	v_mfma_f32_16x16x32_bf16 v[66:69], v[170:173], v[214:217], v[66:69]
	v_mfma_f32_16x16x32_bf16 v[118:121], v[166:169], v[186:189], v[118:121]
	v_mfma_f32_16x16x32_bf16 v[114:117], v[178:181], v[186:189], v[114:117]
	v_mfma_f32_16x16x32_bf16 v[102:105], v[166:169], v[194:197], v[102:105]
	v_mfma_f32_16x16x32_bf16 v[98:101], v[178:181], v[194:197], v[98:101]
	v_mfma_f32_16x16x32_bf16 v[86:89], v[166:169], v[202:205], v[86:89]
	v_mfma_f32_16x16x32_bf16 v[82:85], v[178:181], v[202:205], v[82:85]
	v_mfma_f32_16x16x32_bf16 v[70:73], v[166:169], v[218:221], v[70:73]
	v_mfma_f32_16x16x32_bf16 v[66:69], v[178:181], v[218:221], v[66:69]
	s_setprio 0
	s_barrier
	s_add_i32 s79, s79, s51
	v_lshl_add_u64 v[140:141], s[26:27], 0, v[0:1]
	s_mov_b32 m0, s79
	ds_read_b128 v[182:185], v145 offset:16384
	ds_read_b128 v[186:189], v145 offset:17408
	ds_read_b128 v[190:193], v145 offset:18432
	ds_read_b128 v[194:197], v145 offset:19456
	ds_read_b128 v[198:201], v145 offset:20480
	ds_read_b128 v[202:205], v145 offset:21504
	ds_read_b128 v[214:217], v145 offset:22528
	ds_read_b128 v[218:221], v145 offset:23552
	global_load_lds_dwordx4 v[140:141], off
	s_add_i32 m0, s79, 0x2000
	s_add_u32 s80, s26, 0x40000
	v_lshl_add_u64 v[174:175], s[26:27], 0, v[130:131]
	s_addc_u32 s81, s27, 0
	s_add_i32 s79, s82, s51
	global_load_lds_dwordx4 v[174:175], off
	v_lshl_add_u64 v[208:209], s[80:81], 0, v[0:1]
	s_mov_b32 m0, s79
	v_lshl_add_u64 v[212:213], s[28:29], 0, v[132:133]
	global_load_lds_dwordx4 v[208:209], off
	v_lshl_add_u64 v[208:209], s[80:81], 0, v[130:131]
	s_add_i32 m0, s79, 0x2000
	s_nop 0
	global_load_lds_dwordx4 v[208:209], off
	v_lshl_add_u64 v[208:209], s[28:29], 0, v[134:135]
	s_mov_b32 m0, s21
	s_nop 0
	global_load_lds_dwordx4 v[208:209], off
	s_mov_b32 m0, s23
	s_nop 0
	global_load_lds_dwordx4 v[212:213], off
	s_waitcnt vmcnt(8)
	s_waitcnt lgkmcnt(0)
	s_barrier
; #define PG8_STAGE(bufoff, gbase, voff) do { _Pragma("unroll") for (int _i = 0; _i < 2; ++_i) \
;         __builtin_amdgcn_global_load_lds((const unsigned*)((const char*)(gbase) + (voff)[_i]), (PG8_LAS unsigned*)(lds + (bufoff) + ldsw + _i * 8192), 16, 0, 0); } while (0)
; #define PG8_LDA(dst, b, h) do { _Pragma("unroll") for (int m = 0; m < 4; ++m) _Pragma("unroll") for (int k = 0; k < 2; ++k) dst[m][k] = *(const PG8_LAS bf16x8*)(lds + PG8_SA(b, h) + aoff + m * 2048 + k * 1024); } while (0)
; #define PG8_LDB(dst, b, h) do { _Pragma("unroll") for (int n = 0; n < 2; ++n) _Pragma("unroll") for (int k = 0; k < 2; ++k) dst[n][k] = *(const PG8_LAS bf16x8*)(lds + PG8_SB(b, h) + boff + n * 2048 + k * 1024); } while (0)
; #define PG8_MMA(ai, bj, At, Bt) do { __builtin_amdgcn_s_setprio(1); _Pragma("unroll") for (int m = 0; m < 4; ++m) _Pragma("unroll") for (int n = 0; n < 2; ++n) _Pragma("unroll") for (int k = 0; k < 2; ++k) \
;         acc[ai][bj][m][n] = __builtin_amdgcn_mfma_f32_16x16x32_bf16(Bt[n][k], At[m][k], acc[ai][bj][m][n], 0, 0, 0); __builtin_amdgcn_s_setprio(0); } while (0)
; #define PG8_WAIT_V(n) asm volatile("s_waitcnt vmcnt(" #n ")" ::: "memory")
; #define PG8_WAIT_L(n) asm volatile("s_waitcnt lgkmcnt(" #n ")" ::: "memory")
; #define PG8_BAR __builtin_amdgcn_s_barrier()
; #define PG8_SCHED __builtin_amdgcn_sched_barrier(0)
; template <class Epi, class Sched, bool ALIGN_EPI = false, bool SP2 = false>
; __device__ __forceinline__ void gemm_phase(PG8_LAS unsigned char* lds, const Gemm g, const Sched& S, const Epi& E, int wave_s) {
;     ...
;             PG8_WAIT_V(8); PG8_WAIT_L(0); PG8_BAR; PG8_MMA(1, 0, At, B0); PG8_MMA(1, 1, At, B1); PG8_BAR; PG8_SCHED;
;             PG8_LDB(B0, 1, 0); PG8_LDB(B1, 1, 1); PG8_SCHED; PG8_LDA(At, 1, 0); PG8_STAGE(PG8_SA(0, 1), a2 + hstep, voffA);
;             PG8_WAIT_V(8); PG8_WAIT_L(0); PG8_BAR; PG8_MMA(0, 0, At, B0); PG8_MMA(0, 1, At, B1); PG8_BAR; PG8_SCHED;
	s_setprio 1
	v_mfma_f32_16x16x32_bf16 v[62:65], v[146:149], v[182:185], v[62:65]
	v_mfma_f32_16x16x32_bf16 v[58:61], v[154:157], v[182:185], v[58:61]
	v_mfma_f32_16x16x32_bf16 v[46:49], v[146:149], v[190:193], v[46:49]
	v_mfma_f32_16x16x32_bf16 v[42:45], v[154:157], v[190:193], v[42:45]
	v_mfma_f32_16x16x32_bf16 v[30:33], v[146:149], v[198:201], v[30:33]
	v_mfma_f32_16x16x32_bf16 v[26:29], v[154:157], v[198:201], v[26:29]
	v_mfma_f32_16x16x32_bf16 v[14:17], v[146:149], v[214:217], v[14:17]
	v_mfma_f32_16x16x32_bf16 v[10:13], v[154:157], v[214:217], v[10:13]
	v_mfma_f32_16x16x32_bf16 v[62:65], v[150:153], v[186:189], v[62:65]
	v_mfma_f32_16x16x32_bf16 v[58:61], v[158:161], v[186:189], v[58:61]
	v_mfma_f32_16x16x32_bf16 v[46:49], v[150:153], v[194:197], v[46:49]
	v_mfma_f32_16x16x32_bf16 v[42:45], v[158:161], v[194:197], v[42:45]
	v_mfma_f32_16x16x32_bf16 v[30:33], v[150:153], v[202:205], v[30:33]
	v_mfma_f32_16x16x32_bf16 v[26:29], v[158:161], v[202:205], v[26:29]
	v_mfma_f32_16x16x32_bf16 v[14:17], v[150:153], v[218:221], v[14:17]
	v_mfma_f32_16x16x32_bf16 v[10:13], v[158:161], v[218:221], v[10:13]
	s_setprio 0
	s_setprio 1
	v_mfma_f32_16x16x32_bf16 v[54:57], v[162:165], v[182:185], v[54:57]
	v_mfma_f32_16x16x32_bf16 v[50:53], v[170:173], v[182:185], v[50:53]
	v_mfma_f32_16x16x32_bf16 v[38:41], v[162:165], v[190:193], v[38:41]
	v_mfma_f32_16x16x32_bf16 v[34:37], v[170:173], v[190:193], v[34:37]
	v_mfma_f32_16x16x32_bf16 v[22:25], v[162:165], v[198:201], v[22:25]
	v_mfma_f32_16x16x32_bf16 v[18:21], v[170:173], v[198:201], v[18:21]
	v_mfma_f32_16x16x32_bf16 v[6:9], v[162:165], v[214:217], v[6:9]
	v_mfma_f32_16x16x32_bf16 v[2:5], v[170:173], v[214:217], v[2:5]
	v_mfma_f32_16x16x32_bf16 v[54:57], v[166:169], v[186:189], v[54:57]
	v_mfma_f32_16x16x32_bf16 v[50:53], v[178:181], v[186:189], v[50:53]
	v_mfma_f32_16x16x32_bf16 v[38:41], v[166:169], v[194:197], v[38:41]
	v_mfma_f32_16x16x32_bf16 v[34:37], v[178:181], v[194:197], v[34:37]
	v_mfma_f32_16x16x32_bf16 v[22:25], v[166:169], v[202:205], v[22:25]
	v_mfma_f32_16x16x32_bf16 v[18:21], v[178:181], v[202:205], v[18:21]
	v_mfma_f32_16x16x32_bf16 v[6:9], v[166:169], v[218:221], v[6:9]
	v_mfma_f32_16x16x32_bf16 v[2:5], v[178:181], v[218:221], v[2:5]
	s_setprio 0
	s_barrier
	s_add_i32 s79, 0, 0x18000
	s_add_i32 s80, 0, 0x1c000
	v_add_u32_e32 v158, s79, v143
	v_add_u32_e32 v178, s80, v143
	ds_read_b128 v[146:149], v158
	ds_read_b128 v[150:153], v158 offset:1024
	ds_read_b128 v[154:157], v158 offset:2048
	ds_read_b128 v[158:161], v158 offset:3072
	ds_read_b128 v[162:165], v178
	ds_read_b128 v[166:169], v178 offset:1024
	ds_read_b128 v[170:173], v178 offset:2048
	ds_read_b128 v[178:181], v178 offset:3072
	s_add_u32 s28, s28, 0x40000
	s_addc_u32 s29, s29, 0
	s_mov_b32 m0, s57
	v_lshl_add_u64 v[222:223], s[28:29], 0, v[134:135]
	ds_read_b128 v[182:185], v145 offset:32768
	ds_read_b128 v[186:189], v145 offset:33792
	ds_read_b128 v[190:193], v145 offset:34816
	ds_read_b128 v[194:197], v145 offset:35840
	ds_read_b128 v[198:201], v145 offset:36864
	ds_read_b128 v[202:205], v145 offset:37888
	ds_read_b128 v[214:217], v145 offset:38912
	ds_read_b128 v[218:221], v145 offset:39936
	global_load_lds_dwordx4 v[222:223], off
	v_lshl_add_u64 v[222:223], s[28:29], 0, v[132:133]
	s_mov_b32 m0, s58
	s_nop 0
	global_load_lds_dwordx4 v[222:223], off
	s_waitcnt vmcnt(8)
	s_waitcnt lgkmcnt(0)
	s_barrier
	s_setprio 1
	v_mfma_f32_16x16x32_bf16 v[126:129], v[146:149], v[182:185], v[126:129]
	v_mfma_f32_16x16x32_bf16 v[122:125], v[154:157], v[182:185], v[122:125]
	v_mfma_f32_16x16x32_bf16 v[110:113], v[146:149], v[190:193], v[110:113]
	v_mfma_f32_16x16x32_bf16 v[106:109], v[154:157], v[190:193], v[106:109]
	v_mfma_f32_16x16x32_bf16 v[94:97], v[146:149], v[198:201], v[94:97]
	v_mfma_f32_16x16x32_bf16 v[90:93], v[154:157], v[198:201], v[90:93]
	v_mfma_f32_16x16x32_bf16 v[78:81], v[146:149], v[214:217], v[78:81]
	v_mfma_f32_16x16x32_bf16 v[74:77], v[154:157], v[214:217], v[74:77]
	v_mfma_f32_16x16x32_bf16 v[126:129], v[150:153], v[186:189], v[126:129]
	v_mfma_f32_16x16x32_bf16 v[122:125], v[158:161], v[186:189], v[122:125]
	v_mfma_f32_16x16x32_bf16 v[110:113], v[150:153], v[194:197], v[110:113]
	v_mfma_f32_16x16x32_bf16 v[106:109], v[158:161], v[194:197], v[106:109]
	v_mfma_f32_16x16x32_bf16 v[94:97], v[150:153], v[202:205], v[94:97]
	v_mfma_f32_16x16x32_bf16 v[90:93], v[158:161], v[202:205], v[90:93]
	v_mfma_f32_16x16x32_bf16 v[78:81], v[150:153], v[218:221], v[78:81]
	v_mfma_f32_16x16x32_bf16 v[74:77], v[158:161], v[218:221], v[74:77]
	s_setprio 0
	s_setprio 1
	v_mfma_f32_16x16x32_bf16 v[118:121], v[162:165], v[182:185], v[118:121]
	v_mfma_f32_16x16x32_bf16 v[114:117], v[170:173], v[182:185], v[114:117]
	v_mfma_f32_16x16x32_bf16 v[102:105], v[162:165], v[190:193], v[102:105]
	v_mfma_f32_16x16x32_bf16 v[98:101], v[170:173], v[190:193], v[98:101]
	v_mfma_f32_16x16x32_bf16 v[86:89], v[162:165], v[198:201], v[86:89]
	v_mfma_f32_16x16x32_bf16 v[82:85], v[170:173], v[198:201], v[82:85]
	v_mfma_f32_16x16x32_bf16 v[70:73], v[162:165], v[214:217], v[70:73]
	v_mfma_f32_16x16x32_bf16 v[66:69], v[170:173], v[214:217], v[66:69]
	v_mfma_f32_16x16x32_bf16 v[118:121], v[166:169], v[186:189], v[118:121]
	v_mfma_f32_16x16x32_bf16 v[114:117], v[178:181], v[186:189], v[114:117]
	v_mfma_f32_16x16x32_bf16 v[102:105], v[166:169], v[194:197], v[102:105]
	v_mfma_f32_16x16x32_bf16 v[98:101], v[178:181], v[194:197], v[98:101]
	v_mfma_f32_16x16x32_bf16 v[86:89], v[166:169], v[202:205], v[86:89]
	v_mfma_f32_16x16x32_bf16 v[82:85], v[178:181], v[202:205], v[82:85]
	v_mfma_f32_16x16x32_bf16 v[70:73], v[166:169], v[218:221], v[70:73]
	v_mfma_f32_16x16x32_bf16 v[66:69], v[178:181], v[218:221], v[66:69]
	s_setprio 0
	s_barrier
; #define PG8_STAGE(bufoff, gbase, voff) do { _Pragma("unroll") for (int _i = 0; _i < 2; ++_i) \
;         __builtin_amdgcn_global_load_lds((const unsigned*)((const char*)(gbase) + (voff)[_i]), (PG8_LAS unsigned*)(lds + (bufoff) + ldsw + _i * 8192), 16, 0, 0); } while (0)
; #define PG8_LDA(dst, b, h) do { _Pragma("unroll") for (int m = 0; m < 4; ++m) _Pragma("unroll") for (int k = 0; k < 2; ++k) dst[m][k] = *(const PG8_LAS bf16x8*)(lds + PG8_SA(b, h) + aoff + m * 2048 + k * 1024); } while (0)
; #define PG8_MMA(ai, bj, At, Bt) do { __builtin_amdgcn_s_setprio(1); _Pragma("unroll") for (int m = 0; m < 4; ++m) _Pragma("unroll") for (int n = 0; n < 2; ++n) _Pragma("unroll") for (int k = 0; k < 2; ++k) \
;         acc[ai][bj][m][n] = __builtin_amdgcn_mfma_f32_16x16x32_bf16(Bt[n][k], At[m][k], acc[ai][bj][m][n], 0, 0, 0); __builtin_amdgcn_s_setprio(0); } while (0)
; #define PG8_WAIT_V(n) asm volatile("s_waitcnt vmcnt(" #n ")" ::: "memory")
; #define PG8_WAIT_L(n) asm volatile("s_waitcnt lgkmcnt(" #n ")" ::: "memory")
; #define PG8_BAR __builtin_amdgcn_s_barrier()
; #define PG8_SCHED __builtin_amdgcn_sched_barrier(0)
; template <class Epi, class Sched, bool ALIGN_EPI = false, bool SP2 = false>
; __device__ __forceinline__ void gemm_phase(PG8_LAS unsigned char* lds, const Gemm g, const Sched& S, const Epi& E, int wave_s) {
;     ...
;             PG8_LDA(At, 1, 1); PG8_STAGE(PG8_SB(1, 0), b3, voffB); PG8_STAGE(PG8_SB(1, 1), b3 + hstep, voffB); PG8_STAGE(PG8_SA(1, 0), a3, voffA);
;             PG8_WAIT_V(8); PG8_WAIT_L(0); PG8_BAR; PG8_MMA(1, 0, At, B0); PG8_MMA(1, 1, At, B1); PG8_BAR; PG8_SCHED;
;     ...
;         if constexpr (ALIGN_EPI) { if (wr == 0) PG8_BAR; }
	s_add_i32 s28, s79, s51
	v_lshl_add_u64 v[140:141], v[140:141], 0, s[60:61]
	s_mov_b32 m0, s28
	ds_read_b128 v[182:185], v145 offset:49152
	ds_read_b128 v[186:189], v145 offset:50176
	ds_read_b128 v[190:193], v145 offset:51200
	ds_read_b128 v[194:197], v145 offset:52224
	ds_read_b128 v[198:201], v145 offset:53248
	ds_read_b128 v[202:205], v145 offset:54272
	ds_read_b128 v[214:217], v145 offset:55296
	ds_read_b128 v[218:221], v145 offset:56320
	global_load_lds_dwordx4 v[140:141], off
	s_add_i32 m0, s28, 0x2000
	s_add_u32 s26, s26, 0x40080
	v_lshl_add_u64 v[140:141], v[174:175], 0, s[60:61]
	s_addc_u32 s27, s27, 0
	s_add_i32 s28, s80, s51
	global_load_lds_dwordx4 v[140:141], off
	v_lshl_add_u64 v[140:141], s[26:27], 0, v[0:1]
	s_mov_b32 m0, s28
	s_nop 0
	global_load_lds_dwordx4 v[140:141], off
	v_lshl_add_u64 v[140:141], s[26:27], 0, v[130:131]
	s_add_i32 m0, s28, 0x2000
	s_nop 0
	global_load_lds_dwordx4 v[140:141], off
	v_lshl_add_u64 v[140:141], v[208:209], 0, s[60:61]
	s_mov_b32 m0, s62
	s_nop 0
	global_load_lds_dwordx4 v[140:141], off
	v_lshl_add_u64 v[140:141], v[212:213], 0, s[60:61]
	s_mov_b32 m0, s63
	s_nop 0
	global_load_lds_dwordx4 v[140:141], off
	s_waitcnt vmcnt(8)
	s_waitcnt lgkmcnt(0)
	s_barrier
	s_setprio 1
	v_mfma_f32_16x16x32_bf16 v[62:65], v[146:149], v[182:185], v[62:65]
	v_mfma_f32_16x16x32_bf16 v[58:61], v[154:157], v[182:185], v[58:61]
	v_mfma_f32_16x16x32_bf16 v[46:49], v[146:149], v[190:193], v[46:49]
	v_mfma_f32_16x16x32_bf16 v[42:45], v[154:157], v[190:193], v[42:45]
	v_mfma_f32_16x16x32_bf16 v[30:33], v[146:149], v[198:201], v[30:33]
	v_mfma_f32_16x16x32_bf16 v[26:29], v[154:157], v[198:201], v[26:29]
	v_mfma_f32_16x16x32_bf16 v[14:17], v[146:149], v[214:217], v[14:17]
	v_mfma_f32_16x16x32_bf16 v[10:13], v[154:157], v[214:217], v[10:13]
	v_mfma_f32_16x16x32_bf16 v[62:65], v[150:153], v[186:189], v[62:65]
	v_mfma_f32_16x16x32_bf16 v[58:61], v[158:161], v[186:189], v[58:61]
	v_mfma_f32_16x16x32_bf16 v[46:49], v[150:153], v[194:197], v[46:49]
	v_mfma_f32_16x16x32_bf16 v[42:45], v[158:161], v[194:197], v[42:45]
	v_mfma_f32_16x16x32_bf16 v[30:33], v[150:153], v[202:205], v[30:33]
	v_mfma_f32_16x16x32_bf16 v[26:29], v[158:161], v[202:205], v[26:29]
	v_mfma_f32_16x16x32_bf16 v[14:17], v[150:153], v[218:221], v[14:17]
	v_mfma_f32_16x16x32_bf16 v[10:13], v[158:161], v[218:221], v[10:13]
	s_setprio 0
	s_setprio 1
	v_mfma_f32_16x16x32_bf16 v[54:57], v[162:165], v[182:185], v[54:57]
	v_mfma_f32_16x16x32_bf16 v[50:53], v[170:173], v[182:185], v[50:53]
	v_mfma_f32_16x16x32_bf16 v[38:41], v[162:165], v[190:193], v[38:41]
	v_mfma_f32_16x16x32_bf16 v[34:37], v[170:173], v[190:193], v[34:37]
	v_mfma_f32_16x16x32_bf16 v[22:25], v[162:165], v[198:201], v[22:25]
	v_mfma_f32_16x16x32_bf16 v[18:21], v[170:173], v[198:201], v[18:21]
	v_mfma_f32_16x16x32_bf16 v[6:9], v[162:165], v[214:217], v[6:9]
	v_mfma_f32_16x16x32_bf16 v[2:5], v[170:173], v[214:217], v[2:5]
	v_mfma_f32_16x16x32_bf16 v[54:57], v[166:169], v[186:189], v[54:57]
	v_mfma_f32_16x16x32_bf16 v[50:53], v[178:181], v[186:189], v[50:53]
	v_mfma_f32_16x16x32_bf16 v[38:41], v[166:169], v[194:197], v[38:41]
	v_mfma_f32_16x16x32_bf16 v[34:37], v[178:181], v[194:197], v[34:37]
	v_mfma_f32_16x16x32_bf16 v[22:25], v[166:169], v[202:205], v[22:25]
	v_mfma_f32_16x16x32_bf16 v[18:21], v[178:181], v[202:205], v[18:21]
	v_mfma_f32_16x16x32_bf16 v[6:9], v[166:169], v[218:221], v[6:9]
	v_mfma_f32_16x16x32_bf16 v[2:5], v[178:181], v[218:221], v[2:5]
	s_setprio 0
	s_barrier
	s_add_i32 s78, s78, 2
	s_add_u32 s24, s24, 0x100
	s_addc_u32 s25, s25, 0
	s_add_u32 s76, s76, 0x100
	s_addc_u32 s77, s77, 0
	s_cmp_gt_u32 s78, 13
	s_cbranch_scc0 .LBB0_1008
	s_and_b64 vcc, exec, s[8:9]
	s_cbranch_vccz .LBB0_1011
	s_barrier

; #define PG8_STAGE(bufoff, gbase, voff) do { _Pragma("unroll") for (int _i = 0; _i < 2; ++_i) \
;         __builtin_amdgcn_global_load_lds((const unsigned*)((const char*)(gbase) + (voff)[_i]), (PG8_LAS unsigned*)(lds + (bufoff) + ldsw + _i * 8192), 16, 0, 0); } while (0)
; #define PG8_LDA(dst, b, h) do { _Pragma("unroll") for (int m = 0; m < 4; ++m) _Pragma("unroll") for (int k = 0; k < 2; ++k) dst[m][k] = *(const PG8_LAS bf16x8*)(lds + PG8_SA(b, h) + aoff + m * 2048 + k * 1024); } while (0)
; #define PG8_LDB(dst, b, h) do { _Pragma("unroll") for (int n = 0; n < 2; ++n) _Pragma("unroll") for (int k = 0; k < 2; ++k) dst[n][k] = *(const PG8_LAS bf16x8*)(lds + PG8_SB(b, h) + boff + n * 2048 + k * 1024); } while (0)
; #define PG8_MMA(ai, bj, At, Bt) do { __builtin_amdgcn_s_setprio(1); _Pragma("unroll") for (int m = 0; m < 4; ++m) _Pragma("unroll") for (int n = 0; n < 2; ++n) _Pragma("unroll") for (int k = 0; k < 2; ++k) \
;         acc[ai][bj][m][n] = __builtin_amdgcn_mfma_f32_16x16x32_bf16(Bt[n][k], At[m][k], acc[ai][bj][m][n], 0, 0, 0); __builtin_amdgcn_s_setprio(0); } while (0)
; #define PG8_WAIT_V(n) asm volatile("s_waitcnt vmcnt(" #n ")" ::: "memory")
; #define PG8_WAIT_L(n) asm volatile("s_waitcnt lgkmcnt(" #n ")" ::: "memory")
; template <class Epi, class Sched, bool ALIGN_EPI = false, bool SP2 = false>
; __device__ __forceinline__ void gemm_phase(PG8_LAS unsigned char* lds, const Gemm g, const Sched& S, const Epi& E, int wave_s) {
;     ...
;             const bool last = (t == nt - 2);
;             const char* a1 = cA + (size_t)(t + 1) * kstep;
;             const char* a2 = last ? nA : cA + (size_t)(t + 2) * kstep; const char* b2 = last ? nB : cB + (size_t)(t + 2) * kstep;
;             const char* a3 = a2 + kstep; const char* b3 = b2 + kstep;
;             if (last && has_next) S.a_ready(nxt);
;             if constexpr (SP2) {
;             PG8_LDB(B0, 0, 0); PG8_LDB(B1, 0, 1); PG8_SCHED; PG8_LDA(At, 0, 0); PG8_STAGE(PG8_SA(1, 1), a1 + hstep, voffA);
;             PG8_WAIT_V(8); PG8_WAIT_L(0); PG8_BAR; PG8_MMA(0, 0, At, B0); PG8_MMA(0, 1, At, B1); PG8_BAR; PG8_SCHED;
;             PG8_LDA(At, 0, 1); PG8_STAGE(PG8_SB(0, 0), b2, voffB); PG8_STAGE(PG8_SB(0, 1), b2 + hstep, voffB); PG8_STAGE(PG8_SA(0, 0), a2, voffA);
;             PG8_WAIT_V(8); PG8_WAIT_L(0); PG8_BAR; PG8_MMA(1, 0, At, B0); PG8_MMA(1, 1, At, B1); PG8_BAR; PG8_SCHED;
.LBB0_1084:
	s_add_u32 s22, s20, 0xfff00080
	s_addc_u32 s23, s21, -1
	s_add_i32 s75, 0, 0x10000
	s_cmp_eq_u32 s74, 60
	s_cselect_b32 s25, s13, s23
	s_cselect_b32 s24, s62, s22
	v_add_u32_e32 v140, s75, v143
	s_cselect_b32 s23, s11, s73
	s_cselect_b32 s22, s63, s72
	s_add_i32 s78, 0, 0x14000
	ds_read_b128 v[146:149], v140
	ds_read_b128 v[150:153], v140 offset:1024
	ds_read_b128 v[154:157], v140 offset:2048
	ds_read_b128 v[158:161], v140 offset:3072
	v_add_u32_e32 v140, s78, v143
	ds_read_b128 v[162:165], v140
	ds_read_b128 v[166:169], v140 offset:1024
	ds_read_b128 v[170:173], v140 offset:2048
	ds_read_b128 v[178:181], v140 offset:3072
	v_lshl_add_u64 v[140:141], s[20:21], 0, v[136:137]
	s_add_i32 m0, s46, 0xc000
	ds_read_b128 v[182:185], v145
	ds_read_b128 v[186:189], v145 offset:1024
	ds_read_b128 v[190:193], v145 offset:2048
	ds_read_b128 v[194:197], v145 offset:3072
	ds_read_b128 v[198:201], v145 offset:4096
	ds_read_b128 v[202:205], v145 offset:5120
	ds_read_b128 v[214:217], v145 offset:6144
	ds_read_b128 v[218:221], v145 offset:7168
	global_load_lds_dwordx4 v[140:141], off
	v_lshl_add_u64 v[140:141], s[20:21], 0, v[138:139]
	s_add_i32 m0, s46, 0xe000
	s_nop 0
	global_load_lds_dwordx4 v[140:141], off
	s_waitcnt vmcnt(8)
	s_waitcnt lgkmcnt(0)
	s_barrier
	s_setprio 1
	v_mfma_f32_16x16x32_bf16 v[126:129], v[146:149], v[182:185], v[126:129]
	v_mfma_f32_16x16x32_bf16 v[122:125], v[154:157], v[182:185], v[122:125]
	v_mfma_f32_16x16x32_bf16 v[118:121], v[146:149], v[190:193], v[118:121]
	v_mfma_f32_16x16x32_bf16 v[110:113], v[154:157], v[190:193], v[110:113]
	v_mfma_f32_16x16x32_bf16 v[102:105], v[146:149], v[198:201], v[102:105]
	v_mfma_f32_16x16x32_bf16 v[94:97], v[154:157], v[198:201], v[94:97]
	v_mfma_f32_16x16x32_bf16 v[86:89], v[146:149], v[214:217], v[86:89]
	v_mfma_f32_16x16x32_bf16 v[78:81], v[154:157], v[214:217], v[78:81]
	v_mfma_f32_16x16x32_bf16 v[126:129], v[150:153], v[186:189], v[126:129]
	v_mfma_f32_16x16x32_bf16 v[122:125], v[158:161], v[186:189], v[122:125]
	v_mfma_f32_16x16x32_bf16 v[118:121], v[150:153], v[194:197], v[118:121]
	v_mfma_f32_16x16x32_bf16 v[110:113], v[158:161], v[194:197], v[110:113]
	v_mfma_f32_16x16x32_bf16 v[102:105], v[150:153], v[202:205], v[102:105]
	v_mfma_f32_16x16x32_bf16 v[94:97], v[158:161], v[202:205], v[94:97]
	v_mfma_f32_16x16x32_bf16 v[86:89], v[150:153], v[218:221], v[86:89]
	v_mfma_f32_16x16x32_bf16 v[78:81], v[158:161], v[218:221], v[78:81]
	s_setprio 0
	s_setprio 1
	v_mfma_f32_16x16x32_bf16 v[114:117], v[162:165], v[182:185], v[114:117]
	v_mfma_f32_16x16x32_bf16 v[106:109], v[170:173], v[182:185], v[106:109]
	v_mfma_f32_16x16x32_bf16 v[98:101], v[162:165], v[190:193], v[98:101]
	v_mfma_f32_16x16x32_bf16 v[90:93], v[170:173], v[190:193], v[90:93]
	v_mfma_f32_16x16x32_bf16 v[82:85], v[162:165], v[198:201], v[82:85]
	v_mfma_f32_16x16x32_bf16 v[74:77], v[170:173], v[198:201], v[74:77]
	v_mfma_f32_16x16x32_bf16 v[70:73], v[162:165], v[214:217], v[70:73]
	v_mfma_f32_16x16x32_bf16 v[66:69], v[170:173], v[214:217], v[66:69]
	v_mfma_f32_16x16x32_bf16 v[114:117], v[166:169], v[186:189], v[114:117]
	v_mfma_f32_16x16x32_bf16 v[106:109], v[178:181], v[186:189], v[106:109]
	v_mfma_f32_16x16x32_bf16 v[98:101], v[166:169], v[194:197], v[98:101]
	v_mfma_f32_16x16x32_bf16 v[90:93], v[178:181], v[194:197], v[90:93]
	v_mfma_f32_16x16x32_bf16 v[82:85], v[166:169], v[202:205], v[82:85]
	v_mfma_f32_16x16x32_bf16 v[74:77], v[178:181], v[202:205], v[74:77]
	v_mfma_f32_16x16x32_bf16 v[70:73], v[166:169], v[218:221], v[70:73]
	v_mfma_f32_16x16x32_bf16 v[66:69], v[178:181], v[218:221], v[66:69]
	s_setprio 0
	s_barrier
	s_add_i32 s75, s75, s37
	v_lshl_add_u64 v[140:141], s[22:23], 0, v[0:1]
	s_mov_b32 m0, s75
	ds_read_b128 v[182:185], v145 offset:16384
	ds_read_b128 v[186:189], v145 offset:17408
	ds_read_b128 v[190:193], v145 offset:18432
	ds_read_b128 v[194:197], v145 offset:19456
	ds_read_b128 v[198:201], v145 offset:20480
	ds_read_b128 v[202:205], v145 offset:21504
	ds_read_b128 v[214:217], v145 offset:22528
	ds_read_b128 v[218:221], v145 offset:23552
	global_load_lds_dwordx4 v[140:141], off
	s_add_i32 m0, s75, 0x2000
	s_add_u32 s76, s22, 0x100000
	v_lshl_add_u64 v[174:175], s[22:23], 0, v[134:135]
	s_addc_u32 s77, s23, 0
	s_add_i32 s75, s78, s37
	global_load_lds_dwordx4 v[174:175], off
	v_lshl_add_u64 v[208:209], s[76:77], 0, v[0:1]
	s_mov_b32 m0, s75
	v_lshl_add_u64 v[212:213], s[24:25], 0, v[132:133]
	global_load_lds_dwordx4 v[208:209], off
	v_lshl_add_u64 v[208:209], s[76:77], 0, v[134:135]
	s_add_i32 m0, s75, 0x2000
	s_nop 0
	global_load_lds_dwordx4 v[208:209], off
	v_lshl_add_u64 v[208:209], s[24:25], 0, v[130:131]
	s_mov_b32 m0, s46
	s_nop 0
	global_load_lds_dwordx4 v[208:209], off
	s_mov_b32 m0, s47
	s_nop 0
	global_load_lds_dwordx4 v[212:213], off
	s_waitcnt vmcnt(8)
	s_waitcnt lgkmcnt(0)
	s_barrier
; #define PG8_STAGE(bufoff, gbase, voff) do { _Pragma("unroll") for (int _i = 0; _i < 2; ++_i) \
;         __builtin_amdgcn_global_load_lds((const unsigned*)((const char*)(gbase) + (voff)[_i]), (PG8_LAS unsigned*)(lds + (bufoff) + ldsw + _i * 8192), 16, 0, 0); } while (0)
; #define PG8_LDA(dst, b, h) do { _Pragma("unroll") for (int m = 0; m < 4; ++m) _Pragma("unroll") for (int k = 0; k < 2; ++k) dst[m][k] = *(const PG8_LAS bf16x8*)(lds + PG8_SA(b, h) + aoff + m * 2048 + k * 1024); } while (0)
; #define PG8_LDB(dst, b, h) do { _Pragma("unroll") for (int n = 0; n < 2; ++n) _Pragma("unroll") for (int k = 0; k < 2; ++k) dst[n][k] = *(const PG8_LAS bf16x8*)(lds + PG8_SB(b, h) + boff + n * 2048 + k * 1024); } while (0)
; #define PG8_MMA(ai, bj, At, Bt) do { __builtin_amdgcn_s_setprio(1); _Pragma("unroll") for (int m = 0; m < 4; ++m) _Pragma("unroll") for (int n = 0; n < 2; ++n) _Pragma("unroll") for (int k = 0; k < 2; ++k) \
;         acc[ai][bj][m][n] = __builtin_amdgcn_mfma_f32_16x16x32_bf16(Bt[n][k], At[m][k], acc[ai][bj][m][n], 0, 0, 0); __builtin_amdgcn_s_setprio(0); } while (0)
; #define PG8_WAIT_V(n) asm volatile("s_waitcnt vmcnt(" #n ")" ::: "memory")
; #define PG8_WAIT_L(n) asm volatile("s_waitcnt lgkmcnt(" #n ")" ::: "memory")
; #define PG8_BAR __builtin_amdgcn_s_barrier()
; #define PG8_SCHED __builtin_amdgcn_sched_barrier(0)
; template <class Epi, class Sched, bool ALIGN_EPI = false, bool SP2 = false>
; __device__ __forceinline__ void gemm_phase(PG8_LAS unsigned char* lds, const Gemm g, const Sched& S, const Epi& E, int wave_s) {
;     ...
;             PG8_WAIT_V(8); PG8_WAIT_L(0); PG8_BAR; PG8_MMA(1, 0, At, B0); PG8_MMA(1, 1, At, B1); PG8_BAR; PG8_SCHED;
;             PG8_LDB(B0, 1, 0); PG8_LDB(B1, 1, 1); PG8_SCHED; PG8_LDA(At, 1, 0); PG8_STAGE(PG8_SA(0, 1), a2 + hstep, voffA);
;             PG8_WAIT_V(8); PG8_WAIT_L(0); PG8_BAR; PG8_MMA(0, 0, At, B0); PG8_MMA(0, 1, At, B1); PG8_BAR; PG8_SCHED;
	s_setprio 1
	v_mfma_f32_16x16x32_bf16 v[62:65], v[146:149], v[182:185], v[62:65]
	v_mfma_f32_16x16x32_bf16 v[58:61], v[154:157], v[182:185], v[58:61]
	v_mfma_f32_16x16x32_bf16 v[54:57], v[146:149], v[190:193], v[54:57]
	v_mfma_f32_16x16x32_bf16 v[46:49], v[154:157], v[190:193], v[46:49]
	v_mfma_f32_16x16x32_bf16 v[38:41], v[146:149], v[198:201], v[38:41]
	v_mfma_f32_16x16x32_bf16 v[30:33], v[154:157], v[198:201], v[30:33]
	v_mfma_f32_16x16x32_bf16 v[22:25], v[146:149], v[214:217], v[22:25]
	v_mfma_f32_16x16x32_bf16 v[14:17], v[154:157], v[214:217], v[14:17]
	v_mfma_f32_16x16x32_bf16 v[62:65], v[150:153], v[186:189], v[62:65]
	v_mfma_f32_16x16x32_bf16 v[58:61], v[158:161], v[186:189], v[58:61]
	v_mfma_f32_16x16x32_bf16 v[54:57], v[150:153], v[194:197], v[54:57]
	v_mfma_f32_16x16x32_bf16 v[46:49], v[158:161], v[194:197], v[46:49]
	v_mfma_f32_16x16x32_bf16 v[38:41], v[150:153], v[202:205], v[38:41]
	v_mfma_f32_16x16x32_bf16 v[30:33], v[158:161], v[202:205], v[30:33]
	v_mfma_f32_16x16x32_bf16 v[22:25], v[150:153], v[218:221], v[22:25]
	v_mfma_f32_16x16x32_bf16 v[14:17], v[158:161], v[218:221], v[14:17]
	s_setprio 0
	s_setprio 1
	v_mfma_f32_16x16x32_bf16 v[50:53], v[162:165], v[182:185], v[50:53]
	v_mfma_f32_16x16x32_bf16 v[42:45], v[170:173], v[182:185], v[42:45]
	v_mfma_f32_16x16x32_bf16 v[34:37], v[162:165], v[190:193], v[34:37]
	v_mfma_f32_16x16x32_bf16 v[26:29], v[170:173], v[190:193], v[26:29]
	v_mfma_f32_16x16x32_bf16 v[18:21], v[162:165], v[198:201], v[18:21]
	v_mfma_f32_16x16x32_bf16 v[10:13], v[170:173], v[198:201], v[10:13]
	v_mfma_f32_16x16x32_bf16 v[6:9], v[162:165], v[214:217], v[6:9]
	v_mfma_f32_16x16x32_bf16 v[2:5], v[170:173], v[214:217], v[2:5]
	v_mfma_f32_16x16x32_bf16 v[50:53], v[166:169], v[186:189], v[50:53]
	v_mfma_f32_16x16x32_bf16 v[42:45], v[178:181], v[186:189], v[42:45]
	v_mfma_f32_16x16x32_bf16 v[34:37], v[166:169], v[194:197], v[34:37]
	v_mfma_f32_16x16x32_bf16 v[26:29], v[178:181], v[194:197], v[26:29]
	v_mfma_f32_16x16x32_bf16 v[18:21], v[166:169], v[202:205], v[18:21]
	v_mfma_f32_16x16x32_bf16 v[10:13], v[178:181], v[202:205], v[10:13]
	v_mfma_f32_16x16x32_bf16 v[6:9], v[166:169], v[218:221], v[6:9]
	v_mfma_f32_16x16x32_bf16 v[2:5], v[178:181], v[218:221], v[2:5]
	s_setprio 0
	s_barrier
	s_add_i32 s75, 0, 0x18000
	s_add_i32 s76, 0, 0x1c000
	v_add_u32_e32 v158, s75, v143
	v_add_u32_e32 v178, s76, v143
	ds_read_b128 v[146:149], v158
	ds_read_b128 v[150:153], v158 offset:1024
	ds_read_b128 v[154:157], v158 offset:2048
	ds_read_b128 v[158:161], v158 offset:3072
	ds_read_b128 v[162:165], v178
	ds_read_b128 v[166:169], v178 offset:1024
	ds_read_b128 v[170:173], v178 offset:2048
	ds_read_b128 v[178:181], v178 offset:3072
	s_add_u32 s24, s24, 0x100000
	s_addc_u32 s25, s25, 0
	s_mov_b32 m0, s48
	v_lshl_add_u64 v[222:223], s[24:25], 0, v[130:131]
	ds_read_b128 v[182:185], v145 offset:32768
	ds_read_b128 v[186:189], v145 offset:33792
	ds_read_b128 v[190:193], v145 offset:34816
	ds_read_b128 v[194:197], v145 offset:35840
	ds_read_b128 v[198:201], v145 offset:36864
	ds_read_b128 v[202:205], v145 offset:37888
	ds_read_b128 v[214:217], v145 offset:38912
	ds_read_b128 v[218:221], v145 offset:39936
	global_load_lds_dwordx4 v[222:223], off
	v_lshl_add_u64 v[222:223], s[24:25], 0, v[132:133]
	s_mov_b32 m0, s49
	s_nop 0
	global_load_lds_dwordx4 v[222:223], off
	s_waitcnt vmcnt(8)
	s_waitcnt lgkmcnt(0)
	s_barrier
	s_setprio 1
	v_mfma_f32_16x16x32_bf16 v[126:129], v[146:149], v[182:185], v[126:129]
	v_mfma_f32_16x16x32_bf16 v[122:125], v[154:157], v[182:185], v[122:125]
	v_mfma_f32_16x16x32_bf16 v[118:121], v[146:149], v[190:193], v[118:121]
	v_mfma_f32_16x16x32_bf16 v[110:113], v[154:157], v[190:193], v[110:113]
	v_mfma_f32_16x16x32_bf16 v[102:105], v[146:149], v[198:201], v[102:105]
	v_mfma_f32_16x16x32_bf16 v[94:97], v[154:157], v[198:201], v[94:97]
	v_mfma_f32_16x16x32_bf16 v[86:89], v[146:149], v[214:217], v[86:89]
	v_mfma_f32_16x16x32_bf16 v[78:81], v[154:157], v[214:217], v[78:81]
	v_mfma_f32_16x16x32_bf16 v[126:129], v[150:153], v[186:189], v[126:129]
	v_mfma_f32_16x16x32_bf16 v[122:125], v[158:161], v[186:189], v[122:125]
	v_mfma_f32_16x16x32_bf16 v[118:121], v[150:153], v[194:197], v[118:121]
	v_mfma_f32_16x16x32_bf16 v[110:113], v[158:161], v[194:197], v[110:113]
	v_mfma_f32_16x16x32_bf16 v[102:105], v[150:153], v[202:205], v[102:105]
	v_mfma_f32_16x16x32_bf16 v[94:97], v[158:161], v[202:205], v[94:97]
	v_mfma_f32_16x16x32_bf16 v[86:89], v[150:153], v[218:221], v[86:89]
	v_mfma_f32_16x16x32_bf16 v[78:81], v[158:161], v[218:221], v[78:81]
	s_setprio 0
	s_setprio 1
	v_mfma_f32_16x16x32_bf16 v[114:117], v[162:165], v[182:185], v[114:117]
	v_mfma_f32_16x16x32_bf16 v[106:109], v[170:173], v[182:185], v[106:109]
	v_mfma_f32_16x16x32_bf16 v[98:101], v[162:165], v[190:193], v[98:101]
	v_mfma_f32_16x16x32_bf16 v[90:93], v[170:173], v[190:193], v[90:93]
	v_mfma_f32_16x16x32_bf16 v[82:85], v[162:165], v[198:201], v[82:85]
	v_mfma_f32_16x16x32_bf16 v[74:77], v[170:173], v[198:201], v[74:77]
	v_mfma_f32_16x16x32_bf16 v[70:73], v[162:165], v[214:217], v[70:73]
	v_mfma_f32_16x16x32_bf16 v[66:69], v[170:173], v[214:217], v[66:69]
	v_mfma_f32_16x16x32_bf16 v[114:117], v[166:169], v[186:189], v[114:117]
	v_mfma_f32_16x16x32_bf16 v[106:109], v[178:181], v[186:189], v[106:109]
	v_mfma_f32_16x16x32_bf16 v[98:101], v[166:169], v[194:197], v[98:101]
	v_mfma_f32_16x16x32_bf16 v[90:93], v[178:181], v[194:197], v[90:93]
	v_mfma_f32_16x16x32_bf16 v[82:85], v[166:169], v[202:205], v[82:85]
	v_mfma_f32_16x16x32_bf16 v[74:77], v[178:181], v[202:205], v[74:77]
	v_mfma_f32_16x16x32_bf16 v[70:73], v[166:169], v[218:221], v[70:73]
	v_mfma_f32_16x16x32_bf16 v[66:69], v[178:181], v[218:221], v[66:69]
	s_setprio 0
	s_barrier
; #define PG8_STAGE(bufoff, gbase, voff) do { _Pragma("unroll") for (int _i = 0; _i < 2; ++_i) \
;         __builtin_amdgcn_global_load_lds((const unsigned*)((const char*)(gbase) + (voff)[_i]), (PG8_LAS unsigned*)(lds + (bufoff) + ldsw + _i * 8192), 16, 0, 0); } while (0)
; #define PG8_LDA(dst, b, h) do { _Pragma("unroll") for (int m = 0; m < 4; ++m) _Pragma("unroll") for (int k = 0; k < 2; ++k) dst[m][k] = *(const PG8_LAS bf16x8*)(lds + PG8_SA(b, h) + aoff + m * 2048 + k * 1024); } while (0)
; #define PG8_MMA(ai, bj, At, Bt) do { __builtin_amdgcn_s_setprio(1); _Pragma("unroll") for (int m = 0; m < 4; ++m) _Pragma("unroll") for (int n = 0; n < 2; ++n) _Pragma("unroll") for (int k = 0; k < 2; ++k) \
;         acc[ai][bj][m][n] = __builtin_amdgcn_mfma_f32_16x16x32_bf16(Bt[n][k], At[m][k], acc[ai][bj][m][n], 0, 0, 0); __builtin_amdgcn_s_setprio(0); } while (0)
; #define PG8_WAIT_V(n) asm volatile("s_waitcnt vmcnt(" #n ")" ::: "memory")
; #define PG8_WAIT_L(n) asm volatile("s_waitcnt lgkmcnt(" #n ")" ::: "memory")
; #define PG8_BAR __builtin_amdgcn_s_barrier()
; #define PG8_SCHED __builtin_amdgcn_sched_barrier(0)
; template <class Epi, class Sched, bool ALIGN_EPI = false, bool SP2 = false>
; __device__ __forceinline__ void gemm_phase(PG8_LAS unsigned char* lds, const Gemm g, const Sched& S, const Epi& E, int wave_s) {
;     ...
;             PG8_LDA(At, 1, 1); PG8_STAGE(PG8_SB(1, 0), b3, voffB); PG8_STAGE(PG8_SB(1, 1), b3 + hstep, voffB); PG8_STAGE(PG8_SA(1, 0), a3, voffA);
;             PG8_WAIT_V(8); PG8_WAIT_L(0); PG8_BAR; PG8_MMA(1, 0, At, B0); PG8_MMA(1, 1, At, B1); PG8_BAR; PG8_SCHED;
	s_add_i32 s24, s75, s37
	v_lshl_add_u64 v[140:141], v[140:141], 0, s[60:61]
	s_mov_b32 m0, s24
	ds_read_b128 v[182:185], v145 offset:49152
	ds_read_b128 v[186:189], v145 offset:50176
	ds_read_b128 v[190:193], v145 offset:51200
	ds_read_b128 v[194:197], v145 offset:52224
	ds_read_b128 v[198:201], v145 offset:53248
	ds_read_b128 v[202:205], v145 offset:54272
	ds_read_b128 v[214:217], v145 offset:55296
	ds_read_b128 v[218:221], v145 offset:56320
	global_load_lds_dwordx4 v[140:141], off
	s_add_i32 m0, s24, 0x2000
	s_add_u32 s22, s22, 0x100080
	v_lshl_add_u64 v[140:141], v[174:175], 0, s[60:61]
	s_addc_u32 s23, s23, 0
	s_add_i32 s24, s76, s37
	global_load_lds_dwordx4 v[140:141], off
	v_lshl_add_u64 v[140:141], s[22:23], 0, v[0:1]
	s_mov_b32 m0, s24
	s_nop 0
	global_load_lds_dwordx4 v[140:141], off
	v_lshl_add_u64 v[140:141], s[22:23], 0, v[134:135]
	s_add_i32 m0, s24, 0x2000
	s_nop 0
	global_load_lds_dwordx4 v[140:141], off
	v_lshl_add_u64 v[140:141], v[208:209], 0, s[60:61]
	s_mov_b32 m0, s50
	s_nop 0
	global_load_lds_dwordx4 v[140:141], off
	v_lshl_add_u64 v[140:141], v[212:213], 0, s[60:61]
	s_mov_b32 m0, s51
	s_nop 0
	global_load_lds_dwordx4 v[140:141], off
	s_waitcnt vmcnt(8)
	s_waitcnt lgkmcnt(0)
	s_barrier
	s_setprio 1
	v_mfma_f32_16x16x32_bf16 v[62:65], v[146:149], v[182:185], v[62:65]
	v_mfma_f32_16x16x32_bf16 v[58:61], v[154:157], v[182:185], v[58:61]
	v_mfma_f32_16x16x32_bf16 v[54:57], v[146:149], v[190:193], v[54:57]
	v_mfma_f32_16x16x32_bf16 v[46:49], v[154:157], v[190:193], v[46:49]
	v_mfma_f32_16x16x32_bf16 v[38:41], v[146:149], v[198:201], v[38:41]
	v_mfma_f32_16x16x32_bf16 v[30:33], v[154:157], v[198:201], v[30:33]
	v_mfma_f32_16x16x32_bf16 v[22:25], v[146:149], v[214:217], v[22:25]
	v_mfma_f32_16x16x32_bf16 v[14:17], v[154:157], v[214:217], v[14:17]
	v_mfma_f32_16x16x32_bf16 v[62:65], v[150:153], v[186:189], v[62:65]
	v_mfma_f32_16x16x32_bf16 v[58:61], v[158:161], v[186:189], v[58:61]
	v_mfma_f32_16x16x32_bf16 v[54:57], v[150:153], v[194:197], v[54:57]
	v_mfma_f32_16x16x32_bf16 v[46:49], v[158:161], v[194:197], v[46:49]
	v_mfma_f32_16x16x32_bf16 v[38:41], v[150:153], v[202:205], v[38:41]
	v_mfma_f32_16x16x32_bf16 v[30:33], v[158:161], v[202:205], v[30:33]
	v_mfma_f32_16x16x32_bf16 v[22:25], v[150:153], v[218:221], v[22:25]
	v_mfma_f32_16x16x32_bf16 v[14:17], v[158:161], v[218:221], v[14:17]
	s_setprio 0
	s_setprio 1
	v_mfma_f32_16x16x32_bf16 v[50:53], v[162:165], v[182:185], v[50:53]
	v_mfma_f32_16x16x32_bf16 v[42:45], v[170:173], v[182:185], v[42:45]
	v_mfma_f32_16x16x32_bf16 v[34:37], v[162:165], v[190:193], v[34:37]
	v_mfma_f32_16x16x32_bf16 v[26:29], v[170:173], v[190:193], v[26:29]
	v_mfma_f32_16x16x32_bf16 v[18:21], v[162:165], v[198:201], v[18:21]
	v_mfma_f32_16x16x32_bf16 v[10:13], v[170:173], v[198:201], v[10:13]
	v_mfma_f32_16x16x32_bf16 v[6:9], v[162:165], v[214:217], v[6:9]
	v_mfma_f32_16x16x32_bf16 v[2:5], v[170:173], v[214:217], v[2:5]
	v_mfma_f32_16x16x32_bf16 v[50:53], v[166:169], v[186:189], v[50:53]
	v_mfma_f32_16x16x32_bf16 v[42:45], v[178:181], v[186:189], v[42:45]
	v_mfma_f32_16x16x32_bf16 v[34:37], v[166:169], v[194:197], v[34:37]
	v_mfma_f32_16x16x32_bf16 v[26:29], v[178:181], v[194:197], v[26:29]
	v_mfma_f32_16x16x32_bf16 v[18:21], v[166:169], v[202:205], v[18:21]
	v_mfma_f32_16x16x32_bf16 v[10:13], v[178:181], v[202:205], v[10:13]
	v_mfma_f32_16x16x32_bf16 v[6:9], v[166:169], v[218:221], v[6:9]
	v_mfma_f32_16x16x32_bf16 v[2:5], v[178:181], v[218:221], v[2:5]
	s_setprio 0
	s_barrier
	s_add_i32 s74, s74, 2
	s_add_u32 s20, s20, 0x100
	s_addc_u32 s21, s21, 0
	s_add_u32 s72, s72, 0x100
	s_addc_u32 s73, s73, 0
	s_cmp_gt_u32 s74, 61
	s_cbranch_scc0 .LBB0_1084
	s_and_b64 vcc, exec, s[8:9]
	s_cbranch_vccz .LBB0_1087
	s_barrier

; #define PG8_STAGE(bufoff, gbase, voff) do { _Pragma("unroll") for (int _i = 0; _i < 2; ++_i) \
;         __builtin_amdgcn_global_load_lds((const unsigned*)((const char*)(gbase) + (voff)[_i]), (PG8_LAS unsigned*)(lds + (bufoff) + ldsw + _i * 8192), 16, 0, 0); } while (0)
; #define PG8_LDA(dst, b, h) do { _Pragma("unroll") for (int m = 0; m < 4; ++m) _Pragma("unroll") for (int k = 0; k < 2; ++k) dst[m][k] = *(const PG8_LAS bf16x8*)(lds + PG8_SA(b, h) + aoff + m * 2048 + k * 1024); } while (0)
; #define PG8_LDB(dst, b, h) do { _Pragma("unroll") for (int n = 0; n < 2; ++n) _Pragma("unroll") for (int k = 0; k < 2; ++k) dst[n][k] = *(const PG8_LAS bf16x8*)(lds + PG8_SB(b, h) + boff + n * 2048 + k * 1024); } while (0)
; #define PG8_MMA(ai, bj, At, Bt) do { __builtin_amdgcn_s_setprio(1); _Pragma("unroll") for (int m = 0; m < 4; ++m) _Pragma("unroll") for (int n = 0; n < 2; ++n) _Pragma("unroll") for (int k = 0; k < 2; ++k) \
;         acc[ai][bj][m][n] = __builtin_amdgcn_mfma_f32_16x16x32_bf16(Bt[n][k], At[m][k], acc[ai][bj][m][n], 0, 0, 0); __builtin_amdgcn_s_setprio(0); } while (0)
; #define PG8_WAIT_V(n) asm volatile("s_waitcnt vmcnt(" #n ")" ::: "memory")
; #define PG8_WAIT_L(n) asm volatile("s_waitcnt lgkmcnt(" #n ")" ::: "memory")
; #define PG8_BAR __builtin_amdgcn_s_barrier()
; #define PG8_SCHED __builtin_amdgcn_sched_barrier(0)
; template <class Epi, class Sched, bool ALIGN_EPI = false, bool SP2 = false>
; __device__ __forceinline__ void gemm_phase(PG8_LAS unsigned char* lds, const Gemm g, const Sched& S, const Epi& E, int wave_s) {
;     ...
;             PG8_LDB(B0, 0, 0); PG8_LDB(B1, 0, 1); PG8_SCHED; PG8_LDA(At, 0, 0); PG8_STAGE(PG8_SA(1, 1), a1 + hstep, voffA);
;             PG8_WAIT_V(8); PG8_WAIT_L(0); PG8_BAR; PG8_MMA(0, 0, At, B0); PG8_MMA(0, 1, At, B1); PG8_BAR; PG8_SCHED;
;             PG8_LDA(At, 0, 1); PG8_STAGE(PG8_SB(0, 0), b2, voffB); PG8_STAGE(PG8_SB(0, 1), b2 + hstep, voffB); PG8_STAGE(PG8_SA(0, 0), a2, voffA);
.LBB0_1104:
	s_add_i32 s17, 0, 0x10000
	s_add_i32 s19, 0, 0x14000
	v_add_u32_e32 v220, s17, v136
	v_add_u32_e32 v221, s19, v136
	ds_read_b128 v[2:5], v220
	ds_read_b128 v[6:9], v220 offset:1024
	ds_read_b128 v[10:13], v220 offset:2048
	ds_read_b128 v[14:17], v220 offset:3072
	ds_read_b128 v[18:21], v221
	ds_read_b128 v[22:25], v221 offset:1024
	ds_read_b128 v[26:29], v221 offset:2048
	ds_read_b128 v[30:33], v221 offset:3072
	s_add_u32 s62, s26, 0x100080
	s_addc_u32 s63, s27, 0
	s_add_i32 s70, s9, 0xc000
	v_lshl_add_u64 v[66:67], s[62:63], 0, v[134:135]
	s_mov_b32 m0, s70
	s_add_i32 s7, s9, 0xe000
	ds_read_b128 v[34:37], v139
	ds_read_b128 v[38:41], v139 offset:1024
	ds_read_b128 v[42:45], v139 offset:2048
	ds_read_b128 v[46:49], v139 offset:3072
	ds_read_b128 v[50:53], v139 offset:4096
	ds_read_b128 v[54:57], v139 offset:5120
	ds_read_b128 v[58:61], v139 offset:6144
	ds_read_b128 v[62:65], v139 offset:7168
	global_load_lds_dwordx4 v[66:67], off
	v_lshl_add_u64 v[66:67], s[62:63], 0, v[132:133]
	s_mov_b32 m0, s7
	s_nop 0
	global_load_lds_dwordx4 v[66:67], off
	s_waitcnt vmcnt(8)
	s_waitcnt lgkmcnt(0)
	s_barrier
	s_setprio 1
	v_mfma_f32_16x16x32_bf16 v[66:69], v[2:5], v[34:37], 0
	v_mfma_f32_16x16x32_bf16 v[70:73], v[10:13], v[34:37], 0
	v_mfma_f32_16x16x32_bf16 v[74:77], v[2:5], v[42:45], 0
	v_mfma_f32_16x16x32_bf16 v[78:81], v[10:13], v[42:45], 0
	v_mfma_f32_16x16x32_bf16 v[82:85], v[2:5], v[50:53], 0
	v_mfma_f32_16x16x32_bf16 v[86:89], v[10:13], v[50:53], 0
	v_mfma_f32_16x16x32_bf16 v[90:93], v[2:5], v[58:61], 0
	v_mfma_f32_16x16x32_bf16 v[94:97], v[10:13], v[58:61], 0
	v_mfma_f32_16x16x32_bf16 v[66:69], v[6:9], v[38:41], v[66:69]
	v_mfma_f32_16x16x32_bf16 v[70:73], v[14:17], v[38:41], v[70:73]
	v_mfma_f32_16x16x32_bf16 v[74:77], v[6:9], v[46:49], v[74:77]
	v_mfma_f32_16x16x32_bf16 v[78:81], v[14:17], v[46:49], v[78:81]
	v_mfma_f32_16x16x32_bf16 v[82:85], v[6:9], v[54:57], v[82:85]
	v_mfma_f32_16x16x32_bf16 v[86:89], v[14:17], v[54:57], v[86:89]
	v_mfma_f32_16x16x32_bf16 v[90:93], v[6:9], v[62:65], v[90:93]
	v_mfma_f32_16x16x32_bf16 v[94:97], v[14:17], v[62:65], v[94:97]
	s_setprio 0
	s_setprio 1
	v_mfma_f32_16x16x32_bf16 v[98:101], v[18:21], v[34:37], 0
	v_mfma_f32_16x16x32_bf16 v[34:37], v[26:29], v[34:37], 0
	v_mfma_f32_16x16x32_bf16 v[98:101], v[22:25], v[38:41], v[98:101]
	v_mfma_f32_16x16x32_bf16 v[34:37], v[30:33], v[38:41], v[34:37]
	v_mfma_f32_16x16x32_bf16 v[38:41], v[18:21], v[42:45], 0
	v_mfma_f32_16x16x32_bf16 v[42:45], v[26:29], v[42:45], 0
	v_mfma_f32_16x16x32_bf16 v[38:41], v[22:25], v[46:49], v[38:41]
	v_mfma_f32_16x16x32_bf16 v[42:45], v[30:33], v[46:49], v[42:45]
	v_mfma_f32_16x16x32_bf16 v[46:49], v[18:21], v[50:53], 0
	v_mfma_f32_16x16x32_bf16 v[50:53], v[26:29], v[50:53], 0
	v_mfma_f32_16x16x32_bf16 v[46:49], v[22:25], v[54:57], v[46:49]
	v_mfma_f32_16x16x32_bf16 v[50:53], v[30:33], v[54:57], v[50:53]
	v_mfma_f32_16x16x32_bf16 v[54:57], v[18:21], v[58:61], 0
	v_mfma_f32_16x16x32_bf16 v[58:61], v[26:29], v[58:61], 0
	v_mfma_f32_16x16x32_bf16 v[54:57], v[22:25], v[62:65], v[54:57]
	v_mfma_f32_16x16x32_bf16 v[58:61], v[30:33], v[62:65], v[58:61]
	s_setprio 0
	s_barrier
	s_add_i32 s62, s17, s47
	v_lshl_add_u64 v[172:173], s[28:29], 0, v[0:1]
	s_mov_b64 s[74:75], 0x100
	s_add_i32 s17, s62, 0x2000
	v_lshl_add_u64 v[140:141], v[172:173], 0, s[74:75]
	s_mov_b32 m0, s62
	v_lshl_add_u64 v[174:175], s[28:29], 0, v[130:131]
	s_add_u32 s72, s28, 0x100100
	ds_read_b128 v[62:65], v139 offset:16384
	ds_read_b128 v[102:105], v139 offset:17408
	ds_read_b128 v[106:109], v139 offset:18432
	ds_read_b128 v[110:113], v139 offset:19456
	ds_read_b128 v[114:117], v139 offset:20480
	ds_read_b128 v[118:121], v139 offset:21504
	ds_read_b128 v[122:125], v139 offset:22528
	ds_read_b128 v[126:129], v139 offset:23552
	global_load_lds_dwordx4 v[140:141], off
	v_lshl_add_u64 v[140:141], v[174:175], 0, s[74:75]
	s_mov_b32 m0, s17
	s_addc_u32 s73, s29, 0
	s_add_i32 s19, s19, s47
	global_load_lds_dwordx4 v[140:141], off
	v_lshl_add_u64 v[140:141], s[72:73], 0, v[0:1]
	s_mov_b32 m0, s19
	s_add_i32 s21, s19, 0x2000
	global_load_lds_dwordx4 v[140:141], off
	v_lshl_add_u64 v[140:141], s[72:73], 0, v[130:131]
	s_mov_b32 m0, s21
	v_lshl_add_u64 v[208:209], s[26:27], 0, v[134:135]
	global_load_lds_dwordx4 v[140:141], off
	v_lshl_add_u64 v[140:141], v[208:209], 0, s[74:75]
	s_mov_b32 m0, s9
	v_lshl_add_u64 v[212:213], s[26:27], 0, v[132:133]
	global_load_lds_dwordx4 v[140:141], off
	v_lshl_add_u64 v[140:141], v[212:213], 0, s[74:75]
	s_mov_b32 m0, s11
	s_nop 0
	global_load_lds_dwordx4 v[140:141], off
	s_waitcnt vmcnt(8)
	s_waitcnt lgkmcnt(0)
	s_barrier
; #define PG8_STAGE(bufoff, gbase, voff) do { _Pragma("unroll") for (int _i = 0; _i < 2; ++_i) \
;         __builtin_amdgcn_global_load_lds((const unsigned*)((const char*)(gbase) + (voff)[_i]), (PG8_LAS unsigned*)(lds + (bufoff) + ldsw + _i * 8192), 16, 0, 0); } while (0)
; #define PG8_LDA(dst, b, h) do { _Pragma("unroll") for (int m = 0; m < 4; ++m) _Pragma("unroll") for (int k = 0; k < 2; ++k) dst[m][k] = *(const PG8_LAS bf16x8*)(lds + PG8_SA(b, h) + aoff + m * 2048 + k * 1024); } while (0)
; #define PG8_LDB(dst, b, h) do { _Pragma("unroll") for (int n = 0; n < 2; ++n) _Pragma("unroll") for (int k = 0; k < 2; ++k) dst[n][k] = *(const PG8_LAS bf16x8*)(lds + PG8_SB(b, h) + boff + n * 2048 + k * 1024); } while (0)
; #define PG8_MMA(ai, bj, At, Bt) do { __builtin_amdgcn_s_setprio(1); _Pragma("unroll") for (int m = 0; m < 4; ++m) _Pragma("unroll") for (int n = 0; n < 2; ++n) _Pragma("unroll") for (int k = 0; k < 2; ++k) \
;         acc[ai][bj][m][n] = __builtin_amdgcn_mfma_f32_16x16x32_bf16(Bt[n][k], At[m][k], acc[ai][bj][m][n], 0, 0, 0); __builtin_amdgcn_s_setprio(0); } while (0)
; #define PG8_WAIT_V(n) asm volatile("s_waitcnt vmcnt(" #n ")" ::: "memory")
; #define PG8_WAIT_L(n) asm volatile("s_waitcnt lgkmcnt(" #n ")" ::: "memory")
; #define PG8_BAR __builtin_amdgcn_s_barrier()
; #define PG8_SCHED __builtin_amdgcn_sched_barrier(0)
; template <class Epi, class Sched, bool ALIGN_EPI = false, bool SP2 = false>
; __device__ __forceinline__ void gemm_phase(PG8_LAS unsigned char* lds, const Gemm g, const Sched& S, const Epi& E, int wave_s) {
;     ...
;             PG8_WAIT_V(8); PG8_WAIT_L(0); PG8_BAR; PG8_MMA(1, 0, At, B0); PG8_MMA(1, 1, At, B1); PG8_BAR; PG8_SCHED;
;             PG8_LDB(B0, 1, 0); PG8_LDB(B1, 1, 1); PG8_SCHED; PG8_LDA(At, 1, 0); PG8_STAGE(PG8_SA(0, 1), a2 + hstep, voffA);
;             PG8_WAIT_V(8); PG8_WAIT_L(0); PG8_BAR; PG8_MMA(0, 0, At, B0); PG8_MMA(0, 1, At, B1); PG8_BAR; PG8_SCHED;
	s_setprio 1
	v_mfma_f32_16x16x32_bf16 v[140:143], v[2:5], v[62:65], 0
	v_mfma_f32_16x16x32_bf16 v[148:151], v[2:5], v[106:109], 0
	v_mfma_f32_16x16x32_bf16 v[156:159], v[2:5], v[114:117], 0
	v_mfma_f32_16x16x32_bf16 v[2:5], v[2:5], v[122:125], 0
	v_mfma_f32_16x16x32_bf16 v[140:143], v[6:9], v[102:105], v[140:143]
	v_mfma_f32_16x16x32_bf16 v[148:151], v[6:9], v[110:113], v[148:151]
	v_mfma_f32_16x16x32_bf16 v[156:159], v[6:9], v[118:121], v[156:159]
	v_mfma_f32_16x16x32_bf16 v[2:5], v[6:9], v[126:129], v[2:5]
	v_mfma_f32_16x16x32_bf16 v[6:9], v[10:13], v[122:125], 0
	v_mfma_f32_16x16x32_bf16 v[144:147], v[10:13], v[62:65], 0
	v_mfma_f32_16x16x32_bf16 v[152:155], v[10:13], v[106:109], 0
	v_mfma_f32_16x16x32_bf16 v[160:163], v[10:13], v[114:117], 0
	v_mfma_f32_16x16x32_bf16 v[6:9], v[14:17], v[126:129], v[6:9]
	v_mfma_f32_16x16x32_bf16 v[144:147], v[14:17], v[102:105], v[144:147]
	v_mfma_f32_16x16x32_bf16 v[152:155], v[14:17], v[110:113], v[152:155]
	v_mfma_f32_16x16x32_bf16 v[160:163], v[14:17], v[118:121], v[160:163]
	s_setprio 0
	s_setprio 1
	v_mfma_f32_16x16x32_bf16 v[10:13], v[18:21], v[62:65], 0
	v_mfma_f32_16x16x32_bf16 v[14:17], v[26:29], v[62:65], 0
	v_mfma_f32_16x16x32_bf16 v[10:13], v[22:25], v[102:105], v[10:13]
	v_mfma_f32_16x16x32_bf16 v[14:17], v[30:33], v[102:105], v[14:17]
	v_mfma_f32_16x16x32_bf16 v[62:65], v[18:21], v[106:109], 0
	v_mfma_f32_16x16x32_bf16 v[102:105], v[26:29], v[106:109], 0
	v_mfma_f32_16x16x32_bf16 v[106:109], v[18:21], v[114:117], 0
	v_mfma_f32_16x16x32_bf16 v[18:21], v[18:21], v[122:125], 0
	v_mfma_f32_16x16x32_bf16 v[62:65], v[22:25], v[110:113], v[62:65]
	v_mfma_f32_16x16x32_bf16 v[102:105], v[30:33], v[110:113], v[102:105]
	v_mfma_f32_16x16x32_bf16 v[106:109], v[22:25], v[118:121], v[106:109]
	v_mfma_f32_16x16x32_bf16 v[110:113], v[26:29], v[114:117], 0
	v_mfma_f32_16x16x32_bf16 v[18:21], v[22:25], v[126:129], v[18:21]
	v_mfma_f32_16x16x32_bf16 v[22:25], v[26:29], v[122:125], 0
	v_mfma_f32_16x16x32_bf16 v[110:113], v[30:33], v[118:121], v[110:113]
	v_mfma_f32_16x16x32_bf16 v[22:25], v[30:33], v[126:129], v[22:25]
	s_setprio 0
	s_barrier
	s_add_i32 s63, 0, 0x18000
	s_add_i32 s76, 0, 0x1c000
	v_add_u32_e32 v230, s63, v136
	v_add_u32_e32 v234, s76, v136
	ds_read_b128 v[26:29], v230
	ds_read_b128 v[30:33], v230 offset:1024
	ds_read_b128 v[114:117], v230 offset:2048
	ds_read_b128 v[118:121], v230 offset:3072
	ds_read_b128 v[122:125], v234
	ds_read_b128 v[126:129], v234 offset:1024
	ds_read_b128 v[164:167], v234 offset:2048
	ds_read_b128 v[168:171], v234 offset:3072
	s_add_u32 s72, s26, 0x100100
	s_addc_u32 s73, s27, 0
	s_mov_b32 m0, s48
	v_lshl_add_u64 v[218:219], s[72:73], 0, v[134:135]
	ds_read_b128 v[178:181], v139 offset:32768
	ds_read_b128 v[182:185], v139 offset:33792
	ds_read_b128 v[186:189], v139 offset:34816
	ds_read_b128 v[190:193], v139 offset:35840
	ds_read_b128 v[194:197], v139 offset:36864
	ds_read_b128 v[198:201], v139 offset:37888
	ds_read_b128 v[202:205], v139 offset:38912
	ds_read_b128 v[214:217], v139 offset:39936
	global_load_lds_dwordx4 v[218:219], off
	v_lshl_add_u64 v[218:219], s[72:73], 0, v[132:133]
	s_mov_b32 m0, s49
	s_nop 0
	global_load_lds_dwordx4 v[218:219], off
	s_waitcnt vmcnt(8)
	s_waitcnt lgkmcnt(0)
	s_barrier
	s_setprio 1
	v_mfma_f32_16x16x32_bf16 v[66:69], v[26:29], v[178:181], v[66:69]
	v_mfma_f32_16x16x32_bf16 v[70:73], v[114:117], v[178:181], v[70:73]
	v_mfma_f32_16x16x32_bf16 v[74:77], v[26:29], v[186:189], v[74:77]
	v_mfma_f32_16x16x32_bf16 v[78:81], v[114:117], v[186:189], v[78:81]
	v_mfma_f32_16x16x32_bf16 v[82:85], v[26:29], v[194:197], v[82:85]
	v_mfma_f32_16x16x32_bf16 v[86:89], v[114:117], v[194:197], v[86:89]
	v_mfma_f32_16x16x32_bf16 v[90:93], v[26:29], v[202:205], v[90:93]
	v_mfma_f32_16x16x32_bf16 v[94:97], v[114:117], v[202:205], v[94:97]
	v_mfma_f32_16x16x32_bf16 v[66:69], v[30:33], v[182:185], v[66:69]
	v_mfma_f32_16x16x32_bf16 v[70:73], v[118:121], v[182:185], v[70:73]
	v_mfma_f32_16x16x32_bf16 v[74:77], v[30:33], v[190:193], v[74:77]
	v_mfma_f32_16x16x32_bf16 v[78:81], v[118:121], v[190:193], v[78:81]
	v_mfma_f32_16x16x32_bf16 v[82:85], v[30:33], v[198:201], v[82:85]
	v_mfma_f32_16x16x32_bf16 v[86:89], v[118:121], v[198:201], v[86:89]
	v_mfma_f32_16x16x32_bf16 v[90:93], v[30:33], v[214:217], v[90:93]
	v_mfma_f32_16x16x32_bf16 v[94:97], v[118:121], v[214:217], v[94:97]
	s_setprio 0
	s_setprio 1
	v_mfma_f32_16x16x32_bf16 v[98:101], v[122:125], v[178:181], v[98:101]
	v_mfma_f32_16x16x32_bf16 v[34:37], v[164:167], v[178:181], v[34:37]
	v_mfma_f32_16x16x32_bf16 v[38:41], v[122:125], v[186:189], v[38:41]
	v_mfma_f32_16x16x32_bf16 v[42:45], v[164:167], v[186:189], v[42:45]
	v_mfma_f32_16x16x32_bf16 v[46:49], v[122:125], v[194:197], v[46:49]
	v_mfma_f32_16x16x32_bf16 v[50:53], v[164:167], v[194:197], v[50:53]
	v_mfma_f32_16x16x32_bf16 v[54:57], v[122:125], v[202:205], v[54:57]
	v_mfma_f32_16x16x32_bf16 v[58:61], v[164:167], v[202:205], v[58:61]
	v_mfma_f32_16x16x32_bf16 v[98:101], v[126:129], v[182:185], v[98:101]
	v_mfma_f32_16x16x32_bf16 v[34:37], v[168:171], v[182:185], v[34:37]
	v_mfma_f32_16x16x32_bf16 v[38:41], v[126:129], v[190:193], v[38:41]
	v_mfma_f32_16x16x32_bf16 v[42:45], v[168:171], v[190:193], v[42:45]
	v_mfma_f32_16x16x32_bf16 v[46:49], v[126:129], v[198:201], v[46:49]
	v_mfma_f32_16x16x32_bf16 v[50:53], v[168:171], v[198:201], v[50:53]
	v_mfma_f32_16x16x32_bf16 v[54:57], v[126:129], v[214:217], v[54:57]
	v_mfma_f32_16x16x32_bf16 v[58:61], v[168:171], v[214:217], v[58:61]
	s_setprio 0
	s_barrier
; #define PG8_STAGE(bufoff, gbase, voff) do { _Pragma("unroll") for (int _i = 0; _i < 2; ++_i) \
;         __builtin_amdgcn_global_load_lds((const unsigned*)((const char*)(gbase) + (voff)[_i]), (PG8_LAS unsigned*)(lds + (bufoff) + ldsw + _i * 8192), 16, 0, 0); } while (0)
; #define PG8_LDA(dst, b, h) do { _Pragma("unroll") for (int m = 0; m < 4; ++m) _Pragma("unroll") for (int k = 0; k < 2; ++k) dst[m][k] = *(const PG8_LAS bf16x8*)(lds + PG8_SA(b, h) + aoff + m * 2048 + k * 1024); } while (0)
; #define PG8_LDB(dst, b, h) do { _Pragma("unroll") for (int n = 0; n < 2; ++n) _Pragma("unroll") for (int k = 0; k < 2; ++k) dst[n][k] = *(const PG8_LAS bf16x8*)(lds + PG8_SB(b, h) + boff + n * 2048 + k * 1024); } while (0)
; #define PG8_MMA(ai, bj, At, Bt) do { __builtin_amdgcn_s_setprio(1); _Pragma("unroll") for (int m = 0; m < 4; ++m) _Pragma("unroll") for (int n = 0; n < 2; ++n) _Pragma("unroll") for (int k = 0; k < 2; ++k) \
;         acc[ai][bj][m][n] = __builtin_amdgcn_mfma_f32_16x16x32_bf16(Bt[n][k], At[m][k], acc[ai][bj][m][n], 0, 0, 0); __builtin_amdgcn_s_setprio(0); } while (0)
; #define PG8_WAIT_V(n) asm volatile("s_waitcnt vmcnt(" #n ")" ::: "memory")
; #define PG8_WAIT_L(n) asm volatile("s_waitcnt lgkmcnt(" #n ")" ::: "memory")
; #define PG8_BAR __builtin_amdgcn_s_barrier()
; #define PG8_SCHED __builtin_amdgcn_sched_barrier(0)
; template <class Epi, class Sched, bool ALIGN_EPI = false, bool SP2 = false>
; __device__ __forceinline__ void gemm_phase(PG8_LAS unsigned char* lds, const Gemm g, const Sched& S, const Epi& E, int wave_s) {
;     ...
;             PG8_LDB(B0, 0, 0); PG8_LDB(B1, 0, 1); PG8_SCHED; PG8_LDA(At, 0, 0); PG8_STAGE(PG8_SA(1, 1), a1 + hstep, voffA);
;             PG8_WAIT_V(8); PG8_WAIT_L(0); PG8_BAR; PG8_MMA(0, 0, At, B0); PG8_MMA(0, 1, At, B1); PG8_BAR; PG8_SCHED;
;             PG8_LDA(At, 0, 1); PG8_STAGE(PG8_SB(0, 0), b2, voffB); PG8_STAGE(PG8_SB(0, 1), b2 + hstep, voffB); PG8_STAGE(PG8_SA(0, 0), a2, voffA);
;     ...
;             PG8_LDA(At, 1, 1); PG8_STAGE(PG8_SB(1, 0), b3, voffB); PG8_STAGE(PG8_SB(1, 1), b3 + hstep, voffB); PG8_STAGE(PG8_SA(1, 0), a3, voffA);
;             PG8_WAIT_V(8); PG8_WAIT_L(0); PG8_BAR; PG8_MMA(1, 0, At, B0); PG8_MMA(1, 1, At, B1); PG8_BAR; PG8_SCHED;
	s_add_i32 s72, s63, s47
	s_mov_b64 s[78:79], 0x180
	s_add_i32 s63, s72, 0x2000
	v_lshl_add_u64 v[172:173], v[172:173], 0, s[78:79]
	s_mov_b32 m0, s72
	s_add_u32 s74, s28, 0x100180
	ds_read_b128 v[178:181], v139 offset:49152
	ds_read_b128 v[182:185], v139 offset:50176
	ds_read_b128 v[186:189], v139 offset:51200
	ds_read_b128 v[190:193], v139 offset:52224
	ds_read_b128 v[194:197], v139 offset:53248
	ds_read_b128 v[198:201], v139 offset:54272
	ds_read_b128 v[202:205], v139 offset:55296
	ds_read_b128 v[214:217], v139 offset:56320
	global_load_lds_dwordx4 v[172:173], off
	v_lshl_add_u64 v[172:173], v[174:175], 0, s[78:79]
	s_mov_b32 m0, s63
	s_addc_u32 s75, s29, 0
	s_add_i32 s28, s76, s47
	global_load_lds_dwordx4 v[172:173], off
	v_lshl_add_u64 v[172:173], s[74:75], 0, v[0:1]
	s_mov_b32 m0, s28
	s_add_i32 s29, s28, 0x2000
	global_load_lds_dwordx4 v[172:173], off
	v_lshl_add_u64 v[172:173], s[74:75], 0, v[130:131]
	s_mov_b32 m0, s29
	s_nop 0
	global_load_lds_dwordx4 v[172:173], off
	v_lshl_add_u64 v[172:173], v[208:209], 0, s[78:79]
	s_mov_b32 m0, s56
	s_nop 0
	global_load_lds_dwordx4 v[172:173], off
	v_lshl_add_u64 v[172:173], v[212:213], 0, s[78:79]
	s_mov_b32 m0, s57
	s_nop 0
	global_load_lds_dwordx4 v[172:173], off
	s_waitcnt vmcnt(8)
	s_waitcnt lgkmcnt(0)
	s_barrier
	s_setprio 1
	v_mfma_f32_16x16x32_bf16 v[2:5], v[26:29], v[202:205], v[2:5]
	v_mfma_f32_16x16x32_bf16 v[6:9], v[114:117], v[202:205], v[6:9]
	v_mfma_f32_16x16x32_bf16 v[140:143], v[26:29], v[178:181], v[140:143]
	v_mfma_f32_16x16x32_bf16 v[144:147], v[114:117], v[178:181], v[144:147]
	v_mfma_f32_16x16x32_bf16 v[148:151], v[26:29], v[186:189], v[148:151]
	v_mfma_f32_16x16x32_bf16 v[152:155], v[114:117], v[186:189], v[152:155]
	v_mfma_f32_16x16x32_bf16 v[156:159], v[26:29], v[194:197], v[156:159]
	v_mfma_f32_16x16x32_bf16 v[160:163], v[114:117], v[194:197], v[160:163]
	v_mfma_f32_16x16x32_bf16 v[2:5], v[30:33], v[214:217], v[2:5]
	v_mfma_f32_16x16x32_bf16 v[6:9], v[118:121], v[214:217], v[6:9]
	v_mfma_f32_16x16x32_bf16 v[140:143], v[30:33], v[182:185], v[140:143]
	v_mfma_f32_16x16x32_bf16 v[144:147], v[118:121], v[182:185], v[144:147]
	v_mfma_f32_16x16x32_bf16 v[148:151], v[30:33], v[190:193], v[148:151]
	v_mfma_f32_16x16x32_bf16 v[152:155], v[118:121], v[190:193], v[152:155]
	v_mfma_f32_16x16x32_bf16 v[156:159], v[30:33], v[198:201], v[156:159]
	v_mfma_f32_16x16x32_bf16 v[160:163], v[118:121], v[198:201], v[160:163]
	s_setprio 0
	s_setprio 1
	v_mfma_f32_16x16x32_bf16 v[10:13], v[122:125], v[178:181], v[10:13]
	v_mfma_f32_16x16x32_bf16 v[14:17], v[164:167], v[178:181], v[14:17]
	v_mfma_f32_16x16x32_bf16 v[26:29], v[122:125], v[186:189], v[62:65]
	v_mfma_f32_16x16x32_bf16 v[30:33], v[164:167], v[186:189], v[102:105]
	v_mfma_f32_16x16x32_bf16 v[62:65], v[122:125], v[194:197], v[106:109]
	v_mfma_f32_16x16x32_bf16 v[102:105], v[164:167], v[194:197], v[110:113]
	v_mfma_f32_16x16x32_bf16 v[18:21], v[122:125], v[202:205], v[18:21]
	v_mfma_f32_16x16x32_bf16 v[22:25], v[164:167], v[202:205], v[22:25]
	v_mfma_f32_16x16x32_bf16 v[10:13], v[126:129], v[182:185], v[10:13]
	v_mfma_f32_16x16x32_bf16 v[14:17], v[168:171], v[182:185], v[14:17]
	v_mfma_f32_16x16x32_bf16 v[26:29], v[126:129], v[190:193], v[26:29]
	v_mfma_f32_16x16x32_bf16 v[30:33], v[168:171], v[190:193], v[30:33]
	v_mfma_f32_16x16x32_bf16 v[62:65], v[126:129], v[198:201], v[62:65]
	v_mfma_f32_16x16x32_bf16 v[102:105], v[168:171], v[198:201], v[102:105]
	v_mfma_f32_16x16x32_bf16 v[18:21], v[126:129], v[214:217], v[18:21]
	v_mfma_f32_16x16x32_bf16 v[22:25], v[168:171], v[214:217], v[22:25]
	s_setprio 0
	s_barrier
	ds_read_b128 v[106:109], v220
	ds_read_b128 v[110:113], v220 offset:1024
	ds_read_b128 v[114:117], v220 offset:2048
	ds_read_b128 v[118:121], v220 offset:3072
	ds_read_b128 v[122:125], v221
	ds_read_b128 v[126:129], v221 offset:1024
	ds_read_b128 v[164:167], v221 offset:2048
	ds_read_b128 v[168:171], v221 offset:3072
	s_add_u32 s26, s26, 0x100180
	s_addc_u32 s27, s27, 0
	s_mov_b32 m0, s70
	v_lshl_add_u64 v[172:173], s[26:27], 0, v[134:135]
	ds_read_b128 v[178:181], v139
	ds_read_b128 v[182:185], v139 offset:1024
	ds_read_b128 v[186:189], v139 offset:2048
	ds_read_b128 v[190:193], v139 offset:3072
	ds_read_b128 v[194:197], v139 offset:4096
	ds_read_b128 v[198:201], v139 offset:5120
	ds_read_b128 v[202:205], v139 offset:6144
	ds_read_b128 v[214:217], v139 offset:7168
	global_load_lds_dwordx4 v[172:173], off
	v_lshl_add_u64 v[172:173], s[26:27], 0, v[132:133]
	s_mov_b32 m0, s7
	s_nop 0
	global_load_lds_dwordx4 v[172:173], off
	s_waitcnt vmcnt(8)
	s_waitcnt lgkmcnt(0)
	s_barrier
; #define PG8_STAGE(bufoff, gbase, voff) do { _Pragma("unroll") for (int _i = 0; _i < 2; ++_i) \
;         __builtin_amdgcn_global_load_lds((const unsigned*)((const char*)(gbase) + (voff)[_i]), (PG8_LAS unsigned*)(lds + (bufoff) + ldsw + _i * 8192), 16, 0, 0); } while (0)
; #define PG8_LDA(dst, b, h) do { _Pragma("unroll") for (int m = 0; m < 4; ++m) _Pragma("unroll") for (int k = 0; k < 2; ++k) dst[m][k] = *(const PG8_LAS bf16x8*)(lds + PG8_SA(b, h) + aoff + m * 2048 + k * 1024); } while (0)
; #define PG8_LDB(dst, b, h) do { _Pragma("unroll") for (int n = 0; n < 2; ++n) _Pragma("unroll") for (int k = 0; k < 2; ++k) dst[n][k] = *(const PG8_LAS bf16x8*)(lds + PG8_SB(b, h) + boff + n * 2048 + k * 1024); } while (0)
; #define PG8_MMA(ai, bj, At, Bt) do { __builtin_amdgcn_s_setprio(1); _Pragma("unroll") for (int m = 0; m < 4; ++m) _Pragma("unroll") for (int n = 0; n < 2; ++n) _Pragma("unroll") for (int k = 0; k < 2; ++k) \
;         acc[ai][bj][m][n] = __builtin_amdgcn_mfma_f32_16x16x32_bf16(Bt[n][k], At[m][k], acc[ai][bj][m][n], 0, 0, 0); __builtin_amdgcn_s_setprio(0); } while (0)
; #define PG8_WAIT_V(n) asm volatile("s_waitcnt vmcnt(" #n ")" ::: "memory")
; #define PG8_WAIT_L(n) asm volatile("s_waitcnt lgkmcnt(" #n ")" ::: "memory")
; #define PG8_BAR __builtin_amdgcn_s_barrier()
; #define PG8_SCHED __builtin_amdgcn_sched_barrier(0)
; template <class Epi, class Sched, bool ALIGN_EPI = false, bool SP2 = false>
; __device__ __forceinline__ void gemm_phase(PG8_LAS unsigned char* lds, const Gemm g, const Sched& S, const Epi& E, int wave_s) {
;     ...
;             PG8_LDB(B0, 0, 0); PG8_LDB(B1, 0, 1); PG8_SCHED; PG8_LDA(At, 0, 0); PG8_STAGE(PG8_SA(1, 1), a1 + hstep, voffA);
;             PG8_WAIT_V(8); PG8_WAIT_L(0); PG8_BAR; PG8_MMA(0, 0, At, B0); PG8_MMA(0, 1, At, B1); PG8_BAR; PG8_SCHED;
;             PG8_LDA(At, 0, 1); PG8_STAGE(PG8_SB(0, 0), b2, voffB); PG8_STAGE(PG8_SB(0, 1), b2 + hstep, voffB); PG8_STAGE(PG8_SA(0, 0), a2, voffA);
;             PG8_WAIT_V(8); PG8_WAIT_L(0); PG8_BAR; PG8_MMA(1, 0, At, B0); PG8_MMA(1, 1, At, B1); PG8_BAR; PG8_SCHED;
;             PG8_LDB(B0, 1, 0); PG8_LDB(B1, 1, 1); PG8_SCHED; PG8_LDA(At, 1, 0); PG8_STAGE(PG8_SA(0, 1), a2 + hstep, voffA);
;             PG8_WAIT_V(8); PG8_WAIT_L(0); PG8_BAR; PG8_MMA(0, 0, At, B0); PG8_MMA(0, 1, At, B1); PG8_BAR; PG8_SCHED;
	s_setprio 1
	v_mfma_f32_16x16x32_bf16 v[66:69], v[106:109], v[178:181], v[66:69]
	v_mfma_f32_16x16x32_bf16 v[70:73], v[114:117], v[178:181], v[70:73]
	v_mfma_f32_16x16x32_bf16 v[74:77], v[106:109], v[186:189], v[74:77]
	v_mfma_f32_16x16x32_bf16 v[78:81], v[114:117], v[186:189], v[78:81]
	v_mfma_f32_16x16x32_bf16 v[82:85], v[106:109], v[194:197], v[82:85]
	v_mfma_f32_16x16x32_bf16 v[86:89], v[114:117], v[194:197], v[86:89]
	v_mfma_f32_16x16x32_bf16 v[90:93], v[106:109], v[202:205], v[90:93]
	v_mfma_f32_16x16x32_bf16 v[94:97], v[114:117], v[202:205], v[94:97]
	v_mfma_f32_16x16x32_bf16 v[66:69], v[110:113], v[182:185], v[66:69]
	v_mfma_f32_16x16x32_bf16 v[70:73], v[118:121], v[182:185], v[70:73]
	v_mfma_f32_16x16x32_bf16 v[74:77], v[110:113], v[190:193], v[74:77]
	v_mfma_f32_16x16x32_bf16 v[78:81], v[118:121], v[190:193], v[78:81]
	v_mfma_f32_16x16x32_bf16 v[82:85], v[110:113], v[198:201], v[82:85]
	v_mfma_f32_16x16x32_bf16 v[86:89], v[118:121], v[198:201], v[86:89]
	v_mfma_f32_16x16x32_bf16 v[90:93], v[110:113], v[214:217], v[90:93]
	v_mfma_f32_16x16x32_bf16 v[94:97], v[118:121], v[214:217], v[94:97]
	s_setprio 0
	s_setprio 1
	v_mfma_f32_16x16x32_bf16 v[34:37], v[164:167], v[178:181], v[34:37]
	v_mfma_f32_16x16x32_bf16 v[98:101], v[122:125], v[178:181], v[98:101]
	v_mfma_f32_16x16x32_bf16 v[178:181], v[168:171], v[182:185], v[34:37]
	v_mfma_f32_16x16x32_bf16 v[34:37], v[122:125], v[186:189], v[38:41]
	v_mfma_f32_16x16x32_bf16 v[98:101], v[126:129], v[182:185], v[98:101]
	v_mfma_f32_16x16x32_bf16 v[182:185], v[126:129], v[190:193], v[34:37]
	v_mfma_f32_16x16x32_bf16 v[34:37], v[164:167], v[186:189], v[42:45]
	v_mfma_f32_16x16x32_bf16 v[42:45], v[168:171], v[190:193], v[34:37]
	v_mfma_f32_16x16x32_bf16 v[34:37], v[122:125], v[194:197], v[46:49]
	v_mfma_f32_16x16x32_bf16 v[46:49], v[126:129], v[198:201], v[34:37]
	v_mfma_f32_16x16x32_bf16 v[34:37], v[164:167], v[194:197], v[50:53]
	v_mfma_f32_16x16x32_bf16 v[50:53], v[168:171], v[198:201], v[34:37]
	v_mfma_f32_16x16x32_bf16 v[34:37], v[122:125], v[202:205], v[54:57]
	v_mfma_f32_16x16x32_bf16 v[54:57], v[126:129], v[214:217], v[34:37]
	v_mfma_f32_16x16x32_bf16 v[34:37], v[164:167], v[202:205], v[58:61]
	v_mfma_f32_16x16x32_bf16 v[186:189], v[168:171], v[214:217], v[34:37]
	s_setprio 0
	s_barrier
	s_mov_b32 m0, s62
	v_lshl_add_u64 v[172:173], s[24:25], 0, v[0:1]
	s_add_u32 s26, s24, 0x100000
	s_nop 1
	ds_read_b128 v[34:37], v139 offset:16384
	ds_read_b128 v[38:41], v139 offset:17408
	ds_read_b128 v[58:61], v139 offset:18432
	ds_read_b128 v[190:193], v139 offset:19456
	ds_read_b128 v[194:197], v139 offset:20480
	ds_read_b128 v[198:201], v139 offset:21504
	ds_read_b128 v[202:205], v139 offset:22528
	ds_read_b128 v[214:217], v139 offset:23552
	global_load_lds_dwordx4 v[172:173], off
	v_lshl_add_u64 v[174:175], s[24:25], 0, v[130:131]
	s_mov_b32 m0, s17
	s_addc_u32 s27, s25, 0
	global_load_lds_dwordx4 v[174:175], off
	v_lshl_add_u64 v[208:209], s[26:27], 0, v[0:1]
	s_mov_b32 m0, s19
	v_lshl_add_u64 v[212:213], s[22:23], 0, v[132:133]
	global_load_lds_dwordx4 v[208:209], off
	v_lshl_add_u64 v[208:209], s[26:27], 0, v[130:131]
	s_mov_b32 m0, s21
	s_nop 0
	global_load_lds_dwordx4 v[208:209], off
	v_lshl_add_u64 v[208:209], s[22:23], 0, v[134:135]
	s_mov_b32 m0, s9
	s_nop 0
	global_load_lds_dwordx4 v[208:209], off
	s_mov_b32 m0, s11
	s_nop 0
	global_load_lds_dwordx4 v[212:213], off
	s_waitcnt vmcnt(8)
	s_waitcnt lgkmcnt(0)
	s_barrier
	s_setprio 1
	v_mfma_f32_16x16x32_bf16 v[140:143], v[106:109], v[34:37], v[140:143]
	v_mfma_f32_16x16x32_bf16 v[148:151], v[106:109], v[58:61], v[148:151]
	v_mfma_f32_16x16x32_bf16 v[156:159], v[106:109], v[194:197], v[156:159]
	v_mfma_f32_16x16x32_bf16 v[2:5], v[106:109], v[202:205], v[2:5]
	v_mfma_f32_16x16x32_bf16 v[140:143], v[110:113], v[38:41], v[140:143]
	v_mfma_f32_16x16x32_bf16 v[148:151], v[110:113], v[190:193], v[148:151]
	v_mfma_f32_16x16x32_bf16 v[156:159], v[110:113], v[198:201], v[156:159]
	v_mfma_f32_16x16x32_bf16 v[110:113], v[110:113], v[214:217], v[2:5]
	v_mfma_f32_16x16x32_bf16 v[2:5], v[114:117], v[202:205], v[6:9]
	v_mfma_f32_16x16x32_bf16 v[144:147], v[114:117], v[34:37], v[144:147]
	v_mfma_f32_16x16x32_bf16 v[152:155], v[114:117], v[58:61], v[152:155]
	v_mfma_f32_16x16x32_bf16 v[160:163], v[114:117], v[194:197], v[160:163]
	v_mfma_f32_16x16x32_bf16 v[114:117], v[118:121], v[214:217], v[2:5]
	v_mfma_f32_16x16x32_bf16 v[144:147], v[118:121], v[38:41], v[144:147]
	v_mfma_f32_16x16x32_bf16 v[152:155], v[118:121], v[190:193], v[152:155]
	v_mfma_f32_16x16x32_bf16 v[160:163], v[118:121], v[198:201], v[160:163]
	s_setprio 0
	s_setprio 1
	v_mfma_f32_16x16x32_bf16 v[2:5], v[122:125], v[34:37], v[10:13]
	v_mfma_f32_16x16x32_bf16 v[118:121], v[126:129], v[38:41], v[2:5]
	v_mfma_f32_16x16x32_bf16 v[2:5], v[164:167], v[34:37], v[14:17]
	v_mfma_f32_16x16x32_bf16 v[218:221], v[168:171], v[38:41], v[2:5]
	v_mfma_f32_16x16x32_bf16 v[2:5], v[122:125], v[58:61], v[26:29]
	v_mfma_f32_16x16x32_bf16 v[222:225], v[126:129], v[190:193], v[2:5]
	v_mfma_f32_16x16x32_bf16 v[2:5], v[164:167], v[58:61], v[30:33]
	v_mfma_f32_16x16x32_bf16 v[190:193], v[168:171], v[190:193], v[2:5]
	v_mfma_f32_16x16x32_bf16 v[2:5], v[122:125], v[194:197], v[62:65]
	v_mfma_f32_16x16x32_bf16 v[226:229], v[126:129], v[198:201], v[2:5]
	v_mfma_f32_16x16x32_bf16 v[2:5], v[164:167], v[194:197], v[102:105]
	v_mfma_f32_16x16x32_bf16 v[194:197], v[168:171], v[198:201], v[2:5]
	v_mfma_f32_16x16x32_bf16 v[2:5], v[122:125], v[202:205], v[18:21]
	v_mfma_f32_16x16x32_bf16 v[198:201], v[126:129], v[214:217], v[2:5]
	v_mfma_f32_16x16x32_bf16 v[2:5], v[164:167], v[202:205], v[22:25]
	v_mfma_f32_16x16x32_bf16 v[164:167], v[168:171], v[214:217], v[2:5]
	s_setprio 0
	s_barrier
; #define PG8_STAGE(bufoff, gbase, voff) do { _Pragma("unroll") for (int _i = 0; _i < 2; ++_i) \
;         __builtin_amdgcn_global_load_lds((const unsigned*)((const char*)(gbase) + (voff)[_i]), (PG8_LAS unsigned*)(lds + (bufoff) + ldsw + _i * 8192), 16, 0, 0); } while (0)
; #define PG8_LDA(dst, b, h) do { _Pragma("unroll") for (int m = 0; m < 4; ++m) _Pragma("unroll") for (int k = 0; k < 2; ++k) dst[m][k] = *(const PG8_LAS bf16x8*)(lds + PG8_SA(b, h) + aoff + m * 2048 + k * 1024); } while (0)
; #define PG8_LDB(dst, b, h) do { _Pragma("unroll") for (int n = 0; n < 2; ++n) _Pragma("unroll") for (int k = 0; k < 2; ++k) dst[n][k] = *(const PG8_LAS bf16x8*)(lds + PG8_SB(b, h) + boff + n * 2048 + k * 1024); } while (0)
; #define PG8_MMA(ai, bj, At, Bt) do { __builtin_amdgcn_s_setprio(1); _Pragma("unroll") for (int m = 0; m < 4; ++m) _Pragma("unroll") for (int n = 0; n < 2; ++n) _Pragma("unroll") for (int k = 0; k < 2; ++k) \
;         acc[ai][bj][m][n] = __builtin_amdgcn_mfma_f32_16x16x32_bf16(Bt[n][k], At[m][k], acc[ai][bj][m][n], 0, 0, 0); __builtin_amdgcn_s_setprio(0); } while (0)
; #define PG8_WAIT_V(n) asm volatile("s_waitcnt vmcnt(" #n ")" ::: "memory")
; #define PG8_WAIT_L(n) asm volatile("s_waitcnt lgkmcnt(" #n ")" ::: "memory")
; #define PG8_BAR __builtin_amdgcn_s_barrier()
; #define PG8_SCHED __builtin_amdgcn_sched_barrier(0)
; template <class Epi, class Sched, bool ALIGN_EPI = false, bool SP2 = false>
; __device__ __forceinline__ void gemm_phase(PG8_LAS unsigned char* lds, const Gemm g, const Sched& S, const Epi& E, int wave_s) {
;     ...
;             PG8_LDB(B0, 1, 0); PG8_LDB(B1, 1, 1); PG8_SCHED; PG8_LDA(At, 1, 0); PG8_STAGE(PG8_SA(0, 1), a2 + hstep, voffA);
;             PG8_WAIT_V(8); PG8_WAIT_L(0); PG8_BAR; PG8_MMA(0, 0, At, B0); PG8_MMA(0, 1, At, B1); PG8_BAR; PG8_SCHED;
;             PG8_LDA(At, 1, 1); PG8_STAGE(PG8_SB(1, 0), b3, voffB); PG8_STAGE(PG8_SB(1, 1), b3 + hstep, voffB); PG8_STAGE(PG8_SA(1, 0), a3, voffA);
;             PG8_WAIT_V(8); PG8_WAIT_L(0); PG8_BAR; PG8_MMA(1, 0, At, B0); PG8_MMA(1, 1, At, B1); PG8_BAR; PG8_SCHED;
;     ...
;         if constexpr (ALIGN_EPI) { if (wr == 0) PG8_BAR; }
;         if constexpr (!Epi::AFTER_DRAIN) { E(acc, cur, wr, wc, fr, fq); S.done(cur); }
;         if (!has_next) break;
	ds_read_b128 v[102:105], v230
	ds_read_b128 v[122:125], v230 offset:1024
	ds_read_b128 v[126:129], v230 offset:2048
	ds_read_b128 v[168:171], v230 offset:3072
	ds_read_b128 v[202:205], v234
	ds_read_b128 v[214:217], v234 offset:1024
	ds_read_b128 v[230:233], v234 offset:2048
	ds_read_b128 v[234:237], v234 offset:3072
	s_add_u32 s26, s22, 0x100000
	s_addc_u32 s27, s23, 0
	s_mov_b32 m0, s48
	v_lshl_add_u64 v[2:3], s[26:27], 0, v[134:135]
	ds_read_b128 v[26:29], v139 offset:32768
	ds_read_b128 v[30:33], v139 offset:33792
	ds_read_b128 v[62:65], v139 offset:34816
	ds_read_b128 v[106:109], v139 offset:35840
	ds_read_b128 v[238:241], v139 offset:36864
	ds_read_b128 v[242:245], v139 offset:37888
	ds_read_b128 v[246:249], v139 offset:38912
	ds_read_b128 v[250:253], v139 offset:39936
	global_load_lds_dwordx4 v[2:3], off
	v_lshl_add_u64 v[2:3], s[26:27], 0, v[132:133]
	s_mov_b32 m0, s49
	s_nop 0
	global_load_lds_dwordx4 v[2:3], off
	s_waitcnt vmcnt(8)
	s_waitcnt lgkmcnt(0)
	s_barrier
	s_setprio 1
	v_mfma_f32_16x16x32_bf16 v[2:5], v[102:105], v[26:29], v[66:69]
	v_mfma_f32_16x16x32_bf16 v[34:37], v[122:125], v[30:33], v[2:5]
	v_mfma_f32_16x16x32_bf16 v[2:5], v[126:129], v[26:29], v[70:73]
	v_mfma_f32_16x16x32_bf16 v[38:41], v[168:171], v[30:33], v[2:5]
	v_mfma_f32_16x16x32_bf16 v[2:5], v[102:105], v[62:65], v[74:77]
	v_mfma_f32_16x16x32_bf16 v[18:21], v[122:125], v[106:109], v[2:5]
	v_mfma_f32_16x16x32_bf16 v[2:5], v[126:129], v[62:65], v[78:81]
	v_mfma_f32_16x16x32_bf16 v[22:25], v[168:171], v[106:109], v[2:5]
	v_mfma_f32_16x16x32_bf16 v[2:5], v[102:105], v[238:241], v[82:85]
	v_mfma_f32_16x16x32_bf16 v[10:13], v[122:125], v[242:245], v[2:5]
	v_mfma_f32_16x16x32_bf16 v[2:5], v[126:129], v[238:241], v[86:89]
	v_mfma_f32_16x16x32_bf16 v[14:17], v[168:171], v[242:245], v[2:5]
	v_mfma_f32_16x16x32_bf16 v[2:5], v[102:105], v[246:249], v[90:93]
	v_mfma_f32_16x16x32_bf16 v[6:9], v[126:129], v[246:249], v[94:97]
	v_mfma_f32_16x16x32_bf16 v[2:5], v[122:125], v[250:253], v[2:5]
	v_mfma_f32_16x16x32_bf16 v[6:9], v[168:171], v[250:253], v[6:9]
	s_setprio 0
	s_setprio 1
	v_mfma_f32_16x16x32_bf16 v[58:61], v[202:205], v[26:29], v[98:101]
	v_mfma_f32_16x16x32_bf16 v[26:29], v[230:233], v[26:29], v[178:181]
	v_mfma_f32_16x16x32_bf16 v[78:81], v[234:237], v[30:33], v[26:29]
	v_mfma_f32_16x16x32_bf16 v[26:29], v[202:205], v[62:65], v[182:185]
	v_mfma_f32_16x16x32_bf16 v[70:73], v[214:217], v[30:33], v[58:61]
	v_mfma_f32_16x16x32_bf16 v[58:61], v[214:217], v[106:109], v[26:29]
	v_mfma_f32_16x16x32_bf16 v[26:29], v[230:233], v[62:65], v[42:45]
	v_mfma_f32_16x16x32_bf16 v[62:65], v[234:237], v[106:109], v[26:29]
	v_mfma_f32_16x16x32_bf16 v[26:29], v[202:205], v[238:241], v[46:49]
	v_mfma_f32_16x16x32_bf16 v[42:45], v[214:217], v[242:245], v[26:29]
	v_mfma_f32_16x16x32_bf16 v[26:29], v[230:233], v[238:241], v[50:53]
	v_mfma_f32_16x16x32_bf16 v[46:49], v[234:237], v[242:245], v[26:29]
	v_mfma_f32_16x16x32_bf16 v[26:29], v[202:205], v[246:249], v[54:57]
	v_mfma_f32_16x16x32_bf16 v[30:33], v[230:233], v[246:249], v[186:189]
	v_mfma_f32_16x16x32_bf16 v[26:29], v[214:217], v[250:253], v[26:29]
	v_mfma_f32_16x16x32_bf16 v[30:33], v[234:237], v[250:253], v[30:33]
	s_setprio 0
	s_barrier
	s_mov_b32 m0, s72
	v_lshl_add_u64 v[50:51], v[172:173], 0, s[60:61]
	s_add_u32 s26, s24, 0x100080
	ds_read_b128 v[82:85], v139 offset:49152
	ds_read_b128 v[90:93], v139 offset:50176
	ds_read_b128 v[178:181], v139 offset:51200
	ds_read_b128 v[182:185], v139 offset:52224
	ds_read_b128 v[186:189], v139 offset:53248
	ds_read_b128 v[238:241], v139 offset:54272
	ds_read_b128 v[242:245], v139 offset:55296
	ds_read_b128 v[246:249], v139 offset:56320
	global_load_lds_dwordx4 v[50:51], off
	v_lshl_add_u64 v[50:51], v[174:175], 0, s[60:61]
	s_mov_b32 m0, s63
	s_addc_u32 s27, s25, 0
	global_load_lds_dwordx4 v[50:51], off
	v_lshl_add_u64 v[50:51], s[26:27], 0, v[0:1]
	s_mov_b32 m0, s28
	s_nop 0
	global_load_lds_dwordx4 v[50:51], off
	v_lshl_add_u64 v[50:51], s[26:27], 0, v[130:131]
	s_mov_b32 m0, s29
	s_nop 0
	global_load_lds_dwordx4 v[50:51], off
	v_lshl_add_u64 v[50:51], v[208:209], 0, s[60:61]
	s_mov_b32 m0, s56
	s_nop 0
	global_load_lds_dwordx4 v[50:51], off
	v_lshl_add_u64 v[50:51], v[212:213], 0, s[60:61]
	s_mov_b32 m0, s57
	s_nop 0
	global_load_lds_dwordx4 v[50:51], off
	s_waitcnt vmcnt(8)
	s_waitcnt lgkmcnt(0)
	s_barrier
	s_setprio 1
	v_mfma_f32_16x16x32_bf16 v[50:53], v[102:105], v[82:85], v[140:143]
	v_mfma_f32_16x16x32_bf16 v[98:101], v[122:125], v[90:93], v[50:53]
	v_mfma_f32_16x16x32_bf16 v[50:53], v[126:129], v[82:85], v[144:147]
	v_mfma_f32_16x16x32_bf16 v[106:109], v[168:171], v[90:93], v[50:53]
	v_mfma_f32_16x16x32_bf16 v[50:53], v[102:105], v[178:181], v[148:151]
	v_mfma_f32_16x16x32_bf16 v[86:89], v[122:125], v[182:185], v[50:53]
	v_mfma_f32_16x16x32_bf16 v[50:53], v[126:129], v[178:181], v[152:155]
	v_mfma_f32_16x16x32_bf16 v[94:97], v[168:171], v[182:185], v[50:53]
	v_mfma_f32_16x16x32_bf16 v[50:53], v[102:105], v[186:189], v[156:159]
	v_mfma_f32_16x16x32_bf16 v[66:69], v[122:125], v[238:241], v[50:53]
	v_mfma_f32_16x16x32_bf16 v[50:53], v[126:129], v[186:189], v[160:163]
	v_mfma_f32_16x16x32_bf16 v[74:77], v[168:171], v[238:241], v[50:53]
	v_mfma_f32_16x16x32_bf16 v[50:53], v[102:105], v[242:245], v[110:113]
	v_mfma_f32_16x16x32_bf16 v[54:57], v[126:129], v[242:245], v[114:117]
	v_mfma_f32_16x16x32_bf16 v[50:53], v[122:125], v[246:249], v[50:53]
	v_mfma_f32_16x16x32_bf16 v[54:57], v[168:171], v[246:249], v[54:57]
	s_setprio 0
	s_setprio 1
	v_mfma_f32_16x16x32_bf16 v[102:105], v[202:205], v[82:85], v[118:121]
	v_mfma_f32_16x16x32_bf16 v[82:85], v[230:233], v[82:85], v[218:221]
	v_mfma_f32_16x16x32_bf16 v[126:129], v[234:237], v[90:93], v[82:85]
	v_mfma_f32_16x16x32_bf16 v[82:85], v[202:205], v[178:181], v[222:225]
	v_mfma_f32_16x16x32_bf16 v[114:117], v[214:217], v[182:185], v[82:85]
	v_mfma_f32_16x16x32_bf16 v[82:85], v[230:233], v[178:181], v[190:193]
	v_mfma_f32_16x16x32_bf16 v[118:121], v[234:237], v[182:185], v[82:85]
	v_mfma_f32_16x16x32_bf16 v[82:85], v[202:205], v[186:189], v[226:229]
	v_mfma_f32_16x16x32_bf16 v[122:125], v[214:217], v[90:93], v[102:105]
	v_mfma_f32_16x16x32_bf16 v[102:105], v[214:217], v[238:241], v[82:85]
	v_mfma_f32_16x16x32_bf16 v[82:85], v[230:233], v[186:189], v[194:197]
	v_mfma_f32_16x16x32_bf16 v[110:113], v[234:237], v[238:241], v[82:85]
	v_mfma_f32_16x16x32_bf16 v[82:85], v[202:205], v[242:245], v[198:201]
	v_mfma_f32_16x16x32_bf16 v[90:93], v[230:233], v[242:245], v[164:167]
	v_mfma_f32_16x16x32_bf16 v[82:85], v[214:217], v[246:249], v[82:85]
	v_mfma_f32_16x16x32_bf16 v[90:93], v[234:237], v[246:249], v[90:93]
	s_setprio 0
	s_barrier
	s_andn2_b64 vcc, exec, s[12:13]
	s_cbranch_vccnz .LBB0_1106
	s_barrier
